# per-tile accumulator clear of the GEMM loops: register pairs cleared with v_mov_b64 instead of 128 single VALU moves
# speedup vs baseline: 1.0614x; 1.0011x over previous
; template <class Epi>
; DI void gemm_phase(int wv, LAS unsigned char* lds, const Gemm g, const StaticOrder& S, const Epi& E) {
;     ...
;         const bool has_next = S.next(ui + 1, nxt);
;         const char* nA = has_next ? (const char*)g.A + (size_t)nxt.pm * tstep : cA; const char* nB = has_next ? (const char*)g.Bt + (size_t)nxt.pn * tstep : cB;
;         for (int t = 0; t < nt; t += 2) {
;             const bool last = (t == nt - 2);
;             const char* a1 = cA + (size_t)(t + 1) * kstep;
;             const char* a2 = last ? nA : cA + (size_t)(t + 2) * kstep; const char* b2 = last ? nB : cB + (size_t)(t + 2) * kstep;
;             const char* a3 = a2 + kstep; const char* b3 = b2 + kstep;
;     ...
; #pragma unroll
;         for (int a = 0; a < 2; ++a)
; #pragma unroll
;             for (int b = 0; b < 2; ++b)
; #pragma unroll
;                 for (int m = 0; m < 4; ++m)
; #pragma unroll
;                     for (int n = 0; n < 2; ++n) acc[a][b][m][n] = (f32x4){0.f, 0.f, 0.f, 0.f};
;         cur = nxt; cA = nA; cB = nB; ++ui;
.LBB0_100:
	s_ashr_i32 s13, s12, 31
	v_cmp_lt_i64_e32 vcc, s[14:15], v[144:145]
	s_lshl_b64 s[14:15], s[12:13], 19
	s_add_u32 s14, s24, s14
	s_addc_u32 s15, s25, s15
	s_and_b64 s[16:17], vcc, exec
	s_cselect_b32 s13, s15, s21
	s_cselect_b32 s19, s14, s20
	s_ashr_i32 s11, s10, 31
	s_lshl_b64 s[16:17], s[10:11], 19
	s_add_u32 s16, s37, s16
	s_addc_u32 s17, s38, s17
	s_and_b64 s[30:31], vcc, exec
	s_cselect_b32 s11, s17, s29
	s_cselect_b32 s65, s16, s28
	s_add_u32 s20, s20, 0x40080
	s_addc_u32 s21, s21, 0
	s_add_u32 s66, s28, 0x100
	v_mov_b32_e32 v0, 0
	s_addc_u32 s67, s29, 0
	s_mov_b32 s68, -2
	v_mov_b64_e32 v[0:1], 0
	v_mov_b64_e32 v[2:3], 0
	v_mov_b64_e32 v[4:5], 0
	v_mov_b64_e32 v[6:7], 0
	v_mov_b64_e32 v[16:17], 0
	v_mov_b64_e32 v[18:19], 0
	v_mov_b64_e32 v[20:21], 0
	v_mov_b64_e32 v[22:23], 0
	v_mov_b64_e32 v[32:33], 0
	v_mov_b64_e32 v[34:35], 0
	v_mov_b64_e32 v[36:37], 0
	v_mov_b64_e32 v[38:39], 0
	v_mov_b64_e32 v[48:49], 0
	v_mov_b64_e32 v[50:51], 0
	v_mov_b64_e32 v[52:53], 0
	v_mov_b64_e32 v[54:55], 0
	v_mov_b64_e32 v[8:9], 0
	v_mov_b64_e32 v[10:11], 0
	v_mov_b64_e32 v[12:13], 0
	v_mov_b64_e32 v[14:15], 0
	v_mov_b64_e32 v[24:25], 0
	v_mov_b64_e32 v[26:27], 0
	v_mov_b64_e32 v[28:29], 0
	v_mov_b64_e32 v[30:31], 0
	v_mov_b64_e32 v[40:41], 0
	v_mov_b64_e32 v[42:43], 0
	v_mov_b64_e32 v[44:45], 0
	v_mov_b64_e32 v[46:47], 0
	v_mov_b64_e32 v[56:57], 0
	v_mov_b64_e32 v[58:59], 0
	v_mov_b64_e32 v[60:61], 0
	v_mov_b64_e32 v[62:63], 0
	v_mov_b64_e32 v[64:65], 0
	v_mov_b64_e32 v[66:67], 0
	v_mov_b64_e32 v[68:69], 0
	v_mov_b64_e32 v[70:71], 0
	v_mov_b64_e32 v[80:81], 0
	v_mov_b64_e32 v[82:83], 0
	v_mov_b64_e32 v[84:85], 0
	v_mov_b64_e32 v[86:87], 0
	v_mov_b64_e32 v[96:97], 0
	v_mov_b64_e32 v[98:99], 0
	v_mov_b64_e32 v[100:101], 0
	v_mov_b64_e32 v[102:103], 0
	v_mov_b64_e32 v[112:113], 0
	v_mov_b64_e32 v[114:115], 0
	v_mov_b64_e32 v[116:117], 0
	v_mov_b64_e32 v[118:119], 0
	v_mov_b64_e32 v[72:73], 0
	v_mov_b64_e32 v[74:75], 0
	v_mov_b64_e32 v[76:77], 0
	v_mov_b64_e32 v[78:79], 0
	v_mov_b64_e32 v[88:89], 0
	v_mov_b64_e32 v[90:91], 0
	v_mov_b64_e32 v[92:93], 0
	v_mov_b64_e32 v[94:95], 0
	v_mov_b64_e32 v[104:105], 0
	v_mov_b64_e32 v[106:107], 0
	v_mov_b64_e32 v[108:109], 0
	v_mov_b64_e32 v[110:111], 0
	v_mov_b64_e32 v[120:121], 0
	v_mov_b64_e32 v[122:123], 0
	v_mov_b64_e32 v[124:125], 0
	v_mov_b64_e32 v[126:127], 0

; template <class Epi>
; DI void gemm_phase(int wv, LAS unsigned char* lds, const Gemm g, const StaticOrder& S, const Epi& E) {
;     ...
; #pragma unroll
;         for (int a = 0; a < 2; ++a)
; #pragma unroll
;             for (int b = 0; b < 2; ++b)
; #pragma unroll
;                 for (int m = 0; m < 4; ++m)
; #pragma unroll
;                     for (int n = 0; n < 2; ++n) acc[a][b][m][n] = (f32x4){0.f, 0.f, 0.f, 0.f};
;         cur = nxt; cA = nA; cB = nB; ++ui;
.LBB0_176:
	s_add_u32 s17, s20, 0x100
	v_mov_b32_e32 v0, 0
	s_addc_u32 s66, s21, 0
	s_mov_b32 s67, -2
	v_mov_b64_e32 v[0:1], 0
	v_mov_b64_e32 v[2:3], 0
	v_mov_b64_e32 v[4:5], 0
	v_mov_b64_e32 v[6:7], 0
	v_mov_b64_e32 v[8:9], 0
	v_mov_b64_e32 v[10:11], 0
	v_mov_b64_e32 v[16:17], 0
	v_mov_b64_e32 v[18:19], 0
	v_mov_b64_e32 v[24:25], 0
	v_mov_b64_e32 v[26:27], 0
	v_mov_b64_e32 v[32:33], 0
	v_mov_b64_e32 v[34:35], 0
	v_mov_b64_e32 v[40:41], 0
	v_mov_b64_e32 v[42:43], 0
	v_mov_b64_e32 v[48:49], 0
	v_mov_b64_e32 v[50:51], 0
	v_mov_b64_e32 v[12:13], 0
	v_mov_b64_e32 v[14:15], 0
	v_mov_b64_e32 v[20:21], 0
	v_mov_b64_e32 v[22:23], 0
	v_mov_b64_e32 v[28:29], 0
	v_mov_b64_e32 v[30:31], 0
	v_mov_b64_e32 v[36:37], 0
	v_mov_b64_e32 v[38:39], 0
	v_mov_b64_e32 v[44:45], 0
	v_mov_b64_e32 v[46:47], 0
	v_mov_b64_e32 v[52:53], 0
	v_mov_b64_e32 v[54:55], 0
	v_mov_b64_e32 v[56:57], 0
	v_mov_b64_e32 v[58:59], 0
	v_mov_b64_e32 v[60:61], 0
	v_mov_b64_e32 v[62:63], 0
	v_mov_b64_e32 v[64:65], 0
	v_mov_b64_e32 v[66:67], 0
	v_mov_b64_e32 v[68:69], 0
	v_mov_b64_e32 v[70:71], 0
	v_mov_b64_e32 v[72:73], 0
	v_mov_b64_e32 v[74:75], 0
	v_mov_b64_e32 v[76:77], 0
	v_mov_b64_e32 v[78:79], 0
	v_mov_b64_e32 v[84:85], 0
	v_mov_b64_e32 v[86:87], 0
	v_mov_b64_e32 v[92:93], 0
	v_mov_b64_e32 v[94:95], 0
	v_mov_b64_e32 v[100:101], 0
	v_mov_b64_e32 v[102:103], 0
	v_mov_b64_e32 v[108:109], 0
	v_mov_b64_e32 v[110:111], 0
	v_mov_b64_e32 v[80:81], 0
	v_mov_b64_e32 v[82:83], 0
	v_mov_b64_e32 v[88:89], 0
	v_mov_b64_e32 v[90:91], 0
	v_mov_b64_e32 v[96:97], 0
	v_mov_b64_e32 v[98:99], 0
	v_mov_b64_e32 v[104:105], 0
	v_mov_b64_e32 v[106:107], 0
	v_mov_b64_e32 v[112:113], 0
	v_mov_b64_e32 v[114:115], 0
	v_mov_b64_e32 v[116:117], 0
	v_mov_b64_e32 v[118:119], 0
	v_mov_b64_e32 v[120:121], 0
	v_mov_b64_e32 v[122:123], 0
	v_mov_b64_e32 v[124:125], 0
	v_mov_b64_e32 v[126:127], 0

; template <class Epi>
; DI void gemm_phase(int wv, LAS unsigned char* lds, const Gemm g, const StaticOrder& S, const Epi& E) {
;     ...
;         const bool has_next = S.next(ui + 1, nxt);
;         const char* nA = has_next ? (const char*)g.A + (size_t)nxt.pm * tstep : cA; const char* nB = has_next ? (const char*)g.Bt + (size_t)nxt.pn * tstep : cB;
;         for (int t = 0; t < nt; t += 2) {
;             const bool last = (t == nt - 2);
;             const char* a1 = cA + (size_t)(t + 1) * kstep;
;             const char* a2 = last ? nA : cA + (size_t)(t + 2) * kstep; const char* b2 = last ? nB : cB + (size_t)(t + 2) * kstep;
;             const char* a3 = a2 + kstep; const char* b3 = b2 + kstep;
;     ...
; #pragma unroll
;         for (int a = 0; a < 2; ++a)
; #pragma unroll
;             for (int b = 0; b < 2; ++b)
; #pragma unroll
;                 for (int m = 0; m < 4; ++m)
; #pragma unroll
;                     for (int n = 0; n < 2; ++n) acc[a][b][m][n] = (f32x4){0.f, 0.f, 0.f, 0.f};
;         cur = nxt; cA = nA; cB = nB; ++ui;
.LBB0_451:
	s_ashr_i32 s29, s28, 31
	v_cmp_lt_i64_e32 vcc, s[30:31], v[142:143]
	s_lshl_b64 s[30:31], s[28:29], 19
	s_add_u32 s30, s24, s30
	s_addc_u32 s31, s25, s31
	s_and_b64 s[36:37], vcc, exec
	s_cselect_b32 s7, s31, s47
	s_cselect_b32 s29, s30, s46
	s_ashr_i32 s21, s20, 31
	s_lshl_b64 s[36:37], s[20:21], 19
	s_add_u32 s36, s11, s36
	s_addc_u32 s37, s41, s37
	s_and_b64 s[50:51], vcc, exec
	s_cselect_b32 s21, s37, s49
	s_cselect_b32 s39, s36, s48
	s_add_u32 s46, s46, 0x40080
	s_addc_u32 s47, s47, 0
	s_add_u32 s66, s48, 0x100
	v_mov_b32_e32 v0, 0
	s_addc_u32 s67, s49, 0
	s_mov_b32 s68, -2
	v_mov_b64_e32 v[0:1], 0
	v_mov_b64_e32 v[2:3], 0
	v_mov_b64_e32 v[4:5], 0
	v_mov_b64_e32 v[6:7], 0
	v_mov_b64_e32 v[12:13], 0
	v_mov_b64_e32 v[14:15], 0
	v_mov_b64_e32 v[20:21], 0
	v_mov_b64_e32 v[22:23], 0
	v_mov_b64_e32 v[28:29], 0
	v_mov_b64_e32 v[30:31], 0
	v_mov_b64_e32 v[36:37], 0
	v_mov_b64_e32 v[38:39], 0
	v_mov_b64_e32 v[44:45], 0
	v_mov_b64_e32 v[46:47], 0
	v_mov_b64_e32 v[52:53], 0
	v_mov_b64_e32 v[54:55], 0
	v_mov_b64_e32 v[8:9], 0
	v_mov_b64_e32 v[10:11], 0
	v_mov_b64_e32 v[16:17], 0
	v_mov_b64_e32 v[18:19], 0
	v_mov_b64_e32 v[24:25], 0
	v_mov_b64_e32 v[26:27], 0
	v_mov_b64_e32 v[32:33], 0
	v_mov_b64_e32 v[34:35], 0
	v_mov_b64_e32 v[40:41], 0
	v_mov_b64_e32 v[42:43], 0
	v_mov_b64_e32 v[48:49], 0
	v_mov_b64_e32 v[50:51], 0
	v_mov_b64_e32 v[56:57], 0
	v_mov_b64_e32 v[58:59], 0
	v_mov_b64_e32 v[60:61], 0
	v_mov_b64_e32 v[62:63], 0
	v_mov_b64_e32 v[64:65], 0
	v_mov_b64_e32 v[66:67], 0
	v_mov_b64_e32 v[68:69], 0
	v_mov_b64_e32 v[70:71], 0
	v_mov_b64_e32 v[80:81], 0
	v_mov_b64_e32 v[82:83], 0
	v_mov_b64_e32 v[84:85], 0
	v_mov_b64_e32 v[86:87], 0
	v_mov_b64_e32 v[96:97], 0
	v_mov_b64_e32 v[98:99], 0
	v_mov_b64_e32 v[100:101], 0
	v_mov_b64_e32 v[102:103], 0
	v_mov_b64_e32 v[112:113], 0
	v_mov_b64_e32 v[114:115], 0
	v_mov_b64_e32 v[116:117], 0
	v_mov_b64_e32 v[118:119], 0
	v_mov_b64_e32 v[72:73], 0
	v_mov_b64_e32 v[74:75], 0
	v_mov_b64_e32 v[76:77], 0
	v_mov_b64_e32 v[78:79], 0
	v_mov_b64_e32 v[88:89], 0
	v_mov_b64_e32 v[90:91], 0
	v_mov_b64_e32 v[92:93], 0
	v_mov_b64_e32 v[94:95], 0
	v_mov_b64_e32 v[104:105], 0
	v_mov_b64_e32 v[106:107], 0
	v_mov_b64_e32 v[108:109], 0
	v_mov_b64_e32 v[110:111], 0
	v_mov_b64_e32 v[120:121], 0
	v_mov_b64_e32 v[122:123], 0
	v_mov_b64_e32 v[124:125], 0
	v_mov_b64_e32 v[126:127], 0

; template <class Epi>
; DI void gemm_phase(int wv, LAS unsigned char* lds, const Gemm g, const StaticOrder& S, const Epi& E) {
;     ...
;         const bool has_next = S.next(ui + 1, nxt);
;         const char* nA = has_next ? (const char*)g.A + (size_t)nxt.pm * tstep : cA; const char* nB = has_next ? (const char*)g.Bt + (size_t)nxt.pn * tstep : cB;
;         for (int t = 0; t < nt; t += 2) {
;             const bool last = (t == nt - 2);
;             const char* a1 = cA + (size_t)(t + 1) * kstep;
;             const char* a2 = last ? nA : cA + (size_t)(t + 2) * kstep; const char* b2 = last ? nB : cB + (size_t)(t + 2) * kstep;
;             const char* a3 = a2 + kstep; const char* b3 = b2 + kstep;
;     ...
; #pragma unroll
;         for (int a = 0; a < 2; ++a)
; #pragma unroll
;             for (int b = 0; b < 2; ++b)
; #pragma unroll
;                 for (int m = 0; m < 4; ++m)
; #pragma unroll
;                     for (int n = 0; n < 2; ++n) acc[a][b][m][n] = (f32x4){0.f, 0.f, 0.f, 0.f};
;         cur = nxt; cA = nA; cB = nB; ++ui;
.LBB0_505:
	s_ashr_i32 s31, s30, 31
	v_cmp_lt_i64_e32 vcc, s[36:37], v[142:143]
	s_lshl_b64 s[36:37], s[30:31], 19
	s_add_u32 s36, s11, s36
	s_addc_u32 s37, s41, s37
	s_and_b64 s[38:39], vcc, exec
	s_cselect_b32 s9, s37, s49
	s_cselect_b32 s31, s36, s48
	s_ashr_i32 s29, s28, 31
	s_lshl_b64 s[38:39], s[28:29], 19
	s_add_u32 s38, s24, s38
	s_addc_u32 s39, s25, s39
	s_and_b64 s[62:63], vcc, exec
	s_cselect_b32 s29, s39, s51
	s_cselect_b32 s47, s38, s50
	s_add_u32 s48, s48, 0x40080
	s_addc_u32 s49, s49, 0
	s_add_u32 s68, s50, 0x100
	v_mov_b32_e32 v0, 0
	s_addc_u32 s69, s51, 0
	s_mov_b32 s70, -2
	v_mov_b64_e32 v[0:1], 0
	v_mov_b64_e32 v[2:3], 0
	v_mov_b64_e32 v[4:5], 0
	v_mov_b64_e32 v[6:7], 0
	v_mov_b64_e32 v[12:13], 0
	v_mov_b64_e32 v[14:15], 0
	v_mov_b64_e32 v[20:21], 0
	v_mov_b64_e32 v[22:23], 0
	v_mov_b64_e32 v[28:29], 0
	v_mov_b64_e32 v[30:31], 0
	v_mov_b64_e32 v[36:37], 0
	v_mov_b64_e32 v[38:39], 0
	v_mov_b64_e32 v[44:45], 0
	v_mov_b64_e32 v[46:47], 0
	v_mov_b64_e32 v[52:53], 0
	v_mov_b64_e32 v[54:55], 0
	v_mov_b64_e32 v[8:9], 0
	v_mov_b64_e32 v[10:11], 0
	v_mov_b64_e32 v[16:17], 0
	v_mov_b64_e32 v[18:19], 0
	v_mov_b64_e32 v[24:25], 0
	v_mov_b64_e32 v[26:27], 0
	v_mov_b64_e32 v[32:33], 0
	v_mov_b64_e32 v[34:35], 0
	v_mov_b64_e32 v[40:41], 0
	v_mov_b64_e32 v[42:43], 0
	v_mov_b64_e32 v[48:49], 0
	v_mov_b64_e32 v[50:51], 0
	v_mov_b64_e32 v[56:57], 0
	v_mov_b64_e32 v[58:59], 0
	v_mov_b64_e32 v[60:61], 0
	v_mov_b64_e32 v[62:63], 0
	v_mov_b64_e32 v[64:65], 0
	v_mov_b64_e32 v[66:67], 0
	v_mov_b64_e32 v[68:69], 0
	v_mov_b64_e32 v[70:71], 0
	v_mov_b64_e32 v[80:81], 0
	v_mov_b64_e32 v[82:83], 0
	v_mov_b64_e32 v[84:85], 0
	v_mov_b64_e32 v[86:87], 0
	v_mov_b64_e32 v[96:97], 0
	v_mov_b64_e32 v[98:99], 0
	v_mov_b64_e32 v[100:101], 0
	v_mov_b64_e32 v[102:103], 0
	v_mov_b64_e32 v[112:113], 0
	v_mov_b64_e32 v[114:115], 0
	v_mov_b64_e32 v[116:117], 0
	v_mov_b64_e32 v[118:119], 0
	v_mov_b64_e32 v[72:73], 0
	v_mov_b64_e32 v[74:75], 0
	v_mov_b64_e32 v[76:77], 0
	v_mov_b64_e32 v[78:79], 0
	v_mov_b64_e32 v[88:89], 0
	v_mov_b64_e32 v[90:91], 0
	v_mov_b64_e32 v[92:93], 0
	v_mov_b64_e32 v[94:95], 0
	v_mov_b64_e32 v[104:105], 0
	v_mov_b64_e32 v[106:107], 0
	v_mov_b64_e32 v[108:109], 0
	v_mov_b64_e32 v[110:111], 0
	v_mov_b64_e32 v[120:121], 0
	v_mov_b64_e32 v[122:123], 0
	v_mov_b64_e32 v[124:125], 0
	v_mov_b64_e32 v[126:127], 0

; template <class Epi>
; DI void gemm_phase(int wv, LAS unsigned char* lds, const Gemm g, const StaticOrder& S, const Epi& E) {
;     ...
;         const bool has_next = S.next(ui + 1, nxt);
;         const char* nA = has_next ? (const char*)g.A + (size_t)nxt.pm * tstep : cA; const char* nB = has_next ? (const char*)g.Bt + (size_t)nxt.pn * tstep : cB;
;         for (int t = 0; t < nt; t += 2) {
;             const bool last = (t == nt - 2);
;             const char* a1 = cA + (size_t)(t + 1) * kstep;
;             const char* a2 = last ? nA : cA + (size_t)(t + 2) * kstep; const char* b2 = last ? nB : cB + (size_t)(t + 2) * kstep;
;             const char* a3 = a2 + kstep; const char* b3 = b2 + kstep;
;     ...
; #pragma unroll
;         for (int a = 0; a < 2; ++a)
; #pragma unroll
;             for (int b = 0; b < 2; ++b)
; #pragma unroll
;                 for (int m = 0; m < 4; ++m)
; #pragma unroll
;                     for (int n = 0; n < 2; ++n) acc[a][b][m][n] = (f32x4){0.f, 0.f, 0.f, 0.f};
;         cur = nxt; cA = nA; cB = nB; ++ui;
.LBB0_703:
	s_ashr_i32 s21, s20, 31
	v_cmp_lt_i64_e32 vcc, s[28:29], v[138:139]
	s_lshl_b64 s[28:29], s[20:21], 17
	s_add_u32 s28, s8, s28
	s_addc_u32 s29, s9, s29
	s_and_b64 s[30:31], vcc, exec
	s_cselect_b32 s13, s29, s49
	s_cselect_b32 s21, s28, s48
	s_ashr_i32 s19, s18, 31
	s_lshl_b64 s[30:31], s[18:19], 17
	s_add_u32 s30, s11, s30
	s_addc_u32 s31, s41, s31
	s_and_b64 s[62:63], vcc, exec
	v_mov_b32_e32 v0, 0
	s_cselect_b32 s19, s31, s39
	s_cselect_b32 s37, s30, s38
	s_mov_b32 s66, 0
	s_mov_b64 s[62:63], -1
	s_mov_b64 s[64:65], 0
	v_mov_b64_e32 v[0:1], 0
	v_mov_b64_e32 v[2:3], 0
	v_mov_b64_e32 v[4:5], 0
	v_mov_b64_e32 v[6:7], 0
	v_mov_b64_e32 v[12:13], 0
	v_mov_b64_e32 v[14:15], 0
	v_mov_b64_e32 v[20:21], 0
	v_mov_b64_e32 v[22:23], 0
	v_mov_b64_e32 v[28:29], 0
	v_mov_b64_e32 v[30:31], 0
	v_mov_b64_e32 v[36:37], 0
	v_mov_b64_e32 v[38:39], 0
	v_mov_b64_e32 v[44:45], 0
	v_mov_b64_e32 v[46:47], 0
	v_mov_b64_e32 v[52:53], 0
	v_mov_b64_e32 v[54:55], 0
	v_mov_b64_e32 v[8:9], 0
	v_mov_b64_e32 v[10:11], 0
	v_mov_b64_e32 v[16:17], 0
	v_mov_b64_e32 v[18:19], 0
	v_mov_b64_e32 v[24:25], 0
	v_mov_b64_e32 v[26:27], 0
	v_mov_b64_e32 v[32:33], 0
	v_mov_b64_e32 v[34:35], 0
	v_mov_b64_e32 v[40:41], 0
	v_mov_b64_e32 v[42:43], 0
	v_mov_b64_e32 v[48:49], 0
	v_mov_b64_e32 v[50:51], 0
	v_mov_b64_e32 v[56:57], 0
	v_mov_b64_e32 v[58:59], 0
	v_mov_b64_e32 v[60:61], 0
	v_mov_b64_e32 v[62:63], 0
	v_mov_b64_e32 v[64:65], 0
	v_mov_b64_e32 v[66:67], 0
	v_mov_b64_e32 v[68:69], 0
	v_mov_b64_e32 v[70:71], 0
	v_mov_b64_e32 v[76:77], 0
	v_mov_b64_e32 v[78:79], 0
	v_mov_b64_e32 v[84:85], 0
	v_mov_b64_e32 v[86:87], 0
	v_mov_b64_e32 v[92:93], 0
	v_mov_b64_e32 v[94:95], 0
	v_mov_b64_e32 v[100:101], 0
	v_mov_b64_e32 v[102:103], 0
	v_mov_b64_e32 v[108:109], 0
	v_mov_b64_e32 v[110:111], 0
	v_mov_b64_e32 v[116:117], 0
	v_mov_b64_e32 v[118:119], 0
	v_mov_b64_e32 v[72:73], 0
	v_mov_b64_e32 v[74:75], 0
	v_mov_b64_e32 v[80:81], 0
	v_mov_b64_e32 v[82:83], 0
	v_mov_b64_e32 v[88:89], 0
	v_mov_b64_e32 v[90:91], 0
	v_mov_b64_e32 v[96:97], 0
	v_mov_b64_e32 v[98:99], 0
	v_mov_b64_e32 v[104:105], 0
	v_mov_b64_e32 v[106:107], 0
	v_mov_b64_e32 v[112:113], 0
	v_mov_b64_e32 v[114:115], 0
	v_mov_b64_e32 v[120:121], 0
	v_mov_b64_e32 v[122:123], 0
	v_mov_b64_e32 v[124:125], 0
	v_mov_b64_e32 v[126:127], 0

; template <class Epi>
; DI void gemm_phase(int wv, LAS unsigned char* lds, const Gemm g, const StaticOrder& S, const Epi& E) {
;     ...
;         const bool has_next = S.next(ui + 1, nxt);
;         const char* nA = has_next ? (const char*)g.A + (size_t)nxt.pm * tstep : cA; const char* nB = has_next ? (const char*)g.Bt + (size_t)nxt.pn * tstep : cB;
;         for (int t = 0; t < nt; t += 2) {
;             const bool last = (t == nt - 2);
;             const char* a1 = cA + (size_t)(t + 1) * kstep;
;             const char* a2 = last ? nA : cA + (size_t)(t + 2) * kstep; const char* b2 = last ? nB : cB + (size_t)(t + 2) * kstep;
;             const char* a3 = a2 + kstep; const char* b3 = b2 + kstep;
;     ...
; #pragma unroll
;         for (int a = 0; a < 2; ++a)
; #pragma unroll
;             for (int b = 0; b < 2; ++b)
; #pragma unroll
;                 for (int m = 0; m < 4; ++m)
; #pragma unroll
;                     for (int n = 0; n < 2; ++n) acc[a][b][m][n] = (f32x4){0.f, 0.f, 0.f, 0.f};
;         cur = nxt; cA = nA; cB = nB; ++ui;
.LBB0_809:
	s_ashr_i32 s21, s20, 31
	v_cmp_lt_i64_e32 vcc, s[28:29], v[138:139]
	s_lshl_b64 s[28:29], s[20:21], 17
	s_add_u32 s28, s11, s28
	s_addc_u32 s29, s41, s29
	s_and_b64 s[30:31], vcc, exec
	s_cselect_b32 s13, s29, s49
	s_cselect_b32 s21, s28, s48
	s_ashr_i32 s19, s18, 31
	s_lshl_b64 s[30:31], s[18:19], 17
	s_add_u32 s30, s8, s30
	s_addc_u32 s31, s9, s31
	s_and_b64 s[62:63], vcc, exec
	v_mov_b32_e32 v0, 0
	s_cselect_b32 s19, s31, s39
	s_cselect_b32 s37, s30, s38
	s_mov_b32 s66, 0
	s_mov_b64 s[62:63], -1
	s_mov_b64 s[64:65], 0
	v_mov_b64_e32 v[0:1], 0
	v_mov_b64_e32 v[2:3], 0
	v_mov_b64_e32 v[4:5], 0
	v_mov_b64_e32 v[6:7], 0
	v_mov_b64_e32 v[12:13], 0
	v_mov_b64_e32 v[14:15], 0
	v_mov_b64_e32 v[20:21], 0
	v_mov_b64_e32 v[22:23], 0
	v_mov_b64_e32 v[28:29], 0
	v_mov_b64_e32 v[30:31], 0
	v_mov_b64_e32 v[36:37], 0
	v_mov_b64_e32 v[38:39], 0
	v_mov_b64_e32 v[44:45], 0
	v_mov_b64_e32 v[46:47], 0
	v_mov_b64_e32 v[52:53], 0
	v_mov_b64_e32 v[54:55], 0
	v_mov_b64_e32 v[8:9], 0
	v_mov_b64_e32 v[10:11], 0
	v_mov_b64_e32 v[16:17], 0
	v_mov_b64_e32 v[18:19], 0
	v_mov_b64_e32 v[24:25], 0
	v_mov_b64_e32 v[26:27], 0
	v_mov_b64_e32 v[32:33], 0
	v_mov_b64_e32 v[34:35], 0
	v_mov_b64_e32 v[40:41], 0
	v_mov_b64_e32 v[42:43], 0
	v_mov_b64_e32 v[48:49], 0
	v_mov_b64_e32 v[50:51], 0
	v_mov_b64_e32 v[56:57], 0
	v_mov_b64_e32 v[58:59], 0
	v_mov_b64_e32 v[60:61], 0
	v_mov_b64_e32 v[62:63], 0
	v_mov_b64_e32 v[64:65], 0
	v_mov_b64_e32 v[66:67], 0
	v_mov_b64_e32 v[68:69], 0
	v_mov_b64_e32 v[70:71], 0
	v_mov_b64_e32 v[76:77], 0
	v_mov_b64_e32 v[78:79], 0
	v_mov_b64_e32 v[84:85], 0
	v_mov_b64_e32 v[86:87], 0
	v_mov_b64_e32 v[92:93], 0
	v_mov_b64_e32 v[94:95], 0
	v_mov_b64_e32 v[100:101], 0
	v_mov_b64_e32 v[102:103], 0
	v_mov_b64_e32 v[108:109], 0
	v_mov_b64_e32 v[110:111], 0
	v_mov_b64_e32 v[116:117], 0
	v_mov_b64_e32 v[118:119], 0
	v_mov_b64_e32 v[72:73], 0
	v_mov_b64_e32 v[74:75], 0
	v_mov_b64_e32 v[80:81], 0
	v_mov_b64_e32 v[82:83], 0
	v_mov_b64_e32 v[88:89], 0
	v_mov_b64_e32 v[90:91], 0
	v_mov_b64_e32 v[96:97], 0
	v_mov_b64_e32 v[98:99], 0
	v_mov_b64_e32 v[104:105], 0
	v_mov_b64_e32 v[106:107], 0
	v_mov_b64_e32 v[112:113], 0
	v_mov_b64_e32 v[114:115], 0
	v_mov_b64_e32 v[120:121], 0
	v_mov_b64_e32 v[122:123], 0
	v_mov_b64_e32 v[124:125], 0
	v_mov_b64_e32 v[126:127], 0

; DI void chunk_decode(int g, int& seq, int& c) { if (g < NCP) { seq = 0; c = g; } else { seq = 1 + (g - NCP) / NCS; c = (g - NCP) % NCS; } }
; DI void chunk_range(int c, int& t0, int& t1) { if (c == 0) { t0 = 0; t1 = 16; } else { t0 = 16 + 128 * (c - 1); t1 = t0 + 128; } }
; template <int DIR> DI void scan_item(const Params& p, int l, LAS float* L, LAS float* CL, int item, int lane) {
;     ...
;     const int g = item >> 3, hd = (item >> 1) & 3;
;     int seq, c; chunk_decode(g, seq, c); int t0, t1; chunk_range(c, t0, t1);
;     const int base = seq_start(seq), nsub = (t1 - t0) >> 3, ch = hd * 64 + lane;
;     const int la = lane >> 2, lb = lane & 3;
;     CL[lane] = p.in[16][(size_t)l * 256 + ch]; CL[64 + lane] = p.in[17][(size_t)l * 256 + ch];
;     f32x2 SU[4][8], SP[4][8];
; #pragma unroll
;     for (int ri = 0; ri < 4; ++ri)
; #pragma unroll
;         for (int cp = 0; cp < 8; ++cp) { SU[ri][cp] = (f32x2){0.f, 0.f}; SP[ri][cp] = (f32x2){(4 * la + ri == 16 * lb + 2 * cp) ? 1.f : 0.f, (4 * la + ri == 16 * lb + 2 * cp + 1) ? 1.f : 0.f}; }
;     const int ss = lane >> 3, cg = lane & 7;
.LBB0_909:
	v_bfe_u32 v13, v64, 1, 2
	v_ashrrev_i32_e32 v1, 3, v64
	s_movk_i32 s9, 0x80
	v_lshl_or_b32 v68, v13, 7, v188
	v_cmp_lt_i32_e64 s[20:21], s9, v1
	s_and_saveexec_b64 s[10:11], s[18:19]
	s_xor_b64 s[88:89], exec, s[10:11]
	s_cbranch_execz .LBB0_919
	v_mov_b32_e32 v94, 0
	v_mov_b32_e32 v15, 0
	s_and_saveexec_b64 s[90:91], s[20:21]
	v_lshrrev_b32_e32 v0, 3, v64
	v_add_u16_e32 v0, 0xff7f, v0
	v_mul_u32_u24_e32 v1, 0xf0f1, v0
	v_lshrrev_b32_e32 v1, 20, v1
	v_add_u16_e32 v15, 1, v1
	v_mul_lo_u16_e32 v1, 17, v1
	v_sub_u16_e32 v1, v0, v1
	s_or_b64 exec, exec, s[90:91]
	v_lshlrev_b32_e32 v23, 6, v13
	v_or_b32_e32 v0, v23, v93
	v_lshlrev_b32_e32 v0, 2, v0
	global_load_dword v29, v0, s[36:37]
	global_load_dword v31, v0, s[38:39]
	v_lshlrev_b32_e32 v21, 7, v1
	v_add_u32_e32 v36, 0xffffff90, v21
	v_cmp_ne_u32_e32 vcc, 0, v1
	v_or_b32_e32 v3, 16, v21
	v_mov_b32_e32 v95, v91
	v_cndmask_b32_e32 v1, 0, v36, vcc
	v_sub_u32_e32 v1, v3, v1
	v_ashrrev_i32_e32 v65, 3, v1
	v_mov_b32_e32 v97, v89
	v_mov_b32_e32 v96, 0
	v_mov_b32_e32 v99, v87
	v_mov_b32_e32 v98, 0
	v_mov_b32_e32 v101, v85
	v_mov_b32_e32 v100, 0
	v_mov_b32_e32 v103, 0
	v_mov_b32_e32 v102, v74
	v_mov_b32_e32 v105, 0
	v_mov_b32_e32 v104, v72
	v_mov_b32_e32 v107, 0
	v_mov_b32_e32 v106, v70
	v_mov_b32_e32 v109, 0
	v_mov_b32_e32 v108, v66
	v_mov_b32_e32 v111, v74
	v_mov_b32_e32 v110, 0
	v_mov_b32_e32 v113, v72
	v_mov_b32_e32 v112, 0
	v_mov_b32_e32 v115, v70
	v_mov_b32_e32 v114, 0
	v_mov_b32_e32 v117, v66
	v_mov_b32_e32 v116, 0
	v_mov_b32_e32 v119, 0
	v_mov_b32_e32 v118, v74
	v_mov_b32_e32 v121, 0
	v_mov_b32_e32 v120, v72
	v_mov_b32_e32 v123, 0
	v_mov_b32_e32 v122, v70
	v_mov_b32_e32 v125, 0
	v_mov_b32_e32 v124, v66
	v_mov_b32_e32 v2, 0
	v_mov_b32_e32 v0, 0
	v_mov_b64_e32 v[6:7], 0
	v_mov_b64_e32 v[4:5], 0
	v_mov_b32_e32 v14, 0
	v_mov_b32_e32 v12, 0
	v_mov_b64_e32 v[10:11], 0
	v_mov_b64_e32 v[8:9], 0
	v_mov_b32_e32 v22, 0
	v_mov_b32_e32 v20, 0
	v_mov_b64_e32 v[18:19], 0
	v_mov_b64_e32 v[16:17], 0
	v_mov_b32_e32 v30, 0
	v_mov_b32_e32 v28, 0
	v_mov_b64_e32 v[26:27], 0
	v_mov_b64_e32 v[24:25], 0
	v_mov_b32_e32 v39, 0
	v_mov_b32_e32 v37, 0
	v_mov_b64_e32 v[34:35], 0
	v_mov_b64_e32 v[32:33], 0
	v_mov_b32_e32 v47, 0
	v_mov_b32_e32 v45, 0
	v_mov_b64_e32 v[42:43], 0
	v_mov_b64_e32 v[40:41], 0
	v_mov_b32_e32 v55, 0
	v_mov_b32_e32 v53, 0
	v_mov_b32_e32 v51, 0
	v_cmp_lt_i32_e32 vcc, 0, v65
	v_mov_b32_e32 v50, 0
	v_mov_b32_e32 v49, 0
	v_mov_b32_e32 v48, 0
	v_mov_b32_e32 v63, 0
	v_mov_b32_e32 v61, 0
	v_mov_b32_e32 v59, 0
	v_mov_b32_e32 v58, 0
	v_mov_b32_e32 v57, 0
	v_mov_b32_e32 v56, 0
	s_waitcnt vmcnt(0)
	ds_write2st64_b32 v179, v29, v31 offset1:1
	s_and_saveexec_b64 s[90:91], vcc
	s_cbranch_execz .LBB0_918
	v_mad_u32_u24 v0, v15, s8, v189
	v_cmp_ne_u32_e32 vcc, 0, v15
	v_lshlrev_b32_e32 v4, 2, v13
	v_mov_b32_e32 v5, v69
	v_mov_b32_e32 v12, v69
	v_mov_b32_e32 v13, v69
	s_mov_b32 s9, 0
	v_cndmask_b32_e32 v0, 0, v0, vcc
	v_mov_b32_e32 v1, v69
	v_or_b32_e32 v2, v23, v183
	v_lshl_add_u64 v[4:5], s[70:71], 0, v[4:5]
	v_add_u32_e32 v6, 15, v21
	s_mov_b64 s[92:93], 0
	v_mov_b64_e32 v[14:15], v[12:13]
	v_mov_b64_e32 v[18:19], v[12:13]
	v_mov_b64_e32 v[16:17], v[12:13]
	v_mov_b64_e32 v[20:21], v[12:13]
	v_mov_b64_e32 v[22:23], v[12:13]
	v_mov_b64_e32 v[26:27], v[12:13]
	v_mov_b64_e32 v[24:25], v[12:13]
	v_mov_b64_e32 v[28:29], v[12:13]
	v_mov_b64_e32 v[30:31], v[12:13]
	v_mov_b64_e32 v[34:35], v[12:13]
	v_mov_b64_e32 v[32:33], v[12:13]
	v_mov_b64_e32 v[36:37], v[12:13]
	v_mov_b64_e32 v[38:39], v[12:13]
	v_mov_b64_e32 v[42:43], v[12:13]
	v_mov_b64_e32 v[40:41], v[12:13]
	v_mov_b64_e32 v[44:45], v[12:13]
	v_mov_b64_e32 v[46:47], v[12:13]
	v_mov_b64_e32 v[50:51], v[12:13]
	v_mov_b64_e32 v[48:49], v[12:13]
	v_mov_b64_e32 v[52:53], v[12:13]
	v_mov_b64_e32 v[54:55], v[12:13]
	v_mov_b64_e32 v[58:59], v[12:13]
	v_mov_b64_e32 v[56:57], v[12:13]
	v_mov_b64_e32 v[94:95], v[90:91]
	v_mov_b64_e32 v[126:127], v[12:13]
	v_mov_b64_e32 v[96:97], v[88:89]
	v_mov_b64_e32 v[128:129], v[12:13]
	v_mov_b64_e32 v[98:99], v[86:87]
	v_mov_b64_e32 v[130:131], v[12:13]
	v_mov_b64_e32 v[100:101], v[84:85]
	v_mov_b64_e32 v[132:133], v[12:13]
	v_mov_b64_e32 v[102:103], v[74:75]
	v_mov_b64_e32 v[134:135], v[12:13]
	v_mov_b64_e32 v[104:105], v[72:73]
	v_mov_b64_e32 v[136:137], v[12:13]
	v_mov_b64_e32 v[106:107], v[70:71]
	v_mov_b64_e32 v[138:139], v[12:13]
	v_mov_b64_e32 v[108:109], v[66:67]
	v_mov_b64_e32 v[140:141], v[12:13]
	v_mov_b64_e32 v[142:143], v[12:13]
	v_mov_b64_e32 v[110:111], v[82:83]
	v_mov_b64_e32 v[152:153], v[12:13]
	v_mov_b64_e32 v[112:113], v[80:81]
	v_mov_b64_e32 v[162:163], v[12:13]
	v_mov_b64_e32 v[114:115], v[78:79]
	v_mov_b64_e32 v[164:165], v[12:13]
	v_mov_b64_e32 v[116:117], v[76:77]
	v_mov_b64_e32 v[166:167], v[12:13]
	v_mov_b64_e32 v[118:119], v[74:75]
	v_mov_b64_e32 v[168:169], v[12:13]
	v_mov_b64_e32 v[120:121], v[72:73]
	v_mov_b64_e32 v[62:63], v[12:13]
	v_mov_b64_e32 v[122:123], v[70:71]
	v_mov_b64_e32 v[60:61], v[12:13]
	v_mov_b64_e32 v[124:125], v[66:67]
	v_mov_b64_e32 v[154:155], v[12:13]
	v_mov_b64_e32 v[156:157], v[12:13]
	v_mov_b64_e32 v[158:159], v[12:13]
	v_mov_b64_e32 v[160:161], v[12:13]
	v_mov_b64_e32 v[144:145], v[12:13]
	v_mov_b64_e32 v[146:147], v[12:13]
	v_mov_b64_e32 v[148:149], v[12:13]
	v_mov_b64_e32 v[150:151], v[12:13]

; DI void chunk_decode(int g, int& seq, int& c) { if (g < NCP) { seq = 0; c = g; } else { seq = 1 + (g - NCP) / NCS; c = (g - NCP) % NCS; } }
; DI void chunk_range(int c, int& t0, int& t1) { if (c == 0) { t0 = 0; t1 = 16; } else { t0 = 16 + 128 * (c - 1); t1 = t0 + 128; } }
; template <int DIR> DI void scan_item(const Params& p, int l, LAS float* L, LAS float* CL, int item, int lane) {
;     ...
;     const int g = item >> 3, hd = (item >> 1) & 3;
;     int seq, c; chunk_decode(g, seq, c); int t0, t1; chunk_range(c, t0, t1);
;     const int base = seq_start(seq), nsub = (t1 - t0) >> 3, ch = hd * 64 + lane;
;     const int la = lane >> 2, lb = lane & 3;
;     CL[lane] = p.in[16][(size_t)l * 256 + ch]; CL[64 + lane] = p.in[17][(size_t)l * 256 + ch];
;     f32x2 SU[4][8], SP[4][8];
; #pragma unroll
;     for (int ri = 0; ri < 4; ++ri)
; #pragma unroll
;         for (int cp = 0; cp < 8; ++cp) { SU[ri][cp] = (f32x2){0.f, 0.f}; SP[ri][cp] = (f32x2){(4 * la + ri == 16 * lb + 2 * cp) ? 1.f : 0.f, (4 * la + ri == 16 * lb + 2 * cp + 1) ? 1.f : 0.f}; }
;     const int ss = lane >> 3, cg = lane & 7;
.LBB0_919:
	s_andn2_saveexec_b64 s[88:89], s[88:89]
	s_cbranch_execz .LBB0_908
	v_mov_b32_e32 v94, 0
	v_mov_b32_e32 v15, 0
	s_and_saveexec_b64 s[90:91], s[20:21]
	v_lshrrev_b32_e32 v0, 3, v64
	v_add_u16_e32 v0, 0xff7f, v0
	v_mul_u32_u24_e32 v1, 0xf0f1, v0
	v_lshrrev_b32_e32 v1, 20, v1
	v_add_u16_e32 v15, 1, v1
	v_mul_lo_u16_e32 v1, 17, v1
	v_sub_u16_e32 v1, v0, v1
	s_or_b64 exec, exec, s[90:91]
	v_lshlrev_b32_e32 v21, 6, v13
	v_or_b32_e32 v0, v21, v93
	v_lshlrev_b32_e32 v0, 2, v0
	global_load_dword v23, v0, s[36:37]
	global_load_dword v29, v0, s[38:39]
	v_lshlrev_b32_e32 v3, 7, v1
	v_add_u32_e32 v31, 0xffffff90, v3
	v_cmp_ne_u32_e32 vcc, 0, v1
	v_or_b32_e32 v36, 16, v3
	v_mov_b32_e32 v95, v91
	v_cndmask_b32_e32 v3, 0, v31, vcc
	v_sub_u32_e32 v1, v36, v3
	v_ashrrev_i32_e32 v65, 3, v1
	v_mov_b32_e32 v97, v89
	v_mov_b32_e32 v96, 0
	v_mov_b32_e32 v99, v87
	v_mov_b32_e32 v98, 0
	v_mov_b32_e32 v101, v85
	v_mov_b32_e32 v100, 0
	v_mov_b32_e32 v103, 0
	v_mov_b32_e32 v102, v74
	v_mov_b32_e32 v105, 0
	v_mov_b32_e32 v104, v72
	v_mov_b32_e32 v107, 0
	v_mov_b32_e32 v106, v70
	v_mov_b32_e32 v109, 0
	v_mov_b32_e32 v108, v66
	v_mov_b32_e32 v111, v74
	v_mov_b32_e32 v110, 0
	v_mov_b32_e32 v113, v72
	v_mov_b32_e32 v112, 0
	v_mov_b32_e32 v115, v70
	v_mov_b32_e32 v114, 0
	v_mov_b32_e32 v117, v66
	v_mov_b32_e32 v116, 0
	v_mov_b32_e32 v119, 0
	v_mov_b32_e32 v118, v74
	v_mov_b32_e32 v121, 0
	v_mov_b32_e32 v120, v72
	v_mov_b32_e32 v123, 0
	v_mov_b32_e32 v122, v70
	v_mov_b32_e32 v125, 0
	v_mov_b32_e32 v124, v66
	v_mov_b32_e32 v2, 0
	v_mov_b32_e32 v0, 0
	v_mov_b64_e32 v[6:7], 0
	v_mov_b64_e32 v[4:5], 0
	v_mov_b32_e32 v14, 0
	v_mov_b32_e32 v12, 0
	v_mov_b64_e32 v[10:11], 0
	v_mov_b64_e32 v[8:9], 0
	v_mov_b32_e32 v22, 0
	v_mov_b32_e32 v20, 0
	v_mov_b64_e32 v[18:19], 0
	v_mov_b64_e32 v[16:17], 0
	v_mov_b32_e32 v30, 0
	v_mov_b32_e32 v28, 0
	v_mov_b64_e32 v[26:27], 0
	v_mov_b64_e32 v[24:25], 0
	v_mov_b32_e32 v39, 0
	v_mov_b32_e32 v37, 0
	v_mov_b64_e32 v[34:35], 0
	v_mov_b64_e32 v[32:33], 0
	v_mov_b32_e32 v47, 0
	v_mov_b32_e32 v45, 0
	v_mov_b64_e32 v[42:43], 0
	v_mov_b64_e32 v[40:41], 0
	v_mov_b32_e32 v55, 0
	v_mov_b32_e32 v53, 0
	v_mov_b32_e32 v51, 0
	v_cmp_lt_i32_e32 vcc, 0, v65
	v_mov_b32_e32 v50, 0
	v_mov_b32_e32 v49, 0
	v_mov_b32_e32 v48, 0
	v_mov_b32_e32 v63, 0
	v_mov_b32_e32 v61, 0
	v_mov_b32_e32 v59, 0
	v_mov_b32_e32 v58, 0
	v_mov_b32_e32 v57, 0
	v_mov_b32_e32 v56, 0
	s_waitcnt vmcnt(0)
	ds_write2st64_b32 v179, v23, v29 offset1:1
	s_and_saveexec_b64 s[20:21], vcc
	s_cbranch_execz .LBB0_907
	v_mad_u32_u24 v0, v15, s8, v189
	v_cmp_ne_u32_e32 vcc, 0, v15
	v_lshlrev_b32_e32 v4, 2, v13
	v_mov_b32_e32 v5, v69
	v_lshl_add_u64 v[6:7], s[30:31], 0, v[68:69]
	v_lshl_add_u64 v[8:9], s[28:29], 0, v[68:69]
	v_mov_b32_e32 v68, v69
	s_mov_b32 s9, 0
	v_cndmask_b32_e32 v0, 0, v0, vcc
	v_mov_b32_e32 v1, v69
	v_or_b32_e32 v2, v21, v183
	v_lshl_add_u64 v[4:5], s[70:71], 0, v[4:5]
	s_mov_b64 s[90:91], 0
	v_mov_b32_e32 v10, v3
	v_mov_b64_e32 v[20:21], v[68:69]
	v_mov_b64_e32 v[18:19], v[68:69]
	v_mov_b64_e32 v[22:23], v[68:69]
	v_mov_b64_e32 v[16:17], v[68:69]
	v_mov_b64_e32 v[28:29], v[68:69]
	v_mov_b64_e32 v[26:27], v[68:69]
	v_mov_b64_e32 v[30:31], v[68:69]
	v_mov_b64_e32 v[24:25], v[68:69]
	v_mov_b64_e32 v[36:37], v[68:69]
	v_mov_b64_e32 v[34:35], v[68:69]
	v_mov_b64_e32 v[38:39], v[68:69]
	v_mov_b64_e32 v[32:33], v[68:69]
	v_mov_b64_e32 v[44:45], v[68:69]
	v_mov_b64_e32 v[42:43], v[68:69]
	v_mov_b64_e32 v[46:47], v[68:69]
	v_mov_b64_e32 v[40:41], v[68:69]
	v_mov_b64_e32 v[52:53], v[68:69]
	v_mov_b64_e32 v[50:51], v[68:69]
	v_mov_b64_e32 v[54:55], v[68:69]
	v_mov_b64_e32 v[48:49], v[68:69]
	v_mov_b64_e32 v[60:61], v[68:69]
	v_mov_b64_e32 v[58:59], v[68:69]
	v_mov_b64_e32 v[62:63], v[68:69]
	v_mov_b64_e32 v[56:57], v[68:69]
	v_mov_b64_e32 v[94:95], v[90:91]
	v_mov_b64_e32 v[126:127], v[68:69]
	v_mov_b64_e32 v[96:97], v[88:89]
	v_mov_b64_e32 v[128:129], v[68:69]
	v_mov_b64_e32 v[98:99], v[86:87]
	v_mov_b64_e32 v[130:131], v[68:69]
	v_mov_b64_e32 v[100:101], v[84:85]
	v_mov_b64_e32 v[132:133], v[68:69]
	v_mov_b64_e32 v[102:103], v[74:75]
	v_mov_b64_e32 v[134:135], v[68:69]
	v_mov_b64_e32 v[104:105], v[72:73]
	v_mov_b64_e32 v[136:137], v[68:69]
	v_mov_b64_e32 v[106:107], v[70:71]
	v_mov_b64_e32 v[138:139], v[68:69]
	v_mov_b64_e32 v[108:109], v[66:67]
	v_mov_b64_e32 v[140:141], v[68:69]
	v_mov_b64_e32 v[142:143], v[68:69]
	v_mov_b64_e32 v[110:111], v[82:83]
	v_mov_b64_e32 v[152:153], v[68:69]
	v_mov_b64_e32 v[112:113], v[80:81]
	v_mov_b64_e32 v[162:163], v[68:69]
	v_mov_b64_e32 v[114:115], v[78:79]
	v_mov_b64_e32 v[164:165], v[68:69]
	v_mov_b64_e32 v[116:117], v[76:77]
	v_mov_b64_e32 v[166:167], v[68:69]
	v_mov_b64_e32 v[118:119], v[74:75]
	v_mov_b64_e32 v[168:169], v[68:69]
	v_mov_b64_e32 v[120:121], v[72:73]
	v_mov_b64_e32 v[170:171], v[68:69]
	v_mov_b64_e32 v[122:123], v[70:71]
	v_mov_b64_e32 v[172:173], v[68:69]
	v_mov_b64_e32 v[124:125], v[66:67]
	v_mov_b64_e32 v[154:155], v[68:69]
	v_mov_b64_e32 v[156:157], v[68:69]
	v_mov_b64_e32 v[158:159], v[68:69]
	v_mov_b64_e32 v[160:161], v[68:69]
	v_mov_b64_e32 v[144:145], v[68:69]
	v_mov_b64_e32 v[146:147], v[68:69]
	v_mov_b64_e32 v[148:149], v[68:69]
	v_mov_b64_e32 v[150:151], v[68:69]

; #define LAS __attribute__((address_space(3)))
; #define ATT_GLOAD(k0_, k1_, v_, tile) do { const size_t rb = (size_t)base + (size_t)(tile) * 64; \
;         k0_ = *(const u32x4*)(K + (rb + kkey0) * ldk + koff + kpart0 * 8); \
;         if (kc1 < NKC) k1_ = *(const u32x4*)(K + (rb + kkey1) * ldk + koff + kpart1 * 8); \
;         v_ = *(const u32x4*)(Vt + (size_t)vd * MPAD + rb + vpart * 8); } while (0)
; DI void attn_lut(LAS float* LUT, int tid, const float* relb, int qhead) {
;     if (tid < 259) { const int rel = tid - 129, n = rel < 0 ? -rel : rel; int b;
;         if (n < 8) b = n; else { int m = (31 - __builtin_clz((unsigned)(n * n))) - 6; b = 8 + m; if (b > 15) b = 15; }
;         if (rel > 0) b += 16;
;         LUT[tid] = relb[b * 8 + qhead] * LOG2E; }
; }
; template <int DQK, bool SWA>
; DI void attn_block(int wv, LAS unsigned char* lds, const bf16_t* Q, int ldq, int qoff, const bf16_t* K, int ldk, int koff, const bf16_t* Vt,
;                    int base, int T, int q0, bf16_t* O, int ldo, int ooff, const float* relb, int qhead, float sink_add) {
;     ...
;     const int tid = tid_(wv), lane = tid & 63, w = tid >> 6, r = lane & 31, h = lane >> 5;
;     LAS float* LUT = (LAS float*)(lds + ATT_LUT);
;     __syncthreads();
;     if (SWA) attn_lut(LUT, tid, relb, qhead);
;     const int qw0 = q0 + 32 * w, qpos = qw0 + r; const size_t qrow = (size_t)base + qpos;
;     bf16x8 qf[NKS];
; #pragma unroll
;     for (int ks = 0; ks < NKS; ++ks) qf[ks] = *(const bf16x8*)(Q + qrow * ldq + qoff + 16 * ks + 8 * h);
;     f32x16 o0, o1;
; #pragma unroll
;     for (int i = 0; i < 16; ++i) { o0[i] = 0.f; o1[i] = 0.f; }
;     float lsum = 0.f;
;     const int nt = (T + 63) >> 6;
;     int lo = 0, ntl = nt;
;     if (SWA) { lo = (q0 - 128) >> 6; if (lo < 1) lo = 1; int hi = (q0 + 255 + 128) >> 6; if (hi > nt - 1) hi = nt - 1; ntl = 1 + (hi >= lo ? hi - lo + 1 : 0); }
;     u32x4 kA0, kA1, vA, kB0, kB1, vB;
;     kA1 = (u32x4){0u, 0u, 0u, 0u}; kB1 = kA1;
;     const int kc0 = tid, kc1 = tid + 512;
;     const int kkey0 = kc0 / CPR, kpart0 = kc0 % CPR, kkey1 = kc1 / CPR, kpart1 = kc1 % CPR;
;     const int vd = tid >> 3, vpart = tid & 7;
;     ...
;     ATT_GLOAD(kA0, kA1, vA, ATT_TILE(0)); ATT_LWRITE(kA0, kA1, vA, 0);
;     if (ntl > 1) ATT_GLOAD(kB0, kB1, vB, ATT_TILE(1));
;     if (ntl > 2) ATT_GLOAD(kA0, kA1, vA, ATT_TILE(2));
;     __syncthreads();
.Lswaa_dec:
	s_lshr_b32 s15, s33, 6
	s_lshl_b32 s4, s10, 2
	s_sub_u32 s5, s4, 2
	s_cmp_eq_u32 s10, 0
	s_cselect_b32 s12, 1, s5
	s_add_u32 s5, s4, 5
	s_sub_u32 s6, s13, 1
	s_min_u32 s5, s5, s6
	s_sub_u32 s5, s5, s12
	s_add_u32 s29, s5, 1
	s_lshl_b32 s49, s10, 8
	s_lshl_b32 s4, s15, 5
	s_add_u32 s49, s49, s4
	s_movk_i32 s50, 0xff7f
	s_movk_i32 s51, 0xff80
	s_waitcnt lgkmcnt(0)
	s_lshl_b32 s4, s8, 2
	s_load_dword s46, s[44:45], s4
	v_add_u32_e32 v21, s33, v254
	v_add_u32_e32 v25, 0xffffff40, v21
	v_sub_u32_e32 v23, 0, v25
	v_max_i32_e32 v23, v25, v23
	v_mul_u32_u24_e32 v24, v23, v23
	v_ffbh_u32_e32 v24, v24
	v_sub_u32_e32 v24, 33, v24
	v_min_u32_e32 v24, 15, v24
	v_cmp_gt_u32_e32 vcc, 8, v23
	s_nop 1
	v_cndmask_b32_e32 v24, v24, v23, vcc
	v_cmp_lt_i32_e32 vcc, 0, v25
	s_nop 1
	v_cndmask_b32_e64 v23, 0, 16, vcc
	v_add_u32_e32 v24, v24, v23
	v_lshl_add_u32 v24, v24, 3, s8
	v_lshlrev_b32_e32 v24, 2, v24
	v_min_u32_e32 v24, 0x3fc, v24
	global_load_dword v24, v24, s[42:43]
	s_lshl_b32 s4, s8, 7
	s_add_u32 s16, s40, s4
	s_addc_u32 s17, s41, 0
	s_add_u32 s4, s4, 0x200
	s_add_u32 s22, s34, 0x19548000
	s_addc_u32 s23, s35, 0
	s_add_u32 s22, s22, s4
	s_addc_u32 s23, s23, 0
	s_lshr_b32 s5, s8, 2
	s_lshl_b32 s4, s5, 7
	s_lshl_b32 s6, s11, 8
	s_add_u32 s18, s40, 0x50c0000
	s_addc_u32 s19, s41, 0
	s_add_u32 s18, s18, s4
	s_addc_u32 s19, s19, 0
	s_add_u32 s18, s18, s6
	s_addc_u32 s19, s19, 0
	s_mul_i32 s4, s5, 0xa18000
	s_lshl_b32 s6, s11, 1
	s_add_u32 s20, s34, 0x300a8000
	s_addc_u32 s21, s35, 0
	s_add_u32 s20, s20, s4
	s_addc_u32 s21, s21, 0
	s_add_u32 s20, s20, s6
	s_addc_u32 s21, s21, 0
	v_and_b32_e32 v0, 31, v254
	v_lshrrev_b32_e32 v197, 5, v254
	v_mul_u32_u24_e32 v194, 0x90, v0
	v_add_u32_e32 v195, 0x2400, v194
	v_lshl_add_u32 v194, v197, 4, v194
	v_lshl_add_u32 v195, v197, 3, v195
	v_add_u32_e32 v196, 0x1200, v195
	v_add_u32_e32 v198, s49, v0
	v_lshlrev_b32_e32 v20, 2, v197
	v_sub_u32_e32 v20, v20, v198
	v_add_u32_e32 v198, s11, v198
	v_lshlrev_b32_e32 v199, 10, v198
	v_lshl_add_u32 v199, v197, 4, v199
	v_lshlrev_b32_e32 v198, 11, v198
	v_lshl_add_u32 v200, v197, 3, v198
	v_mov_b32_e32 v19, 0x81
	v_mov_b32_e32 v22, 0x80
	s_movk_i32 s48, 0x71c8
	s_mov_b32 s47, 0x28600
	s_movk_i32 s28, 0x80
	s_movk_i32 s27, 0x4000
	s_add_u32 s4, s15, 0
	s_cmpk_gt_u32 s4, 8
	s_cselect_b32 s7, s47, 0x100
	s_cselect_b32 s36, s28, s27
	s_mov_b32 s37, 0
	s_cselect_b32 s42, s20, s18
	s_cselect_b32 s43, s21, s19
	s_cselect_b32 s5, 9, 0
	s_cselect_b32 s6, 0x2400, 0
	s_sub_u32 s4, s4, s5
	s_cmpk_gt_u32 s4, 8
	s_cselect_b32 s5, 9, 0
	s_sub_u32 s4, s4, s5
	s_lshl_b32 s5, s4, 10
	s_add_u32 s24, s5, s6
	s_lshl_b32 s4, s4, 6
	v_add_u32_e32 v197, s4, v254
	v_mul_lo_u32 v198, v197, s48
	v_lshrrev_b32_e32 v198, 18, v198
	v_mul_u32_u24_e32 v186, 9, v198
	v_sub_u32_e32 v197, v197, v186
	v_cmp_ne_u32_e32 vcc, 8, v197
	s_nop 1
	v_cndmask_b32_e32 v197, 0, v197, vcc
	v_mul_lo_u32 v198, v198, s7
	v_lshl_add_u32 v186, v197, 4, v198
	v_mov_b32_e32 v187, 0
	v_lshl_add_u64 v[186:187], s[42:43], 0, v[186:187]
	s_add_u32 s4, s15, 8
	s_cmpk_gt_u32 s4, 8
	s_cselect_b32 s7, s47, 0x100
	s_cselect_b32 s38, s28, s27
	s_mov_b32 s39, 0
	s_cselect_b32 s42, s20, s18
	s_cselect_b32 s43, s21, s19
	s_cselect_b32 s5, 9, 0
	s_cselect_b32 s6, 0x2400, 0
	s_sub_u32 s4, s4, s5
	s_cmpk_gt_u32 s4, 8
	s_cselect_b32 s5, 9, 0
	s_sub_u32 s4, s4, s5
	s_lshl_b32 s5, s4, 10
	s_add_u32 s25, s5, s6
	s_lshl_b32 s4, s4, 6
	v_add_u32_e32 v197, s4, v254
	v_mul_lo_u32 v198, v197, s48
	v_lshrrev_b32_e32 v198, 18, v198
	v_mul_u32_u24_e32 v188, 9, v198
	v_sub_u32_e32 v197, v197, v188
	v_cmp_ne_u32_e32 vcc, 8, v197
	s_nop 1
	v_cndmask_b32_e32 v197, 0, v197, vcc
	v_mul_lo_u32 v198, v198, s7
	v_lshl_add_u32 v188, v197, 4, v198
	v_mov_b32_e32 v189, 0
	v_lshl_add_u64 v[188:189], s[42:43], 0, v[188:189]
	s_add_u32 s4, s15, 16
	s_cmpk_gt_u32 s4, 8
	s_cselect_b32 s7, s47, 0x100
	s_cselect_b32 s40, s28, s27
	s_mov_b32 s41, 0
	s_cselect_b32 s42, s20, s18
	s_cselect_b32 s43, s21, s19
	s_cselect_b32 s5, 9, 0
	s_cselect_b32 s6, 0x2400, 0
	s_sub_u32 s4, s4, s5
	s_cmpk_gt_u32 s4, 8
	s_cselect_b32 s5, 9, 0
	s_sub_u32 s4, s4, s5
	s_lshl_b32 s5, s4, 10
	s_add_u32 s26, s5, s6
	s_lshl_b32 s4, s4, 6
	v_add_u32_e32 v197, s4, v254
	v_mul_lo_u32 v198, v197, s48
	v_lshrrev_b32_e32 v198, 18, v198
	v_mul_u32_u24_e32 v190, 9, v198
	v_sub_u32_e32 v197, v197, v190
	v_cmp_ne_u32_e32 vcc, 8, v197
	s_nop 1
	v_cndmask_b32_e32 v197, 0, v197, vcc
	v_mul_lo_u32 v198, v198, s7
	v_lshl_add_u32 v190, v197, 4, v198
	v_mov_b32_e32 v191, 0
	v_lshl_add_u64 v[190:191], s[42:43], 0, v[190:191]
	global_load_dwordx4 v[2:5], v199, s[16:17] offset:0
	global_load_dwordx4 v[6:9], v199, s[16:17] offset:32
	global_load_dwordx4 v[10:13], v199, s[16:17] offset:64
	global_load_dwordx4 v[14:17], v199, s[16:17] offset:96
	s_mov_b32 s28, 0x0
	s_add_u32 m0, s28, s24
	s_nop 0
	global_load_lds_dwordx4 v[186:187], off
	s_mul_i32 s4, s36, s12
	s_mov_b32 s5, 0
	v_lshl_add_u64 v[186:187], v[186:187], 0, s[4:5]
	s_add_u32 m0, s28, s25
	s_nop 0
	global_load_lds_dwordx4 v[188:189], off
	s_mul_i32 s4, s38, s12
	s_mov_b32 s5, 0
	v_lshl_add_u64 v[188:189], v[188:189], 0, s[4:5]
	s_add_u32 m0, s28, s26
	s_nop 0
	global_load_lds_dwordx4 v[190:191], off
	s_mul_i32 s4, s40, s12
	s_mov_b32 s5, 0
	v_lshl_add_u64 v[190:191], v[190:191], 0, s[4:5]
	s_mov_b32 s28, 0x4800
	s_add_u32 m0, s28, s24
	s_nop 0
	global_load_lds_dwordx4 v[186:187], off
	v_lshl_add_u64 v[186:187], v[186:187], 0, s[36:37]
	s_add_u32 m0, s28, s25
	s_nop 0
	global_load_lds_dwordx4 v[188:189], off
	v_lshl_add_u64 v[188:189], v[188:189], 0, s[38:39]
	s_add_u32 m0, s28, s26
	s_nop 0
	global_load_lds_dwordx4 v[190:191], off
	v_lshl_add_u64 v[190:191], v[190:191], 0, s[40:41]
	s_mov_b32 s28, 0xf000
	s_add_u32 m0, s28, s24
	s_nop 0
	global_load_lds_dwordx4 v[186:187], off
	v_lshl_add_u64 v[186:187], v[186:187], 0, s[36:37]
	s_add_u32 m0, s28, s25
	s_nop 0
	global_load_lds_dwordx4 v[188:189], off
	v_lshl_add_u64 v[188:189], v[188:189], 0, s[38:39]
	s_add_u32 m0, s28, s26
	s_nop 0
	global_load_lds_dwordx4 v[190:191], off
	v_lshl_add_u64 v[190:191], v[190:191], 0, s[40:41]
	s_mov_b32 s28, 0x13800
	s_add_u32 m0, s28, s24
	s_nop 0
	global_load_lds_dwordx4 v[186:187], off
	v_lshl_add_u64 v[186:187], v[186:187], 0, s[36:37]
	s_add_u32 m0, s28, s25
	s_nop 0
	global_load_lds_dwordx4 v[188:189], off
	v_lshl_add_u64 v[188:189], v[188:189], 0, s[38:39]
	s_add_u32 m0, s28, s26
	s_nop 0
	global_load_lds_dwordx4 v[190:191], off
	v_lshl_add_u64 v[190:191], v[190:191], 0, s[40:41]
	v_mov_b64_e32 v[26:27], 0
	v_mov_b64_e32 v[28:29], 0
	v_mov_b64_e32 v[30:31], 0
	v_mov_b64_e32 v[32:33], 0
	v_mov_b64_e32 v[34:35], 0
	v_mov_b64_e32 v[36:37], 0
	v_mov_b64_e32 v[38:39], 0
	v_mov_b64_e32 v[40:41], 0
	v_mov_b64_e32 v[42:43], 0
	v_mov_b64_e32 v[44:45], 0
	v_mov_b64_e32 v[46:47], 0
	v_mov_b64_e32 v[48:49], 0
	v_mov_b64_e32 v[50:51], 0
	v_mov_b64_e32 v[52:53], 0
	v_mov_b64_e32 v[54:55], 0
	v_mov_b64_e32 v[56:57], 0
	v_mov_b64_e32 v[192:193], 0
	s_waitcnt vmcnt(16)
; #define LAS __attribute__((address_space(3)))
; #define ATT_GLOAD(k0_, k1_, v_, tile) do { const size_t rb = (size_t)base + (size_t)(tile) * 64; \
;         k0_ = *(const u32x4*)(K + (rb + kkey0) * ldk + koff + kpart0 * 8); \
;         if (kc1 < NKC) k1_ = *(const u32x4*)(K + (rb + kkey1) * ldk + koff + kpart1 * 8); \
;         v_ = *(const u32x4*)(Vt + (size_t)vd * MPAD + rb + vpart * 8); } while (0)
; #define ATT_LWRITE(k0_, k1_, v_, b) do { LAS unsigned char* kb = lds + (b) * ATT_BUF; \
;         *(LAS u32x4*)(kb + kkey0 * KP + kpart0 * 16) = k0_; \
;         if (kc1 < NKC) *(LAS u32x4*)(kb + kkey1 * KP + kpart1 * 16) = k1_; \
;         *(LAS u32x4*)(kb + KSZ + vd * 144 + vpart * 16) = v_; } while (0)
; DI void attn_lut(LAS float* LUT, int tid, const float* relb, int qhead) {
;     if (tid < 259) { const int rel = tid - 129, n = rel < 0 ? -rel : rel; int b;
;         if (n < 8) b = n; else { int m = (31 - __builtin_clz((unsigned)(n * n))) - 6; b = 8 + m; if (b > 15) b = 15; }
;         if (rel > 0) b += 16;
;         LUT[tid] = relb[b * 8 + qhead] * LOG2E; }
; }
; template <int DQK, bool SWA>
; DI void attn_block(int wv, LAS unsigned char* lds, const bf16_t* Q, int ldq, int qoff, const bf16_t* K, int ldk, int koff, const bf16_t* Vt,
;                    int base, int T, int q0, bf16_t* O, int ldo, int ooff, const float* relb, int qhead, float sink_add) {
;     ...
;     ATT_GLOAD(kA0, kA1, vA, ATT_TILE(0)); ATT_LWRITE(kA0, kA1, vA, 0);
;     if (ntl > 1) ATT_GLOAD(kB0, kB1, vB, ATT_TILE(1));
;     if (ntl > 2) ATT_GLOAD(kA0, kA1, vA, ATT_TILE(2));
;     __syncthreads();
	v_mul_f32_e32 v24, 0x3fb8aa3b, v24
	v_mov_b32_e32 v23, 0xf149f2ca
	v_add_u32_e32 v25, 0xffffff40, v21
	v_sub_u32_e32 v18, 0, v25
	v_max_i32_e32 v18, v25, v18
	v_cmp_lt_u32_e32 vcc, 0x80, v18
	s_nop 1
	v_cndmask_b32_e32 v24, v24, v23, vcc
	v_lshlrev_b32_e32 v25, 2, v21
	v_cmp_gt_u32_e32 vcc, 0x181, v21
	s_and_saveexec_b64 s[4:5], vcc
	ds_write_b32 v25, v24 offset:49152
	s_mov_b64 exec, s[4:5]
	s_mov_b32 s14, 0
	s_mov_b32 s30, 0x0
	s_mov_b32 s31, 0x18000
	s_waitcnt vmcnt(9) lgkmcnt(0)
	s_barrier
	s_cmpk_lt_u32 s15, 4
	s_cbranch_scc1 .Lswaa_noskew
	s_barrier

; #define LAS __attribute__((address_space(3)))
; #define ATT_GLOAD(k0_, k1_, v_, tile) do { const size_t rb = (size_t)base + (size_t)(tile) * 64; \
;         k0_ = *(const u32x4*)(K + (rb + kkey0) * ldk + koff + kpart0 * 8); \
;         if (kc1 < NKC) k1_ = *(const u32x4*)(K + (rb + kkey1) * ldk + koff + kpart1 * 8); \
;         v_ = *(const u32x4*)(Vt + (size_t)vd * MPAD + rb + vpart * 8); } while (0)
; template <int DQK, bool SWA>
; DI void attn_block(int wv, LAS unsigned char* lds, const bf16_t* Q, int ldq, int qoff, const bf16_t* K, int ldk, int koff, const bf16_t* Vt,
;                    int base, int T, int q0, bf16_t* O, int ldo, int ooff, const float* relb, int qhead, float sink_add) {
;     constexpr int KP = DQK * 2 + 16, CPR = DQK / 8, NKC = 64 * CPR, NKS = DQK / 16, KSZ = 13312;
;     const int tid = tid_(wv), lane = tid & 63, w = tid >> 6, r = lane & 31, h = lane >> 5;
;     LAS float* LUT = (LAS float*)(lds + ATT_LUT);
;     __syncthreads();
;     if (SWA) attn_lut(LUT, tid, relb, qhead);
;     const int qw0 = q0 + 32 * w, qpos = qw0 + r; const size_t qrow = (size_t)base + qpos;
;     bf16x8 qf[NKS];
; #pragma unroll
;     for (int ks = 0; ks < NKS; ++ks) qf[ks] = *(const bf16x8*)(Q + qrow * ldq + qoff + 16 * ks + 8 * h);
;     f32x16 o0, o1;
; #pragma unroll
;     for (int i = 0; i < 16; ++i) { o0[i] = 0.f; o1[i] = 0.f; }
;     float lsum = 0.f;
;     const int nt = (T + 63) >> 6;
;     int lo = 0, ntl = nt;
;     if (SWA) { lo = (q0 - 128) >> 6; if (lo < 1) lo = 1; int hi = (q0 + 255 + 128) >> 6; if (hi > nt - 1) hi = nt - 1; ntl = 1 + (hi >= lo ? hi - lo + 1 : 0); }
;     u32x4 kA0, kA1, vA, kB0, kB1, vB;
;     kA1 = (u32x4){0u, 0u, 0u, 0u}; kB1 = kA1;
;     const int kc0 = tid, kc1 = tid + 512;
;     const int kkey0 = kc0 / CPR, kpart0 = kc0 % CPR, kkey1 = kc1 / CPR, kpart1 = kc1 % CPR;
;     const int vd = tid >> 3, vpart = tid & 7;
;     ...
;     ATT_GLOAD(kA0, kA1, vA, ATT_TILE(0)); ATT_LWRITE(kA0, kA1, vA, 0);
;     if (ntl > 1) ATT_GLOAD(kB0, kB1, vB, ATT_TILE(1));
;     if (ntl > 2) ATT_GLOAD(kA0, kA1, vA, ATT_TILE(2));
;     __syncthreads();
.Lmlaa_dec:
	s_lshr_b32 s15, s33, 6
	s_mul_i32 s4, s8, 0xc0
	s_add_u32 s16, s34, 0x25f28000
	s_addc_u32 s17, s35, 0
	s_add_u32 s16, s16, s4
	s_addc_u32 s17, s17, 0
	s_mul_i32 s5, s11, 0x300
	s_add_u32 s18, s34, 0x29bb8000
	s_addc_u32 s19, s35, 0
	s_add_u32 s18, s18, s4
	s_addc_u32 s19, s19, 0
	s_add_u32 s18, s18, s5
	s_addc_u32 s19, s19, 0
	s_mul_i32 s4, s8, 0xa18000
	s_add_u32 s20, s34, 0x2d848000
	s_addc_u32 s21, s35, 0
	s_add_u32 s20, s20, s4
	s_addc_u32 s21, s21, 0
	s_lshl_b32 s4, s11, 1
	s_add_u32 s20, s20, s4
	s_addc_u32 s21, s21, 0
	s_lshl_b32 s4, s8, 7
	s_add_u32 s4, s4, 0x600
	s_add_u32 s22, s34, 0x19548000
	s_addc_u32 s23, s35, 0
	s_add_u32 s22, s22, s4
	s_addc_u32 s23, s23, 0
	v_and_b32_e32 v0, 31, v254
	v_lshrrev_b32_e32 v197, 5, v254
	v_mul_u32_u24_e32 v194, 0xd0, v0
	v_lshl_add_u32 v194, v197, 4, v194
	v_mul_u32_u24_e32 v195, 0x90, v0
	v_lshl_add_u32 v195, v197, 3, v195
	v_add_u32_e32 v195, 0x3400, v195
	v_add_u32_e32 v196, 0x1200, v195
	s_lshl_b32 s4, s10, 8
	s_add_u32 s4, s4, s11
	s_lshl_b32 s5, s15, 5
	s_add_u32 s4, s4, s5
	v_add_u32_e32 v198, s4, v0
	v_mul_u32_u24_e32 v199, 0x300, v198
	v_lshl_add_u32 v199, v197, 4, v199
	v_lshlrev_b32_e32 v198, 11, v198
	v_lshl_add_u32 v200, v197, 3, v198
	s_movk_i32 s48, 0x71c8
	s_movk_i32 s49, 0x4ec5
	s_mov_b32 s50, 0x28600
	s_movk_i32 s51, 0x300
	s_movk_i32 s28, 0x80
	s_mov_b32 s29, 0xc000
	s_add_u32 s4, s15, 0
	s_cmpk_gt_u32 s4, 12
	s_cselect_b32 s5, 9, 13
	s_cselect_b32 s6, s48, s49
	s_cselect_b32 s7, s50, s51
	s_cselect_b32 s36, s28, s29
	s_mov_b32 s37, 0
	s_cselect_b32 s44, s20, s18
	s_cselect_b32 s45, s21, s19
	s_cselect_b32 s46, 13, 0
	s_cselect_b32 s47, 0x3400, 0
	s_sub_u32 s4, s4, s46
	s_cmpk_gt_u32 s4, 8
	s_cselect_b32 s46, 9, 0
	s_cmpk_gt_u32 s47, 0
	s_cselect_b32 s46, s46, 0
	s_sub_u32 s4, s4, s46
	s_lshl_b32 s46, s4, 10
	s_add_u32 s24, s46, s47
	s_lshl_b32 s4, s4, 6
	v_add_u32_e32 v197, s4, v254
	v_mul_lo_u32 v198, v197, s6
	v_lshrrev_b32_e32 v198, 18, v198
	v_mul_lo_u32 v186, v198, s5
	v_sub_u32_e32 v197, v197, v186
	s_sub_u32 s4, s5, 1
	v_cmp_ne_u32_e32 vcc, s4, v197
	s_nop 1
	v_cndmask_b32_e32 v197, 0, v197, vcc
	v_mul_lo_u32 v198, v198, s7
	v_lshl_add_u32 v186, v197, 4, v198
	v_mov_b32_e32 v187, 0
	v_lshl_add_u64 v[186:187], s[44:45], 0, v[186:187]
	s_add_u32 s4, s15, 8
	s_cmpk_gt_u32 s4, 12
	s_cselect_b32 s5, 9, 13
	s_cselect_b32 s6, s48, s49
	s_cselect_b32 s7, s50, s51
	s_cselect_b32 s38, s28, s29
	s_mov_b32 s39, 0
	s_cselect_b32 s44, s20, s18
	s_cselect_b32 s45, s21, s19
	s_cselect_b32 s46, 13, 0
	s_cselect_b32 s47, 0x3400, 0
	s_sub_u32 s4, s4, s46
	s_cmpk_gt_u32 s4, 8
	s_cselect_b32 s46, 9, 0
	s_cmpk_gt_u32 s47, 0
	s_cselect_b32 s46, s46, 0
	s_sub_u32 s4, s4, s46
	s_lshl_b32 s46, s4, 10
	s_add_u32 s25, s46, s47
	s_lshl_b32 s4, s4, 6
	v_add_u32_e32 v197, s4, v254
	v_mul_lo_u32 v198, v197, s6
	v_lshrrev_b32_e32 v198, 18, v198
	v_mul_lo_u32 v188, v198, s5
	v_sub_u32_e32 v197, v197, v188
	s_sub_u32 s4, s5, 1
	v_cmp_ne_u32_e32 vcc, s4, v197
	s_nop 1
	v_cndmask_b32_e32 v197, 0, v197, vcc
	v_mul_lo_u32 v198, v198, s7
	v_lshl_add_u32 v188, v197, 4, v198
	v_mov_b32_e32 v189, 0
	v_lshl_add_u64 v[188:189], s[44:45], 0, v[188:189]
	s_add_u32 s4, s15, 16
	s_cmpk_gt_u32 s4, 12
	s_cselect_b32 s5, 9, 13
	s_cselect_b32 s6, s48, s49
	s_cselect_b32 s7, s50, s51
	s_cselect_b32 s40, s28, s29
	s_mov_b32 s41, 0
	s_cselect_b32 s44, s20, s18
	s_cselect_b32 s45, s21, s19
	s_cselect_b32 s46, 13, 0
	s_cselect_b32 s47, 0x3400, 0
	s_sub_u32 s4, s4, s46
	s_cmpk_gt_u32 s4, 8
	s_cselect_b32 s46, 9, 0
	s_cmpk_gt_u32 s47, 0
	s_cselect_b32 s46, s46, 0
	s_sub_u32 s4, s4, s46
	s_lshl_b32 s46, s4, 10
	s_add_u32 s26, s46, s47
	s_lshl_b32 s4, s4, 6
	v_add_u32_e32 v197, s4, v254
	v_mul_lo_u32 v198, v197, s6
	v_lshrrev_b32_e32 v198, 18, v198
	v_mul_lo_u32 v190, v198, s5
	v_sub_u32_e32 v197, v197, v190
	s_sub_u32 s4, s5, 1
	v_cmp_ne_u32_e32 vcc, s4, v197
	s_nop 1
	v_cndmask_b32_e32 v197, 0, v197, vcc
	v_mul_lo_u32 v198, v198, s7
	v_lshl_add_u32 v190, v197, 4, v198
	v_mov_b32_e32 v191, 0
	v_lshl_add_u64 v[190:191], s[44:45], 0, v[190:191]
	global_load_dwordx4 v[2:5], v199, s[16:17] offset:0
	global_load_dwordx4 v[6:9], v199, s[16:17] offset:32
	global_load_dwordx4 v[10:13], v199, s[16:17] offset:64
	global_load_dwordx4 v[14:17], v199, s[16:17] offset:96
	global_load_dwordx4 v[18:21], v199, s[16:17] offset:128
	global_load_dwordx4 v[22:25], v199, s[16:17] offset:160
	s_mov_b32 s28, 0x0
	s_add_u32 m0, s28, s24
	s_nop 0
	global_load_lds_dwordx4 v[186:187], off
	v_lshl_add_u64 v[186:187], v[186:187], 0, s[36:37]
	s_add_u32 m0, s28, s25
	s_nop 0
	global_load_lds_dwordx4 v[188:189], off
	v_lshl_add_u64 v[188:189], v[188:189], 0, s[38:39]
	s_add_u32 m0, s28, s26
	s_nop 0
	global_load_lds_dwordx4 v[190:191], off
	v_lshl_add_u64 v[190:191], v[190:191], 0, s[40:41]
	s_mov_b32 s28, 0x5800
	s_add_u32 m0, s28, s24
	s_nop 0
	global_load_lds_dwordx4 v[186:187], off
	v_lshl_add_u64 v[186:187], v[186:187], 0, s[36:37]
	s_add_u32 m0, s28, s25
	s_nop 0
	global_load_lds_dwordx4 v[188:189], off
	v_lshl_add_u64 v[188:189], v[188:189], 0, s[38:39]
	s_add_u32 m0, s28, s26
	s_nop 0
	global_load_lds_dwordx4 v[190:191], off
	v_lshl_add_u64 v[190:191], v[190:191], 0, s[40:41]
	s_mov_b32 s28, 0xf000
	s_add_u32 m0, s28, s24
	s_nop 0
	global_load_lds_dwordx4 v[186:187], off
	v_lshl_add_u64 v[186:187], v[186:187], 0, s[36:37]
	s_add_u32 m0, s28, s25
	s_nop 0
	global_load_lds_dwordx4 v[188:189], off
	v_lshl_add_u64 v[188:189], v[188:189], 0, s[38:39]
	s_add_u32 m0, s28, s26
	s_nop 0
	global_load_lds_dwordx4 v[190:191], off
	v_lshl_add_u64 v[190:191], v[190:191], 0, s[40:41]
	s_mov_b32 s28, 0x14800
	s_add_u32 m0, s28, s24
	s_nop 0
	global_load_lds_dwordx4 v[186:187], off
	v_lshl_add_u64 v[186:187], v[186:187], 0, s[36:37]
	s_add_u32 m0, s28, s25
	s_nop 0
	global_load_lds_dwordx4 v[188:189], off
	v_lshl_add_u64 v[188:189], v[188:189], 0, s[38:39]
	s_add_u32 m0, s28, s26
	s_nop 0
	global_load_lds_dwordx4 v[190:191], off
	v_lshl_add_u64 v[190:191], v[190:191], 0, s[40:41]
	v_mov_b64_e32 v[26:27], 0
	v_mov_b64_e32 v[28:29], 0
	v_mov_b64_e32 v[30:31], 0
	v_mov_b64_e32 v[32:33], 0
	v_mov_b64_e32 v[34:35], 0
	v_mov_b64_e32 v[36:37], 0
	v_mov_b64_e32 v[38:39], 0
	v_mov_b64_e32 v[40:41], 0
	v_mov_b64_e32 v[42:43], 0
	v_mov_b64_e32 v[44:45], 0
	v_mov_b64_e32 v[46:47], 0
	v_mov_b64_e32 v[48:49], 0
	v_mov_b64_e32 v[50:51], 0
	v_mov_b64_e32 v[52:53], 0
	v_mov_b64_e32 v[54:55], 0
	v_mov_b64_e32 v[56:57], 0
	v_mov_b64_e32 v[192:193], 0
	s_mov_b32 s14, 0
	s_mov_b32 s30, 0x0
	s_mov_b32 s31, 0x1a000
	s_sub_u32 s29, s13, 1
	s_waitcnt vmcnt(9)
	s_barrier
	s_cmpk_lt_u32 s15, 4
	s_cbranch_scc1 .Lmlaa_noskew
	s_barrier

; #define LAS __attribute__((address_space(3)))
; template <int DQK, bool SWA>
; DI void attn_tail(int wv, LAS unsigned char* lds, const bf16_t* Q, int ldq, int qoff, const bf16_t* K, int ldk, int koff, const bf16_t* Vt,
;                   int base, int T, int q0, bf16_t* O, int ldo, int ooff, const float* relb, int qhead, float sink_add) {
;     constexpr int NKS = DQK / 16;
;     const int tid = tid_(wv), lane = tid & 63, w = tid >> 6, r = lane & 31, h = lane >> 5;
;     LAS float* LUT = (LAS float*)(lds + ATT_LUT); LAS float* RED = (LAS float*)(lds + ATT_RED);
;     __syncthreads();
;     if (SWA) attn_lut(LUT, tid, relb, qhead);
;     for (int e = tid; e < 64 * 33; e += 512) RED[e] = 0.f;
;     const int qpos = q0 + r; const bool qvalid = qpos < T; const size_t qrow = (size_t)base + (qvalid ? qpos : T - 1);
;     bf16x8 qf[NKS];
; #pragma unroll
;     for (int ks = 0; ks < NKS; ++ks) qf[ks] = *(const bf16x8*)(Q + qrow * ldq + qoff + 16 * ks + 8 * h);
;     f32x16 o0, o1;
; #pragma unroll
;     for (int i = 0; i < 16; ++i) { o0[i] = 0.f; o1[i] = 0.f; }
;     float lsum = 0.f;
;     const int nt = (T + 63) >> 6;
;     int lo = 0, ntl = nt;
;     if (SWA) { lo = (q0 - 128) >> 6; if (lo < 1) lo = 1; int hi = nt - 1; ntl = 1 + (hi >= lo ? hi - lo + 1 : 0); }
;     __syncthreads();
.LBB0_1178:
	s_or_b64 exec, exec, s[6:7]
	s_waitcnt vmcnt(0)
	v_mul_f32_e32 v0, 0x3fb8aa3b, v0
	s_add_i32 s12, s52, 0x3800
	v_exp_f32_e32 v109, v0
	v_and_b32_e32 v0, 31, v108
	s_and_b64 s[6:7], s[76:77], exec
	v_or_b32_e32 v107, s91, v0
	s_cselect_b32 s79, 0, 0
	s_cselect_b32 s78, 0, s12
	s_add_i32 s6, s90, -1
	v_min_u32_e32 v2, s6, v107
	v_add_u32_e32 v2, s78, v2
	v_mov_b32_e32 v3, v1
	v_lshlrev_b64 v[2:3], 10, v[2:3]
	v_bfe_u32 v34, v108, 5, 1
	v_lshl_add_u64 v[2:3], s[16:17], 0, v[2:3]
	s_lshl_b32 s6, s14, 7
	s_mov_b32 s7, s15
	v_lshl_add_u64 v[2:3], v[2:3], 0, s[6:7]
	v_lshlrev_b32_e32 v4, 4, v34
	v_mov_b32_e32 v5, v1
	v_lshl_add_u64 v[2:3], v[2:3], 0, v[4:5]
	global_load_dwordx4 v[50:53], v[2:3], off
	global_load_dwordx4 v[54:57], v[2:3], off offset:32
	global_load_dwordx4 v[58:61], v[2:3], off offset:64
	global_load_dwordx4 v[62:65], v[2:3], off offset:96
	s_add_i32 s6, s90, 63
	s_lshr_b32 s7, s6, 6
	s_add_i32 s6, s90, 0xffffff70
	s_lshr_b32 s6, s6, 6
	v_mov_b32_e32 v2, s6
	v_ashrrev_i32_e32 v110, 6, v106
	v_sub_u32_e64 v111, s7, v2 clamp
	v_mov_b32_e32 v17, 0
	v_lshlrev_b32_e32 v94, 3, v34
	v_cmp_le_i32_e32 vcc, v110, v111
	v_mov_b64_e32 v[16:17], 0
	v_mov_b64_e32 v[14:15], 0
	v_mov_b64_e32 v[12:13], 0
	v_mov_b64_e32 v[10:11], 0
	v_mov_b64_e32 v[8:9], 0
	v_mov_b64_e32 v[6:7], 0
	v_mov_b64_e32 v[4:5], 0
	v_mov_b64_e32 v[2:3], 0
	v_mov_b64_e32 v[32:33], 0
	v_mov_b64_e32 v[30:31], 0
	v_mov_b64_e32 v[28:29], 0
	v_mov_b64_e32 v[26:27], 0
	v_mov_b64_e32 v[24:25], 0
	v_mov_b64_e32 v[22:23], 0
	v_mov_b64_e32 v[20:21], 0
	v_mov_b64_e32 v[18:19], 0
	v_mov_b32_e32 v113, 0
	s_waitcnt lgkmcnt(0)
	s_barrier
	s_and_saveexec_b64 s[80:81], vcc
	s_cbranch_execz .LBB0_1219
	s_lshr_b32 s7, s14, 2
	s_mul_i32 s12, s7, 0xa18000
	s_mul_hi_u32 s13, s7, 0xa18000
	s_add_u32 s12, s87, s12
	s_addc_u32 s13, s88, s13
	s_lshl_b32 s7, s7, 7
	s_add_u32 s82, s38, s7
	s_addc_u32 s83, s39, 0
	v_lshlrev_b32_e32 v2, 1, v94
	v_mov_b32_e32 v3, v1
	v_lshl_add_u64 v[96:97], s[82:83], 0, v[2:3]
	v_mov_b64_e32 v[2:3], s[12:13]
	v_mul_u32_u24_e32 v4, 0x28600, v0
	v_mov_b32_e32 v5, v1
	v_mov_b32_e32 v95, v1
	v_mad_u64_u32 v[2:3], s[82:83], v0, s50, v[2:3]
	v_lshl_add_u64 v[4:5], s[12:13], 0, v[4:5]
	v_lshl_add_u64 v[98:99], v[2:3], 0, v[94:95]
	v_lshl_add_u64 v[2:3], v[4:5], 0, v[94:95]
	v_lshl_add_u64 v[100:101], v[2:3], 0, s[72:73]
	v_add_u32_e32 v2, s6, v110
	v_mov_b32_e32 v113, 0
	v_lshlrev_b32_e32 v112, 2, v34
	v_lshl_add_u32 v95, v2, 6, v204
	s_mov_b64 s[82:83], 0
	v_mov_b32_e32 v2, 0
	v_mov_b32_e32 v3, v113
	v_mov_b32_e32 v4, v113
	v_mov_b32_e32 v5, v113
	v_mov_b32_e32 v6, v113
	v_mov_b32_e32 v7, v113
	v_mov_b32_e32 v8, v113
	v_mov_b32_e32 v9, v113
	v_mov_b32_e32 v10, v113
	v_mov_b32_e32 v11, v113
	v_mov_b32_e32 v12, v113
	v_mov_b32_e32 v13, v113
	v_mov_b32_e32 v14, v113
	v_mov_b32_e32 v15, v113
	v_mov_b32_e32 v16, v113
	v_mov_b32_e32 v17, v113
	v_mov_b32_e32 v18, 0
	v_mov_b32_e32 v19, v113
	v_mov_b32_e32 v20, v113
	v_mov_b32_e32 v21, v113
	v_mov_b32_e32 v22, v113
	v_mov_b32_e32 v23, v113
	v_mov_b32_e32 v24, v113
	v_mov_b32_e32 v25, v113
	v_mov_b32_e32 v26, v113
	v_mov_b32_e32 v27, v113
	v_mov_b32_e32 v28, v113
	v_mov_b32_e32 v29, v113
	v_mov_b32_e32 v30, v113
	v_mov_b32_e32 v31, v113
	v_mov_b32_e32 v32, v113
	v_mov_b32_e32 v33, v113
	s_branch .LBB0_1181

; #define LAS __attribute__((address_space(3)))
; template <int DQK, bool SWA>
; DI void attn_tail(int wv, LAS unsigned char* lds, const bf16_t* Q, int ldq, int qoff, const bf16_t* K, int ldk, int koff, const bf16_t* Vt,
;                   int base, int T, int q0, bf16_t* O, int ldo, int ooff, const float* relb, int qhead, float sink_add) {
;     constexpr int NKS = DQK / 16;
;     const int tid = tid_(wv), lane = tid & 63, w = tid >> 6, r = lane & 31, h = lane >> 5;
;     LAS float* LUT = (LAS float*)(lds + ATT_LUT); LAS float* RED = (LAS float*)(lds + ATT_RED);
;     __syncthreads();
;     if (SWA) attn_lut(LUT, tid, relb, qhead);
;     for (int e = tid; e < 64 * 33; e += 512) RED[e] = 0.f;
;     const int qpos = q0 + r; const bool qvalid = qpos < T; const size_t qrow = (size_t)base + (qvalid ? qpos : T - 1);
;     bf16x8 qf[NKS];
; #pragma unroll
;     for (int ks = 0; ks < NKS; ++ks) qf[ks] = *(const bf16x8*)(Q + qrow * ldq + qoff + 16 * ks + 8 * h);
;     f32x16 o0, o1;
; #pragma unroll
;     for (int i = 0; i < 16; ++i) { o0[i] = 0.f; o1[i] = 0.f; }
;     float lsum = 0.f;
;     const int nt = (T + 63) >> 6;
;     int lo = 0, ntl = nt;
;     if (SWA) { lo = (q0 - 128) >> 6; if (lo < 1) lo = 1; int hi = nt - 1; ntl = 1 + (hi >= lo ? hi - lo + 1 : 0); }
;     __syncthreads();
.LBB0_1228:
	s_or_b64 exec, exec, s[6:7]
	s_addk_i32 s52, 0x3800
	v_and_b32_e32 v0, 31, v88
	s_and_b64 s[6:7], s[76:77], exec
	v_or_b32_e32 v86, s91, v0
	s_cselect_b32 s7, 0, 0
	s_cselect_b32 s6, 0, s52
	s_add_i32 s12, s90, -1
	s_waitcnt vmcnt(0)
	v_min_u32_e32 v2, s12, v86
	s_mul_i32 s14, s74, 0x60
	v_add_u32_e32 v4, s6, v2
	v_mov_b64_e32 v[2:3], s[30:31]
	v_bfe_u32 v34, v88, 5, 1
	v_mad_u64_u32 v[2:3], s[12:13], v4, s54, v[2:3]
	s_lshl_b32 s14, s14, 1
	v_lshl_add_u64 v[2:3], v[2:3], 0, s[14:15]
	v_lshlrev_b32_e32 v4, 4, v34
	v_mov_b32_e32 v5, v1
	v_lshl_add_u64 v[2:3], v[2:3], 0, v[4:5]
	global_load_dwordx4 v[50:53], v[2:3], off
	global_load_dwordx4 v[54:57], v[2:3], off offset:32
	global_load_dwordx4 v[58:61], v[2:3], off offset:64
	global_load_dwordx4 v[62:65], v[2:3], off offset:96
	global_load_dwordx4 v[66:69], v[2:3], off offset:128
	global_load_dwordx4 v[70:73], v[2:3], off offset:160
	s_add_i32 s12, s90, 63
	v_ashrrev_i32_e32 v89, 6, v87
	s_lshr_b32 s75, s12, 6
	v_mov_b32_e32 v17, 0
	v_lshlrev_b32_e32 v74, 3, v34
	v_cmp_gt_i32_e32 vcc, s75, v89
	v_mov_b64_e32 v[16:17], 0
	v_mov_b64_e32 v[14:15], 0
	v_mov_b64_e32 v[12:13], 0
	v_mov_b64_e32 v[10:11], 0
	v_mov_b64_e32 v[8:9], 0
	v_mov_b64_e32 v[6:7], 0
	v_mov_b64_e32 v[4:5], 0
	v_mov_b64_e32 v[2:3], 0
	v_mov_b64_e32 v[32:33], 0
	v_mov_b64_e32 v[30:31], 0
	v_mov_b64_e32 v[28:29], 0
	v_mov_b64_e32 v[26:27], 0
	v_mov_b64_e32 v[24:25], 0
	v_mov_b64_e32 v[22:23], 0
	v_mov_b64_e32 v[20:21], 0
	v_mov_b64_e32 v[18:19], 0
	v_mov_b32_e32 v75, 0
	s_waitcnt lgkmcnt(0)
	s_barrier
	s_and_saveexec_b64 s[12:13], vcc
	s_cbranch_execz .LBB0_1232
	s_mul_i32 s52, s74, 0x50c000
	s_mov_b32 s53, s15
	s_lshl_b64 s[52:53], s[52:53], 1
	s_add_u32 s52, s41, s52
	s_addc_u32 s53, s86, s53
	s_add_u32 s76, s36, s14
	s_addc_u32 s77, s37, 0
	v_lshlrev_b32_e32 v2, 1, v74
	v_mov_b32_e32 v3, v1
	v_lshl_add_u64 v[76:77], s[76:77], 0, v[2:3]
	v_mov_b64_e32 v[2:3], s[52:53]
	v_mul_u32_u24_e32 v4, 0x28600, v0
	v_mov_b32_e32 v5, v1
	v_mov_b32_e32 v75, v1
	v_mad_u64_u32 v[2:3], s[76:77], v0, s50, v[2:3]
	v_lshl_add_u64 v[4:5], s[52:53], 0, v[4:5]
	v_lshl_add_u64 v[78:79], v[2:3], 0, v[74:75]
	v_lshl_add_u64 v[2:3], v[4:5], 0, v[74:75]
	v_mov_b32_e32 v75, 0
	v_lshlrev_b32_e32 v90, 2, v34
	v_lshl_add_u64 v[80:81], v[2:3], 0, s[72:73]
	v_lshlrev_b32_e32 v82, 6, v89
	s_mov_b64 s[76:77], 0
	v_mov_b32_e32 v2, 0
	v_mov_b32_e32 v3, v75
	v_mov_b32_e32 v4, v75
	v_mov_b32_e32 v5, v75
	v_mov_b32_e32 v6, v75
	v_mov_b32_e32 v7, v75
	v_mov_b32_e32 v8, v75
	v_mov_b32_e32 v9, v75
	v_mov_b32_e32 v10, v75
	v_mov_b32_e32 v11, v75
	v_mov_b32_e32 v12, v75
	v_mov_b32_e32 v13, v75
	v_mov_b32_e32 v14, v75
	v_mov_b32_e32 v15, v75
	v_mov_b32_e32 v16, v75
	v_mov_b32_e32 v17, v75
	v_mov_b32_e32 v18, 0
	v_mov_b32_e32 v19, v75
	v_mov_b32_e32 v20, v75
	v_mov_b32_e32 v21, v75
	v_mov_b32_e32 v22, v75
	v_mov_b32_e32 v23, v75
	v_mov_b32_e32 v24, v75
	v_mov_b32_e32 v25, v75
	v_mov_b32_e32 v26, v75
	v_mov_b32_e32 v27, v75
	v_mov_b32_e32 v28, v75
	v_mov_b32_e32 v29, v75
	v_mov_b32_e32 v30, v75
	v_mov_b32_e32 v31, v75
	v_mov_b32_e32 v32, v75
	v_mov_b32_e32 v33, v75

; template <class Epi>
; DI void gemm_phase(int wv, LAS unsigned char* lds, const Gemm g, const StaticOrder& S, const Epi& E) {
;     ...
;         const bool has_next = S.next(ui + 1, nxt);
;         const char* nA = has_next ? (const char*)g.A + (size_t)nxt.pm * tstep : cA; const char* nB = has_next ? (const char*)g.Bt + (size_t)nxt.pn * tstep : cB;
;         for (int t = 0; t < nt; t += 2) {
;             const bool last = (t == nt - 2);
;             const char* a1 = cA + (size_t)(t + 1) * kstep;
;             const char* a2 = last ? nA : cA + (size_t)(t + 2) * kstep; const char* b2 = last ? nB : cB + (size_t)(t + 2) * kstep;
;             const char* a3 = a2 + kstep; const char* b3 = b2 + kstep;
;     ...
; #pragma unroll
;         for (int a = 0; a < 2; ++a)
; #pragma unroll
;             for (int b = 0; b < 2; ++b)
; #pragma unroll
;                 for (int m = 0; m < 4; ++m)
; #pragma unroll
;                     for (int n = 0; n < 2; ++n) acc[a][b][m][n] = (f32x4){0.f, 0.f, 0.f, 0.f};
;         cur = nxt; cA = nA; cB = nB; ++ui;
.LBB0_1373:
	s_ashr_i32 s29, s28, 31
	v_cmp_lt_i64_e32 vcc, s[30:31], v[140:141]
	s_lshl_b64 s[30:31], s[28:29], 19
	s_add_u32 s30, s9, s30
	s_addc_u32 s31, s10, s31
	s_and_b64 s[38:39], vcc, exec
	s_cselect_b32 s29, s31, s63
	s_cselect_b32 s61, s30, s62
	s_ashr_i32 s21, s20, 31
	s_lshl_b64 s[38:39], s[20:21], 19
	s_add_u32 s38, s11, s38
	s_addc_u32 s39, s41, s39
	s_and_b64 s[66:67], vcc, exec
	s_cselect_b32 s21, s39, s65
	s_cselect_b32 s79, s38, s64
	s_add_u32 s80, s64, 0x100
	v_mov_b32_e32 v0, 0
	s_addc_u32 s81, s65, 0
	s_mov_b32 s82, -2
	v_mov_b64_e32 v[0:1], 0
	v_mov_b64_e32 v[2:3], 0
	v_mov_b64_e32 v[4:5], 0
	v_mov_b64_e32 v[6:7], 0
	v_mov_b64_e32 v[8:9], 0
	v_mov_b64_e32 v[10:11], 0
	v_mov_b64_e32 v[16:17], 0
	v_mov_b64_e32 v[18:19], 0
	v_mov_b64_e32 v[24:25], 0
	v_mov_b64_e32 v[26:27], 0
	v_mov_b64_e32 v[32:33], 0
	v_mov_b64_e32 v[34:35], 0
	v_mov_b64_e32 v[40:41], 0
	v_mov_b64_e32 v[42:43], 0
	v_mov_b64_e32 v[48:49], 0
	v_mov_b64_e32 v[50:51], 0
	v_mov_b64_e32 v[12:13], 0
	v_mov_b64_e32 v[14:15], 0
	v_mov_b64_e32 v[20:21], 0
	v_mov_b64_e32 v[22:23], 0
	v_mov_b64_e32 v[28:29], 0
	v_mov_b64_e32 v[30:31], 0
	v_mov_b64_e32 v[36:37], 0
	v_mov_b64_e32 v[38:39], 0
	v_mov_b64_e32 v[44:45], 0
	v_mov_b64_e32 v[46:47], 0
	v_mov_b64_e32 v[52:53], 0
	v_mov_b64_e32 v[54:55], 0
	v_mov_b64_e32 v[56:57], 0
	v_mov_b64_e32 v[58:59], 0
	v_mov_b64_e32 v[60:61], 0
	v_mov_b64_e32 v[62:63], 0
	v_mov_b64_e32 v[64:65], 0
	v_mov_b64_e32 v[66:67], 0
	v_mov_b64_e32 v[68:69], 0
	v_mov_b64_e32 v[70:71], 0
	v_mov_b64_e32 v[72:73], 0
	v_mov_b64_e32 v[74:75], 0
	v_mov_b64_e32 v[76:77], 0
	v_mov_b64_e32 v[78:79], 0
	v_mov_b64_e32 v[84:85], 0
	v_mov_b64_e32 v[86:87], 0
	v_mov_b64_e32 v[92:93], 0
	v_mov_b64_e32 v[94:95], 0
	v_mov_b64_e32 v[100:101], 0
	v_mov_b64_e32 v[102:103], 0
	v_mov_b64_e32 v[108:109], 0
	v_mov_b64_e32 v[110:111], 0
	v_mov_b64_e32 v[80:81], 0
	v_mov_b64_e32 v[82:83], 0
	v_mov_b64_e32 v[88:89], 0
	v_mov_b64_e32 v[90:91], 0
	v_mov_b64_e32 v[96:97], 0
	v_mov_b64_e32 v[98:99], 0
	v_mov_b64_e32 v[104:105], 0
	v_mov_b64_e32 v[106:107], 0
	v_mov_b64_e32 v[112:113], 0
	v_mov_b64_e32 v[114:115], 0
	v_mov_b64_e32 v[116:117], 0
	v_mov_b64_e32 v[118:119], 0
	v_mov_b64_e32 v[120:121], 0
	v_mov_b64_e32 v[122:123], 0
	v_mov_b64_e32 v[124:125], 0
	v_mov_b64_e32 v[126:127], 0

; template <class Epi>
; DI void gemm_phase(int wv, LAS unsigned char* lds, const Gemm g, const StaticOrder& S, const Epi& E) {
;     ...
;         const bool has_next = S.next(ui + 1, nxt);
;         const char* nA = has_next ? (const char*)g.A + (size_t)nxt.pm * tstep : cA; const char* nB = has_next ? (const char*)g.Bt + (size_t)nxt.pn * tstep : cB;
;         for (int t = 0; t < nt; t += 2) {
;             const bool last = (t == nt - 2);
;             const char* a1 = cA + (size_t)(t + 1) * kstep;
;             const char* a2 = last ? nA : cA + (size_t)(t + 2) * kstep; const char* b2 = last ? nB : cB + (size_t)(t + 2) * kstep;
;             const char* a3 = a2 + kstep; const char* b3 = b2 + kstep;
;     ...
; #pragma unroll
;         for (int a = 0; a < 2; ++a)
; #pragma unroll
;             for (int b = 0; b < 2; ++b)
; #pragma unroll
;                 for (int m = 0; m < 4; ++m)
; #pragma unroll
;                     for (int n = 0; n < 2; ++n) acc[a][b][m][n] = (f32x4){0.f, 0.f, 0.f, 0.f};
;         cur = nxt; cA = nA; cB = nB; ++ui;
.LBB0_1529:
	s_ashr_i32 s31, s30, 31
	v_cmp_lt_i64_e32 vcc, s[38:39], v[144:145]
	s_lshl_b64 s[38:39], s[30:31], 19
	s_add_u32 s38, s24, s38
	s_addc_u32 s39, s25, s39
	s_and_b64 s[54:55], vcc, exec
	s_cselect_b32 s31, s39, s59
	s_cselect_b32 s57, s38, s58
	s_ashr_i32 s29, s28, 31
	s_lshl_b64 s[54:55], s[28:29], 19
	s_add_u32 s54, s9, s54
	s_addc_u32 s55, s10, s55
	s_and_b64 s[62:63], vcc, exec
	s_cselect_b32 s29, s55, s61
	s_cselect_b32 s76, s54, s60
	s_add_u32 s58, s58, 0x40080
	s_addc_u32 s59, s59, 0
	s_add_u32 s77, s60, 0x100
	v_mov_b32_e32 v0, 0
	s_addc_u32 s78, s61, 0
	s_mov_b32 s79, -2
	v_mov_b64_e32 v[0:1], 0
	v_mov_b64_e32 v[2:3], 0
	v_mov_b64_e32 v[4:5], 0
	v_mov_b64_e32 v[6:7], 0
	v_mov_b64_e32 v[16:17], 0
	v_mov_b64_e32 v[18:19], 0
	v_mov_b64_e32 v[20:21], 0
	v_mov_b64_e32 v[22:23], 0
	v_mov_b64_e32 v[32:33], 0
	v_mov_b64_e32 v[34:35], 0
	v_mov_b64_e32 v[36:37], 0
	v_mov_b64_e32 v[38:39], 0
	v_mov_b64_e32 v[48:49], 0
	v_mov_b64_e32 v[50:51], 0
	v_mov_b64_e32 v[52:53], 0
	v_mov_b64_e32 v[54:55], 0
	v_mov_b64_e32 v[8:9], 0
	v_mov_b64_e32 v[10:11], 0
	v_mov_b64_e32 v[12:13], 0
	v_mov_b64_e32 v[14:15], 0
	v_mov_b64_e32 v[24:25], 0
	v_mov_b64_e32 v[26:27], 0
	v_mov_b64_e32 v[28:29], 0
	v_mov_b64_e32 v[30:31], 0
	v_mov_b64_e32 v[40:41], 0
	v_mov_b64_e32 v[42:43], 0
	v_mov_b64_e32 v[44:45], 0
	v_mov_b64_e32 v[46:47], 0
	v_mov_b64_e32 v[56:57], 0
	v_mov_b64_e32 v[58:59], 0
	v_mov_b64_e32 v[60:61], 0
	v_mov_b64_e32 v[62:63], 0
	v_mov_b64_e32 v[64:65], 0
	v_mov_b64_e32 v[66:67], 0
	v_mov_b64_e32 v[68:69], 0
	v_mov_b64_e32 v[70:71], 0
	v_mov_b64_e32 v[80:81], 0
	v_mov_b64_e32 v[82:83], 0
	v_mov_b64_e32 v[84:85], 0
	v_mov_b64_e32 v[86:87], 0
	v_mov_b64_e32 v[96:97], 0
	v_mov_b64_e32 v[98:99], 0
	v_mov_b64_e32 v[100:101], 0
	v_mov_b64_e32 v[102:103], 0
	v_mov_b64_e32 v[112:113], 0
	v_mov_b64_e32 v[114:115], 0
	v_mov_b64_e32 v[116:117], 0
	v_mov_b64_e32 v[118:119], 0
	v_mov_b64_e32 v[72:73], 0
	v_mov_b64_e32 v[74:75], 0
	v_mov_b64_e32 v[76:77], 0
	v_mov_b64_e32 v[78:79], 0
	v_mov_b64_e32 v[88:89], 0
	v_mov_b64_e32 v[90:91], 0
	v_mov_b64_e32 v[92:93], 0
	v_mov_b64_e32 v[94:95], 0
	v_mov_b64_e32 v[104:105], 0
	v_mov_b64_e32 v[106:107], 0
	v_mov_b64_e32 v[108:109], 0
	v_mov_b64_e32 v[110:111], 0
	v_mov_b64_e32 v[120:121], 0
	v_mov_b64_e32 v[122:123], 0
	v_mov_b64_e32 v[124:125], 0
	v_mov_b64_e32 v[126:127], 0

; template <class Epi>
; DI void gemm_phase(int wv, LAS unsigned char* lds, const Gemm g, const StaticOrder& S, const Epi& E) {
;     ...
; #pragma unroll
;         for (int a = 0; a < 2; ++a)
; #pragma unroll
;             for (int b = 0; b < 2; ++b)
; #pragma unroll
;                 for (int m = 0; m < 4; ++m)
; #pragma unroll
;                     for (int n = 0; n < 2; ++n) acc[a][b][m][n] = (f32x4){0.f, 0.f, 0.f, 0.f};
;         cur = nxt; cA = nA; cB = nB; ++ui;
.LBB0_1605:
	s_add_u32 s31, s54, 0x100
	v_mov_b32_e32 v0, 0
	s_addc_u32 s74, s55, 0
	s_mov_b32 s75, -2
	v_mov_b64_e32 v[0:1], 0
	v_mov_b64_e32 v[2:3], 0
	v_mov_b64_e32 v[4:5], 0
	v_mov_b64_e32 v[6:7], 0
	v_mov_b64_e32 v[8:9], 0
	v_mov_b64_e32 v[10:11], 0
	v_mov_b64_e32 v[16:17], 0
	v_mov_b64_e32 v[18:19], 0
	v_mov_b64_e32 v[24:25], 0
	v_mov_b64_e32 v[26:27], 0
	v_mov_b64_e32 v[32:33], 0
	v_mov_b64_e32 v[34:35], 0
	v_mov_b64_e32 v[40:41], 0
	v_mov_b64_e32 v[42:43], 0
	v_mov_b64_e32 v[48:49], 0
	v_mov_b64_e32 v[50:51], 0
	v_mov_b64_e32 v[12:13], 0
	v_mov_b64_e32 v[14:15], 0
	v_mov_b64_e32 v[20:21], 0
	v_mov_b64_e32 v[22:23], 0
	v_mov_b64_e32 v[28:29], 0
	v_mov_b64_e32 v[30:31], 0
	v_mov_b64_e32 v[36:37], 0
	v_mov_b64_e32 v[38:39], 0
	v_mov_b64_e32 v[44:45], 0
	v_mov_b64_e32 v[46:47], 0
	v_mov_b64_e32 v[52:53], 0
	v_mov_b64_e32 v[54:55], 0
	v_mov_b64_e32 v[56:57], 0
	v_mov_b64_e32 v[58:59], 0
	v_mov_b64_e32 v[60:61], 0
	v_mov_b64_e32 v[62:63], 0
	v_mov_b64_e32 v[64:65], 0
	v_mov_b64_e32 v[66:67], 0
	v_mov_b64_e32 v[68:69], 0
	v_mov_b64_e32 v[70:71], 0
	v_mov_b64_e32 v[72:73], 0
	v_mov_b64_e32 v[74:75], 0
	v_mov_b64_e32 v[76:77], 0
	v_mov_b64_e32 v[78:79], 0
	v_mov_b64_e32 v[84:85], 0
	v_mov_b64_e32 v[86:87], 0
	v_mov_b64_e32 v[92:93], 0
	v_mov_b64_e32 v[94:95], 0
	v_mov_b64_e32 v[100:101], 0
	v_mov_b64_e32 v[102:103], 0
	v_mov_b64_e32 v[108:109], 0
	v_mov_b64_e32 v[110:111], 0
	v_mov_b64_e32 v[80:81], 0
	v_mov_b64_e32 v[82:83], 0
	v_mov_b64_e32 v[88:89], 0
	v_mov_b64_e32 v[90:91], 0
	v_mov_b64_e32 v[96:97], 0
	v_mov_b64_e32 v[98:99], 0
	v_mov_b64_e32 v[104:105], 0
	v_mov_b64_e32 v[106:107], 0
	v_mov_b64_e32 v[112:113], 0
	v_mov_b64_e32 v[114:115], 0
	v_mov_b64_e32 v[116:117], 0
	v_mov_b64_e32 v[118:119], 0
	v_mov_b64_e32 v[120:121], 0
	v_mov_b64_e32 v[122:123], 0
	v_mov_b64_e32 v[124:125], 0
	v_mov_b64_e32 v[126:127], 0

; template <class Epi>
; DI void gemm_phase(int wv, LAS unsigned char* lds, const Gemm g, const StaticOrder& S, const Epi& E) {
;     ...
;         const bool has_next = S.next(ui + 1, nxt);
;         const char* nA = has_next ? (const char*)g.A + (size_t)nxt.pm * tstep : cA; const char* nB = has_next ? (const char*)g.Bt + (size_t)nxt.pn * tstep : cB;
;         for (int t = 0; t < nt; t += 2) {
;             const bool last = (t == nt - 2);
;             const char* a1 = cA + (size_t)(t + 1) * kstep;
;             const char* a2 = last ? nA : cA + (size_t)(t + 2) * kstep; const char* b2 = last ? nB : cB + (size_t)(t + 2) * kstep;
;             const char* a3 = a2 + kstep; const char* b3 = b2 + kstep;
;     ...
; #pragma unroll
;         for (int a = 0; a < 2; ++a)
; #pragma unroll
;             for (int b = 0; b < 2; ++b)
; #pragma unroll
;                 for (int m = 0; m < 4; ++m)
; #pragma unroll
;                     for (int n = 0; n < 2; ++n) acc[a][b][m][n] = (f32x4){0.f, 0.f, 0.f, 0.f};
;         cur = nxt; cA = nA; cB = nB; ++ui;
.LBB0_1877:
	s_ashr_i32 s27, s26, 31
	v_cmp_lt_i64_e32 vcc, s[28:29], v[144:145]
	s_lshl_b64 s[28:29], s[26:27], 19
	s_add_u32 s28, s20, s28
	s_addc_u32 s29, s21, s29
	s_and_b64 s[30:31], vcc, exec
	s_cselect_b32 s27, s29, s55
	s_cselect_b32 s53, s28, s54
	s_ashr_i32 s25, s24, 31
	s_lshl_b64 s[30:31], s[24:25], 19
	s_add_u32 s30, s9, s30
	s_addc_u32 s31, s10, s31
	s_and_b64 s[58:59], vcc, exec
	s_cselect_b32 s25, s31, s57
	s_cselect_b32 s74, s30, s56
	s_add_u32 s54, s54, 0x40080
	s_addc_u32 s55, s55, 0
	s_add_u32 s75, s56, 0x100
	v_mov_b32_e32 v0, 0
	s_addc_u32 s76, s57, 0
	s_mov_b32 s77, -2
	v_mov_b64_e32 v[0:1], 0
	v_mov_b64_e32 v[2:3], 0
	v_mov_b64_e32 v[4:5], 0
	v_mov_b64_e32 v[6:7], 0
	v_mov_b64_e32 v[16:17], 0
	v_mov_b64_e32 v[18:19], 0
	v_mov_b64_e32 v[20:21], 0
	v_mov_b64_e32 v[22:23], 0
	v_mov_b64_e32 v[32:33], 0
	v_mov_b64_e32 v[34:35], 0
	v_mov_b64_e32 v[36:37], 0
	v_mov_b64_e32 v[38:39], 0
	v_mov_b64_e32 v[48:49], 0
	v_mov_b64_e32 v[50:51], 0
	v_mov_b64_e32 v[52:53], 0
	v_mov_b64_e32 v[54:55], 0
	v_mov_b64_e32 v[8:9], 0
	v_mov_b64_e32 v[10:11], 0
	v_mov_b64_e32 v[12:13], 0
	v_mov_b64_e32 v[14:15], 0
	v_mov_b64_e32 v[24:25], 0
	v_mov_b64_e32 v[26:27], 0
	v_mov_b64_e32 v[28:29], 0
	v_mov_b64_e32 v[30:31], 0
	v_mov_b64_e32 v[40:41], 0
	v_mov_b64_e32 v[42:43], 0
	v_mov_b64_e32 v[44:45], 0
	v_mov_b64_e32 v[46:47], 0
	v_mov_b64_e32 v[56:57], 0
	v_mov_b64_e32 v[58:59], 0
	v_mov_b64_e32 v[60:61], 0
	v_mov_b64_e32 v[62:63], 0
	v_mov_b64_e32 v[64:65], 0
	v_mov_b64_e32 v[66:67], 0
	v_mov_b64_e32 v[68:69], 0
	v_mov_b64_e32 v[70:71], 0
	v_mov_b64_e32 v[80:81], 0
	v_mov_b64_e32 v[82:83], 0
	v_mov_b64_e32 v[84:85], 0
	v_mov_b64_e32 v[86:87], 0
	v_mov_b64_e32 v[96:97], 0
	v_mov_b64_e32 v[98:99], 0
	v_mov_b64_e32 v[100:101], 0
	v_mov_b64_e32 v[102:103], 0
	v_mov_b64_e32 v[112:113], 0
	v_mov_b64_e32 v[114:115], 0
	v_mov_b64_e32 v[116:117], 0
	v_mov_b64_e32 v[118:119], 0
	v_mov_b64_e32 v[72:73], 0
	v_mov_b64_e32 v[74:75], 0
	v_mov_b64_e32 v[76:77], 0
	v_mov_b64_e32 v[78:79], 0
	v_mov_b64_e32 v[88:89], 0
	v_mov_b64_e32 v[90:91], 0
	v_mov_b64_e32 v[92:93], 0
	v_mov_b64_e32 v[94:95], 0
	v_mov_b64_e32 v[104:105], 0
	v_mov_b64_e32 v[106:107], 0
	v_mov_b64_e32 v[108:109], 0
	v_mov_b64_e32 v[110:111], 0
	v_mov_b64_e32 v[120:121], 0
	v_mov_b64_e32 v[122:123], 0
	v_mov_b64_e32 v[124:125], 0
	v_mov_b64_e32 v[126:127], 0

; template <class Epi>
; DI void gemm_phase(int wv, LAS unsigned char* lds, const Gemm g, const StaticOrder& S, const Epi& E) {
;     ...
; #pragma unroll
;         for (int a = 0; a < 2; ++a)
; #pragma unroll
;             for (int b = 0; b < 2; ++b)
; #pragma unroll
;                 for (int m = 0; m < 4; ++m)
; #pragma unroll
;                     for (int n = 0; n < 2; ++n) acc[a][b][m][n] = (f32x4){0.f, 0.f, 0.f, 0.f};
;         cur = nxt; cA = nA; cB = nB; ++ui;
.LBB0_1953:
	s_add_u32 s31, s54, 0x100
	v_mov_b32_e32 v0, 0
	s_addc_u32 s76, s55, 0
	s_mov_b32 s77, -2
	v_mov_b64_e32 v[0:1], 0
	v_mov_b64_e32 v[2:3], 0
	v_mov_b64_e32 v[4:5], 0
	v_mov_b64_e32 v[6:7], 0
	v_mov_b64_e32 v[8:9], 0
	v_mov_b64_e32 v[10:11], 0
	v_mov_b64_e32 v[16:17], 0
	v_mov_b64_e32 v[18:19], 0
	v_mov_b64_e32 v[24:25], 0
	v_mov_b64_e32 v[26:27], 0
	v_mov_b64_e32 v[32:33], 0
	v_mov_b64_e32 v[34:35], 0
	v_mov_b64_e32 v[40:41], 0
	v_mov_b64_e32 v[42:43], 0
	v_mov_b64_e32 v[48:49], 0
	v_mov_b64_e32 v[50:51], 0
	v_mov_b64_e32 v[12:13], 0
	v_mov_b64_e32 v[14:15], 0
	v_mov_b64_e32 v[20:21], 0
	v_mov_b64_e32 v[22:23], 0
	v_mov_b64_e32 v[28:29], 0
	v_mov_b64_e32 v[30:31], 0
	v_mov_b64_e32 v[36:37], 0
	v_mov_b64_e32 v[38:39], 0
	v_mov_b64_e32 v[44:45], 0
	v_mov_b64_e32 v[46:47], 0
	v_mov_b64_e32 v[52:53], 0
	v_mov_b64_e32 v[54:55], 0
	v_mov_b64_e32 v[56:57], 0
	v_mov_b64_e32 v[58:59], 0
	v_mov_b64_e32 v[60:61], 0
	v_mov_b64_e32 v[62:63], 0
	v_mov_b64_e32 v[64:65], 0
	v_mov_b64_e32 v[66:67], 0
	v_mov_b64_e32 v[68:69], 0
	v_mov_b64_e32 v[70:71], 0
	v_mov_b64_e32 v[72:73], 0
	v_mov_b64_e32 v[74:75], 0
	v_mov_b64_e32 v[76:77], 0
	v_mov_b64_e32 v[78:79], 0
	v_mov_b64_e32 v[84:85], 0
	v_mov_b64_e32 v[86:87], 0
	v_mov_b64_e32 v[92:93], 0
	v_mov_b64_e32 v[94:95], 0
	v_mov_b64_e32 v[100:101], 0
	v_mov_b64_e32 v[102:103], 0
	v_mov_b64_e32 v[108:109], 0
	v_mov_b64_e32 v[110:111], 0
	v_mov_b64_e32 v[80:81], 0
	v_mov_b64_e32 v[82:83], 0
	v_mov_b64_e32 v[88:89], 0
	v_mov_b64_e32 v[90:91], 0
	v_mov_b64_e32 v[96:97], 0
	v_mov_b64_e32 v[98:99], 0
	v_mov_b64_e32 v[104:105], 0
	v_mov_b64_e32 v[106:107], 0
	v_mov_b64_e32 v[112:113], 0
	v_mov_b64_e32 v[114:115], 0
	v_mov_b64_e32 v[116:117], 0
	v_mov_b64_e32 v[118:119], 0
	v_mov_b64_e32 v[120:121], 0
	v_mov_b64_e32 v[122:123], 0
	v_mov_b64_e32 v[124:125], 0
	v_mov_b64_e32 v[126:127], 0

; template <class Epi>
; DI void gemm_phase(int wv, LAS unsigned char* lds, const Gemm g, const StaticOrder& S, const Epi& E) {
;     ...
;         const bool has_next = S.next(ui + 1, nxt);
;         const char* nA = has_next ? (const char*)g.A + (size_t)nxt.pm * tstep : cA; const char* nB = has_next ? (const char*)g.Bt + (size_t)nxt.pn * tstep : cB;
;         for (int t = 0; t < nt; t += 2) {
;             const bool last = (t == nt - 2);
;             const char* a1 = cA + (size_t)(t + 1) * kstep;
;             const char* a2 = last ? nA : cA + (size_t)(t + 2) * kstep; const char* b2 = last ? nB : cB + (size_t)(t + 2) * kstep;
;             const char* a3 = a2 + kstep; const char* b3 = b2 + kstep;
;     ...
; #pragma unroll
;         for (int a = 0; a < 2; ++a)
; #pragma unroll
;             for (int b = 0; b < 2; ++b)
; #pragma unroll
;                 for (int m = 0; m < 4; ++m)
; #pragma unroll
;                     for (int n = 0; n < 2; ++n) acc[a][b][m][n] = (f32x4){0.f, 0.f, 0.f, 0.f};
;         cur = nxt; cA = nA; cB = nB; ++ui;
.LBB0_2085:
	s_ashr_i32 s53, s52, 31
	v_cmp_lt_i64_e32 vcc, s[54:55], v[142:143]
	s_lshl_b64 s[54:55], s[52:53], 19
	s_add_u32 s54, s20, s54
	s_addc_u32 s55, s21, s55
	s_and_b64 s[56:57], vcc, exec
	s_cselect_b32 s15, s55, s61
	s_cselect_b32 s53, s54, s60
	s_ashr_i32 s31, s30, 31
	s_lshl_b64 s[56:57], s[30:31], 19
	s_add_u32 s56, s9, s56
	s_addc_u32 s57, s41, s57
	s_and_b64 s[64:65], vcc, exec
	s_cselect_b32 s31, s57, s63
	s_cselect_b32 s59, s56, s62
	s_add_u32 s60, s60, 0x40080
	s_addc_u32 s61, s61, 0
	s_add_u32 s76, s62, 0x100
	v_mov_b32_e32 v0, 0
	s_addc_u32 s77, s63, 0
	s_mov_b32 s78, -2
	v_mov_b64_e32 v[0:1], 0
	v_mov_b64_e32 v[2:3], 0
	v_mov_b64_e32 v[4:5], 0
	v_mov_b64_e32 v[6:7], 0
	v_mov_b64_e32 v[12:13], 0
	v_mov_b64_e32 v[14:15], 0
	v_mov_b64_e32 v[20:21], 0
	v_mov_b64_e32 v[22:23], 0
	v_mov_b64_e32 v[28:29], 0
	v_mov_b64_e32 v[30:31], 0
	v_mov_b64_e32 v[36:37], 0
	v_mov_b64_e32 v[38:39], 0
	v_mov_b64_e32 v[44:45], 0
	v_mov_b64_e32 v[46:47], 0
	v_mov_b64_e32 v[52:53], 0
	v_mov_b64_e32 v[54:55], 0
	v_mov_b64_e32 v[8:9], 0
	v_mov_b64_e32 v[10:11], 0
	v_mov_b64_e32 v[16:17], 0
	v_mov_b64_e32 v[18:19], 0
	v_mov_b64_e32 v[24:25], 0
	v_mov_b64_e32 v[26:27], 0
	v_mov_b64_e32 v[32:33], 0
	v_mov_b64_e32 v[34:35], 0
	v_mov_b64_e32 v[40:41], 0
	v_mov_b64_e32 v[42:43], 0
	v_mov_b64_e32 v[48:49], 0
	v_mov_b64_e32 v[50:51], 0
	v_mov_b64_e32 v[56:57], 0
	v_mov_b64_e32 v[58:59], 0
	v_mov_b64_e32 v[60:61], 0
	v_mov_b64_e32 v[62:63], 0
	v_mov_b64_e32 v[64:65], 0
	v_mov_b64_e32 v[66:67], 0
	v_mov_b64_e32 v[68:69], 0
	v_mov_b64_e32 v[70:71], 0
	v_mov_b64_e32 v[80:81], 0
	v_mov_b64_e32 v[82:83], 0
	v_mov_b64_e32 v[84:85], 0
	v_mov_b64_e32 v[86:87], 0
	v_mov_b64_e32 v[96:97], 0
	v_mov_b64_e32 v[98:99], 0
	v_mov_b64_e32 v[100:101], 0
	v_mov_b64_e32 v[102:103], 0
	v_mov_b64_e32 v[112:113], 0
	v_mov_b64_e32 v[114:115], 0
	v_mov_b64_e32 v[116:117], 0
	v_mov_b64_e32 v[118:119], 0
	v_mov_b64_e32 v[72:73], 0
	v_mov_b64_e32 v[74:75], 0
	v_mov_b64_e32 v[76:77], 0
	v_mov_b64_e32 v[78:79], 0
	v_mov_b64_e32 v[88:89], 0
	v_mov_b64_e32 v[90:91], 0
	v_mov_b64_e32 v[92:93], 0
	v_mov_b64_e32 v[94:95], 0
	v_mov_b64_e32 v[104:105], 0
	v_mov_b64_e32 v[106:107], 0
	v_mov_b64_e32 v[108:109], 0
	v_mov_b64_e32 v[110:111], 0
	v_mov_b64_e32 v[120:121], 0
	v_mov_b64_e32 v[122:123], 0
	v_mov_b64_e32 v[124:125], 0
	v_mov_b64_e32 v[126:127], 0

; template <class Epi>
; DI void gemm_phase(int wv, LAS unsigned char* lds, const Gemm g, const StaticOrder& S, const Epi& E) {
;     ...
;         const bool has_next = S.next(ui + 1, nxt);
;         const char* nA = has_next ? (const char*)g.A + (size_t)nxt.pm * tstep : cA; const char* nB = has_next ? (const char*)g.Bt + (size_t)nxt.pn * tstep : cB;
;         for (int t = 0; t < nt; t += 2) {
;             const bool last = (t == nt - 2);
;             const char* a1 = cA + (size_t)(t + 1) * kstep;
;             const char* a2 = last ? nA : cA + (size_t)(t + 2) * kstep; const char* b2 = last ? nB : cB + (size_t)(t + 2) * kstep;
;             const char* a3 = a2 + kstep; const char* b3 = b2 + kstep;
;     ...
; #pragma unroll
;         for (int a = 0; a < 2; ++a)
; #pragma unroll
;             for (int b = 0; b < 2; ++b)
; #pragma unroll
;                 for (int m = 0; m < 4; ++m)
; #pragma unroll
;                     for (int n = 0; n < 2; ++n) acc[a][b][m][n] = (f32x4){0.f, 0.f, 0.f, 0.f};
;         cur = nxt; cA = nA; cB = nB; ++ui;
.LBB0_2139:
	s_ashr_i32 s53, s52, 31
	v_cmp_lt_i64_e32 vcc, s[54:55], v[142:143]
	s_lshl_b64 s[54:55], s[52:53], 19
	s_add_u32 s54, s9, s54
	s_addc_u32 s55, s41, s55
	s_and_b64 s[56:57], vcc, exec
	s_cselect_b32 s15, s55, s61
	s_cselect_b32 s53, s54, s60
	s_ashr_i32 s31, s30, 31
	s_lshl_b64 s[56:57], s[30:31], 19
	s_add_u32 s56, s20, s56
	s_addc_u32 s57, s21, s57
	s_and_b64 s[64:65], vcc, exec
	s_cselect_b32 s31, s57, s63
	s_cselect_b32 s59, s56, s62
	s_add_u32 s60, s60, 0x40080
	s_addc_u32 s61, s61, 0
	s_add_u32 s76, s62, 0x100
	v_mov_b32_e32 v0, 0
	s_addc_u32 s77, s63, 0
	s_mov_b32 s78, -2
	v_mov_b64_e32 v[0:1], 0
	v_mov_b64_e32 v[2:3], 0
	v_mov_b64_e32 v[4:5], 0
	v_mov_b64_e32 v[6:7], 0
	v_mov_b64_e32 v[12:13], 0
	v_mov_b64_e32 v[14:15], 0
	v_mov_b64_e32 v[20:21], 0
	v_mov_b64_e32 v[22:23], 0
	v_mov_b64_e32 v[28:29], 0
	v_mov_b64_e32 v[30:31], 0
	v_mov_b64_e32 v[36:37], 0
	v_mov_b64_e32 v[38:39], 0
	v_mov_b64_e32 v[44:45], 0
	v_mov_b64_e32 v[46:47], 0
	v_mov_b64_e32 v[52:53], 0
	v_mov_b64_e32 v[54:55], 0
	v_mov_b64_e32 v[8:9], 0
	v_mov_b64_e32 v[10:11], 0
	v_mov_b64_e32 v[16:17], 0
	v_mov_b64_e32 v[18:19], 0
	v_mov_b64_e32 v[24:25], 0
	v_mov_b64_e32 v[26:27], 0
	v_mov_b64_e32 v[32:33], 0
	v_mov_b64_e32 v[34:35], 0
	v_mov_b64_e32 v[40:41], 0
	v_mov_b64_e32 v[42:43], 0
	v_mov_b64_e32 v[48:49], 0
	v_mov_b64_e32 v[50:51], 0
	v_mov_b64_e32 v[56:57], 0
	v_mov_b64_e32 v[58:59], 0
	v_mov_b64_e32 v[60:61], 0
	v_mov_b64_e32 v[62:63], 0
	v_mov_b64_e32 v[64:65], 0
	v_mov_b64_e32 v[66:67], 0
	v_mov_b64_e32 v[68:69], 0
	v_mov_b64_e32 v[70:71], 0
	v_mov_b64_e32 v[80:81], 0
	v_mov_b64_e32 v[82:83], 0
	v_mov_b64_e32 v[84:85], 0
	v_mov_b64_e32 v[86:87], 0
	v_mov_b64_e32 v[96:97], 0
	v_mov_b64_e32 v[98:99], 0
	v_mov_b64_e32 v[100:101], 0
	v_mov_b64_e32 v[102:103], 0
	v_mov_b64_e32 v[112:113], 0
	v_mov_b64_e32 v[114:115], 0
	v_mov_b64_e32 v[116:117], 0
	v_mov_b64_e32 v[118:119], 0
	v_mov_b64_e32 v[72:73], 0
	v_mov_b64_e32 v[74:75], 0
	v_mov_b64_e32 v[76:77], 0
	v_mov_b64_e32 v[78:79], 0
	v_mov_b64_e32 v[88:89], 0
	v_mov_b64_e32 v[90:91], 0
	v_mov_b64_e32 v[92:93], 0
	v_mov_b64_e32 v[94:95], 0
	v_mov_b64_e32 v[104:105], 0
	v_mov_b64_e32 v[106:107], 0
	v_mov_b64_e32 v[108:109], 0
	v_mov_b64_e32 v[110:111], 0
	v_mov_b64_e32 v[120:121], 0
	v_mov_b64_e32 v[122:123], 0
	v_mov_b64_e32 v[124:125], 0
	v_mov_b64_e32 v[126:127], 0

; template <class Epi>
; DI void gemm_phase(int wv, LAS unsigned char* lds, const Gemm g, const StaticOrder& S, const Epi& E) {
;     ...
;         const bool has_next = S.next(ui + 1, nxt);
;         const char* nA = has_next ? (const char*)g.A + (size_t)nxt.pm * tstep : cA; const char* nB = has_next ? (const char*)g.Bt + (size_t)nxt.pn * tstep : cB;
;         for (int t = 0; t < nt; t += 2) {
;             const bool last = (t == nt - 2);
;             const char* a1 = cA + (size_t)(t + 1) * kstep;
;             const char* a2 = last ? nA : cA + (size_t)(t + 2) * kstep; const char* b2 = last ? nB : cB + (size_t)(t + 2) * kstep;
;             const char* a3 = a2 + kstep; const char* b3 = b2 + kstep;
;     ...
; #pragma unroll
;         for (int a = 0; a < 2; ++a)
; #pragma unroll
;             for (int b = 0; b < 2; ++b)
; #pragma unroll
;                 for (int m = 0; m < 4; ++m)
; #pragma unroll
;                     for (int n = 0; n < 2; ++n) acc[a][b][m][n] = (f32x4){0.f, 0.f, 0.f, 0.f};
;         cur = nxt; cA = nA; cB = nB; ++ui;
.LBB0_2337:
	s_ashr_i32 s29, s28, 31
	v_cmp_lt_i64_e32 vcc, s[30:31], v[138:139]
	s_lshl_b64 s[30:31], s[28:29], 17
	s_add_u32 s30, s70, s30
	s_addc_u32 s31, s71, s31
	s_and_b64 s[46:47], vcc, exec
	s_cselect_b32 s11, s31, s55
	s_cselect_b32 s29, s30, s54
	s_ashr_i32 s27, s26, 31
	s_lshl_b64 s[46:47], s[26:27], 17
	s_add_u32 s46, s72, s46
	s_addc_u32 s47, s73, s47
	s_and_b64 s[56:57], vcc, exec
	v_mov_b32_e32 v0, 0
	s_cselect_b32 s27, s47, s53
	s_cselect_b32 s51, s46, s52
	s_mov_b32 s60, 0
	s_mov_b64 s[56:57], -1
	s_mov_b64 s[58:59], 0
	v_mov_b64_e32 v[0:1], 0
	v_mov_b64_e32 v[2:3], 0
	v_mov_b64_e32 v[4:5], 0
	v_mov_b64_e32 v[6:7], 0
	v_mov_b64_e32 v[12:13], 0
	v_mov_b64_e32 v[14:15], 0
	v_mov_b64_e32 v[20:21], 0
	v_mov_b64_e32 v[22:23], 0
	v_mov_b64_e32 v[28:29], 0
	v_mov_b64_e32 v[30:31], 0
	v_mov_b64_e32 v[36:37], 0
	v_mov_b64_e32 v[38:39], 0
	v_mov_b64_e32 v[44:45], 0
	v_mov_b64_e32 v[46:47], 0
	v_mov_b64_e32 v[52:53], 0
	v_mov_b64_e32 v[54:55], 0
	v_mov_b64_e32 v[8:9], 0
	v_mov_b64_e32 v[10:11], 0
	v_mov_b64_e32 v[16:17], 0
	v_mov_b64_e32 v[18:19], 0
	v_mov_b64_e32 v[24:25], 0
	v_mov_b64_e32 v[26:27], 0
	v_mov_b64_e32 v[32:33], 0
	v_mov_b64_e32 v[34:35], 0
	v_mov_b64_e32 v[40:41], 0
	v_mov_b64_e32 v[42:43], 0
	v_mov_b64_e32 v[48:49], 0
	v_mov_b64_e32 v[50:51], 0
	v_mov_b64_e32 v[56:57], 0
	v_mov_b64_e32 v[58:59], 0
	v_mov_b64_e32 v[60:61], 0
	v_mov_b64_e32 v[62:63], 0
	v_mov_b64_e32 v[64:65], 0
	v_mov_b64_e32 v[66:67], 0
	v_mov_b64_e32 v[68:69], 0
	v_mov_b64_e32 v[70:71], 0
	v_mov_b64_e32 v[76:77], 0
	v_mov_b64_e32 v[78:79], 0
	v_mov_b64_e32 v[84:85], 0
	v_mov_b64_e32 v[86:87], 0
	v_mov_b64_e32 v[92:93], 0
	v_mov_b64_e32 v[94:95], 0
	v_mov_b64_e32 v[100:101], 0
	v_mov_b64_e32 v[102:103], 0
	v_mov_b64_e32 v[108:109], 0
	v_mov_b64_e32 v[110:111], 0
	v_mov_b64_e32 v[116:117], 0
	v_mov_b64_e32 v[118:119], 0
	v_mov_b64_e32 v[72:73], 0
	v_mov_b64_e32 v[74:75], 0
	v_mov_b64_e32 v[80:81], 0
	v_mov_b64_e32 v[82:83], 0
	v_mov_b64_e32 v[88:89], 0
	v_mov_b64_e32 v[90:91], 0
	v_mov_b64_e32 v[96:97], 0
	v_mov_b64_e32 v[98:99], 0
	v_mov_b64_e32 v[104:105], 0
	v_mov_b64_e32 v[106:107], 0
	v_mov_b64_e32 v[112:113], 0
	v_mov_b64_e32 v[114:115], 0
	v_mov_b64_e32 v[120:121], 0
	v_mov_b64_e32 v[122:123], 0
	v_mov_b64_e32 v[124:125], 0
	v_mov_b64_e32 v[126:127], 0

; template <class Epi>
; DI void gemm_phase(int wv, LAS unsigned char* lds, const Gemm g, const StaticOrder& S, const Epi& E) {
;     ...
;         const bool has_next = S.next(ui + 1, nxt);
;         const char* nA = has_next ? (const char*)g.A + (size_t)nxt.pm * tstep : cA; const char* nB = has_next ? (const char*)g.Bt + (size_t)nxt.pn * tstep : cB;
;         for (int t = 0; t < nt; t += 2) {
;             const bool last = (t == nt - 2);
;             const char* a1 = cA + (size_t)(t + 1) * kstep;
;             const char* a2 = last ? nA : cA + (size_t)(t + 2) * kstep; const char* b2 = last ? nB : cB + (size_t)(t + 2) * kstep;
;             const char* a3 = a2 + kstep; const char* b3 = b2 + kstep;
;     ...
; #pragma unroll
;         for (int a = 0; a < 2; ++a)
; #pragma unroll
;             for (int b = 0; b < 2; ++b)
; #pragma unroll
;                 for (int m = 0; m < 4; ++m)
; #pragma unroll
;                     for (int n = 0; n < 2; ++n) acc[a][b][m][n] = (f32x4){0.f, 0.f, 0.f, 0.f};
;         cur = nxt; cA = nA; cB = nB; ++ui;
.LBB0_2443:
	s_ashr_i32 s29, s28, 31
	v_cmp_lt_i64_e32 vcc, s[30:31], v[138:139]
	s_lshl_b64 s[30:31], s[28:29], 17
	s_add_u32 s30, s72, s30
	s_addc_u32 s31, s73, s31
	s_and_b64 s[46:47], vcc, exec
	s_cselect_b32 s9, s31, s55
	s_cselect_b32 s29, s30, s54
	s_ashr_i32 s27, s26, 31
	s_lshl_b64 s[46:47], s[26:27], 17
	s_add_u32 s46, s41, s46
	s_addc_u32 s47, s70, s47
	s_and_b64 s[56:57], vcc, exec
	v_mov_b32_e32 v0, 0
	s_cselect_b32 s27, s47, s53
	s_cselect_b32 s51, s46, s52
	s_mov_b32 s60, 0
	s_mov_b64 s[56:57], -1
	s_mov_b64 s[58:59], 0
	v_mov_b64_e32 v[0:1], 0
	v_mov_b64_e32 v[2:3], 0
	v_mov_b64_e32 v[4:5], 0
	v_mov_b64_e32 v[6:7], 0
	v_mov_b64_e32 v[12:13], 0
	v_mov_b64_e32 v[14:15], 0
	v_mov_b64_e32 v[20:21], 0
	v_mov_b64_e32 v[22:23], 0
	v_mov_b64_e32 v[28:29], 0
	v_mov_b64_e32 v[30:31], 0
	v_mov_b64_e32 v[36:37], 0
	v_mov_b64_e32 v[38:39], 0
	v_mov_b64_e32 v[44:45], 0
	v_mov_b64_e32 v[46:47], 0
	v_mov_b64_e32 v[52:53], 0
	v_mov_b64_e32 v[54:55], 0
	v_mov_b64_e32 v[8:9], 0
	v_mov_b64_e32 v[10:11], 0
	v_mov_b64_e32 v[16:17], 0
	v_mov_b64_e32 v[18:19], 0
	v_mov_b64_e32 v[24:25], 0
	v_mov_b64_e32 v[26:27], 0
	v_mov_b64_e32 v[32:33], 0
	v_mov_b64_e32 v[34:35], 0
	v_mov_b64_e32 v[40:41], 0
	v_mov_b64_e32 v[42:43], 0
	v_mov_b64_e32 v[48:49], 0
	v_mov_b64_e32 v[50:51], 0
	v_mov_b64_e32 v[56:57], 0
	v_mov_b64_e32 v[58:59], 0
	v_mov_b64_e32 v[60:61], 0
	v_mov_b64_e32 v[62:63], 0
	v_mov_b64_e32 v[64:65], 0
	v_mov_b64_e32 v[66:67], 0
	v_mov_b64_e32 v[68:69], 0
	v_mov_b64_e32 v[70:71], 0
	v_mov_b64_e32 v[76:77], 0
	v_mov_b64_e32 v[78:79], 0
	v_mov_b64_e32 v[84:85], 0
	v_mov_b64_e32 v[86:87], 0
	v_mov_b64_e32 v[92:93], 0
	v_mov_b64_e32 v[94:95], 0
	v_mov_b64_e32 v[100:101], 0
	v_mov_b64_e32 v[102:103], 0
	v_mov_b64_e32 v[108:109], 0
	v_mov_b64_e32 v[110:111], 0
	v_mov_b64_e32 v[116:117], 0
	v_mov_b64_e32 v[118:119], 0
	v_mov_b64_e32 v[72:73], 0
	v_mov_b64_e32 v[74:75], 0
	v_mov_b64_e32 v[80:81], 0
	v_mov_b64_e32 v[82:83], 0
	v_mov_b64_e32 v[88:89], 0
	v_mov_b64_e32 v[90:91], 0
	v_mov_b64_e32 v[96:97], 0
	v_mov_b64_e32 v[98:99], 0
	v_mov_b64_e32 v[104:105], 0
	v_mov_b64_e32 v[106:107], 0
	v_mov_b64_e32 v[112:113], 0
	v_mov_b64_e32 v[114:115], 0
	v_mov_b64_e32 v[120:121], 0
	v_mov_b64_e32 v[122:123], 0
	v_mov_b64_e32 v[124:125], 0
	v_mov_b64_e32 v[126:127], 0

; DI void chunk_decode(int g, int& seq, int& c) { if (g < NCP) { seq = 0; c = g; } else { seq = 1 + (g - NCP) / NCS; c = (g - NCP) % NCS; } }
; DI void chunk_range(int c, int& t0, int& t1) { if (c == 0) { t0 = 0; t1 = 16; } else { t0 = 16 + 128 * (c - 1); t1 = t0 + 128; } }
; template <int DIR> DI void scan_item(const Params& p, int l, LAS float* L, LAS float* CL, int item, int lane) {
;     ...
;     const int g = item >> 3, hd = (item >> 1) & 3;
;     int seq, c; chunk_decode(g, seq, c); int t0, t1; chunk_range(c, t0, t1);
;     const int base = seq_start(seq), nsub = (t1 - t0) >> 3, ch = hd * 64 + lane;
;     const int la = lane >> 2, lb = lane & 3;
;     CL[lane] = p.in[16][(size_t)l * 256 + ch]; CL[64 + lane] = p.in[17][(size_t)l * 256 + ch];
;     f32x2 SU[4][8], SP[4][8];
; #pragma unroll
;     for (int ri = 0; ri < 4; ++ri)
; #pragma unroll
;         for (int cp = 0; cp < 8; ++cp) { SU[ri][cp] = (f32x2){0.f, 0.f}; SP[ri][cp] = (f32x2){(4 * la + ri == 16 * lb + 2 * cp) ? 1.f : 0.f, (4 * la + ri == 16 * lb + 2 * cp + 1) ? 1.f : 0.f}; }
;     const int ss = lane >> 3, cg = lane & 7;
.LBB0_2543:
	v_bfe_u32 v13, v64, 1, 2
	v_ashrrev_i32_e32 v1, 3, v64
	v_lshl_or_b32 v68, v13, 7, v188
	v_cmp_lt_i32_e64 s[18:19], s41, v1
	s_and_saveexec_b64 s[72:73], s[16:17]
	s_xor_b64 s[72:73], exec, s[72:73]
	s_cbranch_execz .LBB0_2553
	v_mov_b32_e32 v94, 0
	v_mov_b32_e32 v15, 0
	s_and_saveexec_b64 s[74:75], s[18:19]
	v_lshrrev_b32_e32 v0, 3, v64
	v_add_u16_e32 v0, 0xff7f, v0
	v_mul_u32_u24_e32 v1, 0xf0f1, v0
	v_lshrrev_b32_e32 v1, 20, v1
	v_add_u16_e32 v15, 1, v1
	v_mul_lo_u16_e32 v1, 17, v1
	v_sub_u16_e32 v1, v0, v1
	s_or_b64 exec, exec, s[74:75]
	v_lshlrev_b32_e32 v23, 6, v13
	v_or_b32_e32 v0, v23, v93
	v_lshlrev_b32_e32 v0, 2, v0
	global_load_dword v29, v0, s[28:29] offset:1024
	global_load_dword v31, v0, s[30:31] offset:1024
	v_lshlrev_b32_e32 v21, 7, v1
	v_add_u32_e32 v36, 0xffffff90, v21
	v_cmp_ne_u32_e32 vcc, 0, v1
	v_or_b32_e32 v3, 16, v21
	v_mov_b32_e32 v95, v91
	v_cndmask_b32_e32 v1, 0, v36, vcc
	v_sub_u32_e32 v1, v3, v1
	v_ashrrev_i32_e32 v65, 3, v1
	v_mov_b32_e32 v97, v89
	v_mov_b32_e32 v96, 0
	v_mov_b32_e32 v99, v87
	v_mov_b32_e32 v98, 0
	v_mov_b32_e32 v101, v85
	v_mov_b32_e32 v100, 0
	v_mov_b32_e32 v103, 0
	v_mov_b32_e32 v102, v74
	v_mov_b32_e32 v105, 0
	v_mov_b32_e32 v104, v72
	v_mov_b32_e32 v107, 0
	v_mov_b32_e32 v106, v70
	v_mov_b32_e32 v109, 0
	v_mov_b32_e32 v108, v66
	v_mov_b32_e32 v111, v74
	v_mov_b32_e32 v110, 0
	v_mov_b32_e32 v113, v72
	v_mov_b32_e32 v112, 0
	v_mov_b32_e32 v115, v70
	v_mov_b32_e32 v114, 0
	v_mov_b32_e32 v117, v66
	v_mov_b32_e32 v116, 0
	v_mov_b32_e32 v119, 0
	v_mov_b32_e32 v118, v74
	v_mov_b32_e32 v121, 0
	v_mov_b32_e32 v120, v72
	v_mov_b32_e32 v123, 0
	v_mov_b32_e32 v122, v70
	v_mov_b32_e32 v125, 0
	v_mov_b32_e32 v124, v66
	v_mov_b32_e32 v2, 0
	v_mov_b32_e32 v0, 0
	v_mov_b64_e32 v[6:7], 0
	v_mov_b64_e32 v[4:5], 0
	v_mov_b32_e32 v14, 0
	v_mov_b32_e32 v12, 0
	v_mov_b64_e32 v[10:11], 0
	v_mov_b64_e32 v[8:9], 0
	v_mov_b32_e32 v22, 0
	v_mov_b32_e32 v20, 0
	v_mov_b64_e32 v[18:19], 0
	v_mov_b64_e32 v[16:17], 0
	v_mov_b32_e32 v30, 0
	v_mov_b32_e32 v28, 0
	v_mov_b64_e32 v[26:27], 0
	v_mov_b64_e32 v[24:25], 0
	v_mov_b32_e32 v39, 0
	v_mov_b32_e32 v37, 0
	v_mov_b64_e32 v[34:35], 0
	v_mov_b64_e32 v[32:33], 0
	v_mov_b32_e32 v47, 0
	v_mov_b32_e32 v45, 0
	v_mov_b64_e32 v[42:43], 0
	v_mov_b64_e32 v[40:41], 0
	v_mov_b32_e32 v55, 0
	v_mov_b32_e32 v53, 0
	v_mov_b32_e32 v51, 0
	v_cmp_lt_i32_e32 vcc, 0, v65
	v_mov_b32_e32 v50, 0
	v_mov_b32_e32 v49, 0
	v_mov_b32_e32 v48, 0
	v_mov_b32_e32 v63, 0
	v_mov_b32_e32 v61, 0
	v_mov_b32_e32 v59, 0
	v_mov_b32_e32 v58, 0
	v_mov_b32_e32 v57, 0
	v_mov_b32_e32 v56, 0
	s_waitcnt vmcnt(0)
	ds_write2st64_b32 v179, v29, v31 offset1:1
	s_and_saveexec_b64 s[74:75], vcc
	s_cbranch_execz .LBB0_2552
	v_mad_u32_u24 v0, v15, s78, v189
	v_cmp_ne_u32_e32 vcc, 0, v15
	v_lshlrev_b32_e32 v4, 2, v13
	v_mov_b32_e32 v5, v69
	v_mov_b32_e32 v12, v69
	v_mov_b32_e32 v13, v69
	s_mov_b32 s84, 0
	v_cndmask_b32_e32 v0, 0, v0, vcc
	v_mov_b32_e32 v1, v69
	v_or_b32_e32 v2, v23, v183
	v_lshl_add_u64 v[4:5], s[54:55], 0, v[4:5]
	v_add_u32_e32 v6, 15, v21
	s_mov_b64 s[76:77], 0
	v_mov_b64_e32 v[14:15], v[12:13]
	v_mov_b64_e32 v[18:19], v[12:13]
	v_mov_b64_e32 v[16:17], v[12:13]
	v_mov_b64_e32 v[20:21], v[12:13]
	v_mov_b64_e32 v[22:23], v[12:13]
	v_mov_b64_e32 v[26:27], v[12:13]
	v_mov_b64_e32 v[24:25], v[12:13]
	v_mov_b64_e32 v[28:29], v[12:13]
	v_mov_b64_e32 v[30:31], v[12:13]
	v_mov_b64_e32 v[34:35], v[12:13]
	v_mov_b64_e32 v[32:33], v[12:13]
	v_mov_b64_e32 v[36:37], v[12:13]
	v_mov_b64_e32 v[38:39], v[12:13]
	v_mov_b64_e32 v[42:43], v[12:13]
	v_mov_b64_e32 v[40:41], v[12:13]
	v_mov_b64_e32 v[44:45], v[12:13]
	v_mov_b64_e32 v[46:47], v[12:13]
	v_mov_b64_e32 v[50:51], v[12:13]
	v_mov_b64_e32 v[48:49], v[12:13]
	v_mov_b64_e32 v[52:53], v[12:13]
	v_mov_b64_e32 v[54:55], v[12:13]
	v_mov_b64_e32 v[58:59], v[12:13]
	v_mov_b64_e32 v[56:57], v[12:13]
	v_mov_b64_e32 v[94:95], v[90:91]
	v_mov_b64_e32 v[126:127], v[12:13]
	v_mov_b64_e32 v[96:97], v[88:89]
	v_mov_b64_e32 v[128:129], v[12:13]
	v_mov_b64_e32 v[98:99], v[86:87]
	v_mov_b64_e32 v[130:131], v[12:13]
	v_mov_b64_e32 v[100:101], v[84:85]
	v_mov_b64_e32 v[132:133], v[12:13]
	v_mov_b64_e32 v[102:103], v[74:75]
	v_mov_b64_e32 v[134:135], v[12:13]
	v_mov_b64_e32 v[104:105], v[72:73]
	v_mov_b64_e32 v[136:137], v[12:13]
	v_mov_b64_e32 v[106:107], v[70:71]
	v_mov_b64_e32 v[138:139], v[12:13]
	v_mov_b64_e32 v[108:109], v[66:67]
	v_mov_b64_e32 v[140:141], v[12:13]
	v_mov_b64_e32 v[142:143], v[12:13]
	v_mov_b64_e32 v[110:111], v[82:83]
	v_mov_b64_e32 v[152:153], v[12:13]
	v_mov_b64_e32 v[112:113], v[80:81]
	v_mov_b64_e32 v[162:163], v[12:13]
	v_mov_b64_e32 v[114:115], v[78:79]
	v_mov_b64_e32 v[164:165], v[12:13]
	v_mov_b64_e32 v[116:117], v[76:77]
	v_mov_b64_e32 v[166:167], v[12:13]
	v_mov_b64_e32 v[118:119], v[74:75]
	v_mov_b64_e32 v[168:169], v[12:13]
	v_mov_b64_e32 v[120:121], v[72:73]
	v_mov_b64_e32 v[62:63], v[12:13]
	v_mov_b64_e32 v[122:123], v[70:71]
	v_mov_b64_e32 v[60:61], v[12:13]
	v_mov_b64_e32 v[124:125], v[66:67]
	v_mov_b64_e32 v[154:155], v[12:13]
	v_mov_b64_e32 v[156:157], v[12:13]
	v_mov_b64_e32 v[158:159], v[12:13]
	v_mov_b64_e32 v[160:161], v[12:13]
	v_mov_b64_e32 v[144:145], v[12:13]
	v_mov_b64_e32 v[146:147], v[12:13]
	v_mov_b64_e32 v[148:149], v[12:13]
	v_mov_b64_e32 v[150:151], v[12:13]

; DI void chunk_decode(int g, int& seq, int& c) { if (g < NCP) { seq = 0; c = g; } else { seq = 1 + (g - NCP) / NCS; c = (g - NCP) % NCS; } }
; DI void chunk_range(int c, int& t0, int& t1) { if (c == 0) { t0 = 0; t1 = 16; } else { t0 = 16 + 128 * (c - 1); t1 = t0 + 128; } }
; template <int DIR> DI void scan_item(const Params& p, int l, LAS float* L, LAS float* CL, int item, int lane) {
;     ...
;     const int g = item >> 3, hd = (item >> 1) & 3;
;     int seq, c; chunk_decode(g, seq, c); int t0, t1; chunk_range(c, t0, t1);
;     const int base = seq_start(seq), nsub = (t1 - t0) >> 3, ch = hd * 64 + lane;
;     const int la = lane >> 2, lb = lane & 3;
;     CL[lane] = p.in[16][(size_t)l * 256 + ch]; CL[64 + lane] = p.in[17][(size_t)l * 256 + ch];
;     f32x2 SU[4][8], SP[4][8];
; #pragma unroll
;     for (int ri = 0; ri < 4; ++ri)
; #pragma unroll
;         for (int cp = 0; cp < 8; ++cp) { SU[ri][cp] = (f32x2){0.f, 0.f}; SP[ri][cp] = (f32x2){(4 * la + ri == 16 * lb + 2 * cp) ? 1.f : 0.f, (4 * la + ri == 16 * lb + 2 * cp + 1) ? 1.f : 0.f}; }
;     const int ss = lane >> 3, cg = lane & 7;
.LBB0_2553:
	s_andn2_saveexec_b64 s[72:73], s[72:73]
	s_cbranch_execz .LBB0_2542
	v_mov_b32_e32 v94, 0
	v_mov_b32_e32 v15, 0
	s_and_saveexec_b64 s[74:75], s[18:19]
	v_lshrrev_b32_e32 v0, 3, v64
	v_add_u16_e32 v0, 0xff7f, v0
	v_mul_u32_u24_e32 v1, 0xf0f1, v0
	v_lshrrev_b32_e32 v1, 20, v1
	v_add_u16_e32 v15, 1, v1
	v_mul_lo_u16_e32 v1, 17, v1
	v_sub_u16_e32 v1, v0, v1
	s_or_b64 exec, exec, s[74:75]
	v_lshlrev_b32_e32 v21, 6, v13
	v_or_b32_e32 v0, v21, v93
	v_lshlrev_b32_e32 v0, 2, v0
	global_load_dword v23, v0, s[28:29] offset:1024
	global_load_dword v29, v0, s[30:31] offset:1024
	v_lshlrev_b32_e32 v3, 7, v1
	v_add_u32_e32 v31, 0xffffff90, v3
	v_cmp_ne_u32_e32 vcc, 0, v1
	v_or_b32_e32 v36, 16, v3
	v_mov_b32_e32 v95, v91
	v_cndmask_b32_e32 v3, 0, v31, vcc
	v_sub_u32_e32 v1, v36, v3
	v_ashrrev_i32_e32 v65, 3, v1
	v_mov_b32_e32 v97, v89
	v_mov_b32_e32 v96, 0
	v_mov_b32_e32 v99, v87
	v_mov_b32_e32 v98, 0
	v_mov_b32_e32 v101, v85
	v_mov_b32_e32 v100, 0
	v_mov_b32_e32 v103, 0
	v_mov_b32_e32 v102, v74
	v_mov_b32_e32 v105, 0
	v_mov_b32_e32 v104, v72
	v_mov_b32_e32 v107, 0
	v_mov_b32_e32 v106, v70
	v_mov_b32_e32 v109, 0
	v_mov_b32_e32 v108, v66
	v_mov_b32_e32 v111, v74
	v_mov_b32_e32 v110, 0
	v_mov_b32_e32 v113, v72
	v_mov_b32_e32 v112, 0
	v_mov_b32_e32 v115, v70
	v_mov_b32_e32 v114, 0
	v_mov_b32_e32 v117, v66
	v_mov_b32_e32 v116, 0
	v_mov_b32_e32 v119, 0
	v_mov_b32_e32 v118, v74
	v_mov_b32_e32 v121, 0
	v_mov_b32_e32 v120, v72
	v_mov_b32_e32 v123, 0
	v_mov_b32_e32 v122, v70
	v_mov_b32_e32 v125, 0
	v_mov_b32_e32 v124, v66
	v_mov_b32_e32 v2, 0
	v_mov_b32_e32 v0, 0
	v_mov_b64_e32 v[6:7], 0
	v_mov_b64_e32 v[4:5], 0
	v_mov_b32_e32 v14, 0
	v_mov_b32_e32 v12, 0
	v_mov_b64_e32 v[10:11], 0
	v_mov_b64_e32 v[8:9], 0
	v_mov_b32_e32 v22, 0
	v_mov_b32_e32 v20, 0
	v_mov_b64_e32 v[18:19], 0
	v_mov_b64_e32 v[16:17], 0
	v_mov_b32_e32 v30, 0
	v_mov_b32_e32 v28, 0
	v_mov_b64_e32 v[26:27], 0
	v_mov_b64_e32 v[24:25], 0
	v_mov_b32_e32 v39, 0
	v_mov_b32_e32 v37, 0
	v_mov_b64_e32 v[34:35], 0
	v_mov_b64_e32 v[32:33], 0
	v_mov_b32_e32 v47, 0
	v_mov_b32_e32 v45, 0
	v_mov_b64_e32 v[42:43], 0
	v_mov_b64_e32 v[40:41], 0
	v_mov_b32_e32 v55, 0
	v_mov_b32_e32 v53, 0
	v_mov_b32_e32 v51, 0
	v_cmp_lt_i32_e32 vcc, 0, v65
	v_mov_b32_e32 v50, 0
	v_mov_b32_e32 v49, 0
	v_mov_b32_e32 v48, 0
	v_mov_b32_e32 v63, 0
	v_mov_b32_e32 v61, 0
	v_mov_b32_e32 v59, 0
	v_mov_b32_e32 v58, 0
	v_mov_b32_e32 v57, 0
	v_mov_b32_e32 v56, 0
	s_waitcnt vmcnt(0)
	ds_write2st64_b32 v179, v23, v29 offset1:1
	s_and_saveexec_b64 s[18:19], vcc
	s_cbranch_execz .LBB0_2541
	v_mad_u32_u24 v0, v15, s78, v189
	v_cmp_ne_u32_e32 vcc, 0, v15
	v_lshlrev_b32_e32 v4, 2, v13
	v_mov_b32_e32 v5, v69
	v_lshl_add_u64 v[6:7], s[26:27], 0, v[68:69]
	v_lshl_add_u64 v[8:9], s[24:25], 0, v[68:69]
	v_mov_b32_e32 v68, v69
	s_mov_b32 s84, 0
	v_cndmask_b32_e32 v0, 0, v0, vcc
	v_mov_b32_e32 v1, v69
	v_or_b32_e32 v2, v21, v183
	v_lshl_add_u64 v[4:5], s[54:55], 0, v[4:5]
	s_mov_b64 s[74:75], 0
	v_mov_b32_e32 v10, v3
	v_mov_b64_e32 v[20:21], v[68:69]
	v_mov_b64_e32 v[18:19], v[68:69]
	v_mov_b64_e32 v[22:23], v[68:69]
	v_mov_b64_e32 v[16:17], v[68:69]
	v_mov_b64_e32 v[28:29], v[68:69]
	v_mov_b64_e32 v[26:27], v[68:69]
	v_mov_b64_e32 v[30:31], v[68:69]
	v_mov_b64_e32 v[24:25], v[68:69]
	v_mov_b64_e32 v[36:37], v[68:69]
	v_mov_b64_e32 v[34:35], v[68:69]
	v_mov_b64_e32 v[38:39], v[68:69]
	v_mov_b64_e32 v[32:33], v[68:69]
	v_mov_b64_e32 v[44:45], v[68:69]
	v_mov_b64_e32 v[42:43], v[68:69]
	v_mov_b64_e32 v[46:47], v[68:69]
	v_mov_b64_e32 v[40:41], v[68:69]
	v_mov_b64_e32 v[52:53], v[68:69]
	v_mov_b64_e32 v[50:51], v[68:69]
	v_mov_b64_e32 v[54:55], v[68:69]
	v_mov_b64_e32 v[48:49], v[68:69]
	v_mov_b64_e32 v[60:61], v[68:69]
	v_mov_b64_e32 v[58:59], v[68:69]
	v_mov_b64_e32 v[62:63], v[68:69]
	v_mov_b64_e32 v[56:57], v[68:69]
	v_mov_b64_e32 v[94:95], v[90:91]
	v_mov_b64_e32 v[126:127], v[68:69]
	v_mov_b64_e32 v[96:97], v[88:89]
	v_mov_b64_e32 v[128:129], v[68:69]
	v_mov_b64_e32 v[98:99], v[86:87]
	v_mov_b64_e32 v[130:131], v[68:69]
	v_mov_b64_e32 v[100:101], v[84:85]
	v_mov_b64_e32 v[132:133], v[68:69]
	v_mov_b64_e32 v[102:103], v[74:75]
	v_mov_b64_e32 v[134:135], v[68:69]
	v_mov_b64_e32 v[104:105], v[72:73]
	v_mov_b64_e32 v[136:137], v[68:69]
	v_mov_b64_e32 v[106:107], v[70:71]
	v_mov_b64_e32 v[138:139], v[68:69]
	v_mov_b64_e32 v[108:109], v[66:67]
	v_mov_b64_e32 v[140:141], v[68:69]
	v_mov_b64_e32 v[142:143], v[68:69]
	v_mov_b64_e32 v[110:111], v[82:83]
	v_mov_b64_e32 v[152:153], v[68:69]
	v_mov_b64_e32 v[112:113], v[80:81]
	v_mov_b64_e32 v[162:163], v[68:69]
	v_mov_b64_e32 v[114:115], v[78:79]
	v_mov_b64_e32 v[164:165], v[68:69]
	v_mov_b64_e32 v[116:117], v[76:77]
	v_mov_b64_e32 v[166:167], v[68:69]
	v_mov_b64_e32 v[118:119], v[74:75]
	v_mov_b64_e32 v[168:169], v[68:69]
	v_mov_b64_e32 v[120:121], v[72:73]
	v_mov_b64_e32 v[170:171], v[68:69]
	v_mov_b64_e32 v[122:123], v[70:71]
	v_mov_b64_e32 v[172:173], v[68:69]
	v_mov_b64_e32 v[124:125], v[66:67]
	v_mov_b64_e32 v[154:155], v[68:69]
	v_mov_b64_e32 v[156:157], v[68:69]
	v_mov_b64_e32 v[158:159], v[68:69]
	v_mov_b64_e32 v[160:161], v[68:69]
	v_mov_b64_e32 v[144:145], v[68:69]
	v_mov_b64_e32 v[146:147], v[68:69]
	v_mov_b64_e32 v[148:149], v[68:69]
	v_mov_b64_e32 v[150:151], v[68:69]

; #define LAS __attribute__((address_space(3)))
; #define ATT_GLOAD(k0_, k1_, v_, tile) do { const size_t rb = (size_t)base + (size_t)(tile) * 64; \
;         k0_ = *(const u32x4*)(K + (rb + kkey0) * ldk + koff + kpart0 * 8); \
;         if (kc1 < NKC) k1_ = *(const u32x4*)(K + (rb + kkey1) * ldk + koff + kpart1 * 8); \
;         v_ = *(const u32x4*)(Vt + (size_t)vd * MPAD + rb + vpart * 8); } while (0)
; DI void attn_lut(LAS float* LUT, int tid, const float* relb, int qhead) {
;     if (tid < 259) { const int rel = tid - 129, n = rel < 0 ? -rel : rel; int b;
;         if (n < 8) b = n; else { int m = (31 - __builtin_clz((unsigned)(n * n))) - 6; b = 8 + m; if (b > 15) b = 15; }
;         if (rel > 0) b += 16;
;         LUT[tid] = relb[b * 8 + qhead] * LOG2E; }
; }
; template <int DQK, bool SWA>
; DI void attn_block(int wv, LAS unsigned char* lds, const bf16_t* Q, int ldq, int qoff, const bf16_t* K, int ldk, int koff, const bf16_t* Vt,
;                    int base, int T, int q0, bf16_t* O, int ldo, int ooff, const float* relb, int qhead, float sink_add) {
;     ...
;     const int tid = tid_(wv), lane = tid & 63, w = tid >> 6, r = lane & 31, h = lane >> 5;
;     LAS float* LUT = (LAS float*)(lds + ATT_LUT);
;     __syncthreads();
;     if (SWA) attn_lut(LUT, tid, relb, qhead);
;     const int qw0 = q0 + 32 * w, qpos = qw0 + r; const size_t qrow = (size_t)base + qpos;
;     bf16x8 qf[NKS];
; #pragma unroll
;     for (int ks = 0; ks < NKS; ++ks) qf[ks] = *(const bf16x8*)(Q + qrow * ldq + qoff + 16 * ks + 8 * h);
;     f32x16 o0, o1;
; #pragma unroll
;     for (int i = 0; i < 16; ++i) { o0[i] = 0.f; o1[i] = 0.f; }
;     float lsum = 0.f;
;     const int nt = (T + 63) >> 6;
;     int lo = 0, ntl = nt;
;     if (SWA) { lo = (q0 - 128) >> 6; if (lo < 1) lo = 1; int hi = (q0 + 255 + 128) >> 6; if (hi > nt - 1) hi = nt - 1; ntl = 1 + (hi >= lo ? hi - lo + 1 : 0); }
;     u32x4 kA0, kA1, vA, kB0, kB1, vB;
;     kA1 = (u32x4){0u, 0u, 0u, 0u}; kB1 = kA1;
;     const int kc0 = tid, kc1 = tid + 512;
;     const int kkey0 = kc0 / CPR, kpart0 = kc0 % CPR, kkey1 = kc1 / CPR, kpart1 = kc1 % CPR;
;     const int vd = tid >> 3, vpart = tid & 7;
;     ...
;     ATT_GLOAD(kA0, kA1, vA, ATT_TILE(0)); ATT_LWRITE(kA0, kA1, vA, 0);
;     if (ntl > 1) ATT_GLOAD(kB0, kB1, vB, ATT_TILE(1));
;     if (ntl > 2) ATT_GLOAD(kA0, kA1, vA, ATT_TILE(2));
;     __syncthreads();
.Lswab_dec:
	s_lshr_b32 s15, s33, 6
	s_lshl_b32 s4, s10, 2
	s_sub_u32 s5, s4, 2
	s_cmp_eq_u32 s10, 0
	s_cselect_b32 s12, 1, s5
	s_add_u32 s5, s4, 5
	s_sub_u32 s6, s13, 1
	s_min_u32 s5, s5, s6
	s_sub_u32 s5, s5, s12
	s_add_u32 s29, s5, 1
	s_lshl_b32 s49, s10, 8
	s_lshl_b32 s4, s15, 5
	s_add_u32 s49, s49, s4
	s_movk_i32 s50, 0xff7f
	s_movk_i32 s51, 0xff80
	s_waitcnt lgkmcnt(0)
	s_lshl_b32 s4, s8, 2
	s_add_u32 s4, s4, 32
	s_load_dword s46, s[44:45], s4
	v_add_u32_e32 v21, s33, v254
	v_add_u32_e32 v25, 0xffffff40, v21
	v_sub_u32_e32 v23, 0, v25
	v_max_i32_e32 v23, v25, v23
	v_mul_u32_u24_e32 v24, v23, v23
	v_ffbh_u32_e32 v24, v24
	v_sub_u32_e32 v24, 33, v24
	v_min_u32_e32 v24, 15, v24
	v_cmp_gt_u32_e32 vcc, 8, v23
	s_nop 1
	v_cndmask_b32_e32 v24, v24, v23, vcc
	v_cmp_lt_i32_e32 vcc, 0, v25
	s_nop 1
	v_cndmask_b32_e64 v23, 0, 16, vcc
	v_add_u32_e32 v24, v24, v23
	v_lshl_add_u32 v24, v24, 3, s8
	v_lshlrev_b32_e32 v24, 2, v24
	v_min_u32_e32 v24, 0x3fc, v24
	global_load_dword v24, v24, s[42:43]
	s_lshl_b32 s4, s8, 7
	s_add_u32 s16, s40, s4
	s_addc_u32 s17, s41, 0
	s_add_u32 s4, s4, 0x200
	s_add_u32 s22, s34, 0x19548000
	s_addc_u32 s23, s35, 0
	s_add_u32 s22, s22, s4
	s_addc_u32 s23, s23, 0
	s_lshr_b32 s5, s8, 2
	s_lshl_b32 s4, s5, 7
	s_lshl_b32 s6, s11, 8
	s_add_u32 s18, s40, 0x50c0000
	s_addc_u32 s19, s41, 0
	s_add_u32 s18, s18, s4
	s_addc_u32 s19, s19, 0
	s_add_u32 s18, s18, s6
	s_addc_u32 s19, s19, 0
	s_mul_i32 s4, s5, 0xa18000
	s_lshl_b32 s6, s11, 1
	s_add_u32 s20, s34, 0x300a8000
	s_addc_u32 s21, s35, 0
	s_add_u32 s20, s20, s4
	s_addc_u32 s21, s21, 0
	s_add_u32 s20, s20, s6
	s_addc_u32 s21, s21, 0
	v_and_b32_e32 v0, 31, v254
	v_lshrrev_b32_e32 v197, 5, v254
	v_mul_u32_u24_e32 v194, 0x90, v0
	v_add_u32_e32 v195, 0x2400, v194
	v_lshl_add_u32 v194, v197, 4, v194
	v_lshl_add_u32 v195, v197, 3, v195
	v_add_u32_e32 v196, 0x1200, v195
	v_add_u32_e32 v198, s49, v0
	v_lshlrev_b32_e32 v20, 2, v197
	v_sub_u32_e32 v20, v20, v198
	v_add_u32_e32 v198, s11, v198
	v_lshlrev_b32_e32 v199, 10, v198
	v_lshl_add_u32 v199, v197, 4, v199
	v_lshlrev_b32_e32 v198, 11, v198
	v_lshl_add_u32 v200, v197, 3, v198
	v_mov_b32_e32 v19, 0x81
	v_mov_b32_e32 v22, 0x80
	s_movk_i32 s48, 0x71c8
	s_mov_b32 s47, 0x28600
	s_movk_i32 s28, 0x80
	s_movk_i32 s27, 0x4000
	s_add_u32 s4, s15, 0
	s_cmpk_gt_u32 s4, 8
	s_cselect_b32 s7, s47, 0x100
	s_cselect_b32 s36, s28, s27
	s_mov_b32 s37, 0
	s_cselect_b32 s42, s20, s18
	s_cselect_b32 s43, s21, s19
	s_cselect_b32 s5, 9, 0
	s_cselect_b32 s6, 0x2400, 0
	s_sub_u32 s4, s4, s5
	s_cmpk_gt_u32 s4, 8
	s_cselect_b32 s5, 9, 0
	s_sub_u32 s4, s4, s5
	s_lshl_b32 s5, s4, 10
	s_add_u32 s24, s5, s6
	s_lshl_b32 s4, s4, 6
	v_add_u32_e32 v197, s4, v254
	v_mul_lo_u32 v198, v197, s48
	v_lshrrev_b32_e32 v198, 18, v198
	v_mul_u32_u24_e32 v186, 9, v198
	v_sub_u32_e32 v197, v197, v186
	v_cmp_ne_u32_e32 vcc, 8, v197
	s_nop 1
	v_cndmask_b32_e32 v197, 0, v197, vcc
	v_mul_lo_u32 v198, v198, s7
	v_lshl_add_u32 v186, v197, 4, v198
	v_mov_b32_e32 v187, 0
	v_lshl_add_u64 v[186:187], s[42:43], 0, v[186:187]
	s_add_u32 s4, s15, 8
	s_cmpk_gt_u32 s4, 8
	s_cselect_b32 s7, s47, 0x100
	s_cselect_b32 s38, s28, s27
	s_mov_b32 s39, 0
	s_cselect_b32 s42, s20, s18
	s_cselect_b32 s43, s21, s19
	s_cselect_b32 s5, 9, 0
	s_cselect_b32 s6, 0x2400, 0
	s_sub_u32 s4, s4, s5
	s_cmpk_gt_u32 s4, 8
	s_cselect_b32 s5, 9, 0
	s_sub_u32 s4, s4, s5
	s_lshl_b32 s5, s4, 10
	s_add_u32 s25, s5, s6
	s_lshl_b32 s4, s4, 6
	v_add_u32_e32 v197, s4, v254
	v_mul_lo_u32 v198, v197, s48
	v_lshrrev_b32_e32 v198, 18, v198
	v_mul_u32_u24_e32 v188, 9, v198
	v_sub_u32_e32 v197, v197, v188
	v_cmp_ne_u32_e32 vcc, 8, v197
	s_nop 1
	v_cndmask_b32_e32 v197, 0, v197, vcc
	v_mul_lo_u32 v198, v198, s7
	v_lshl_add_u32 v188, v197, 4, v198
	v_mov_b32_e32 v189, 0
	v_lshl_add_u64 v[188:189], s[42:43], 0, v[188:189]
	s_add_u32 s4, s15, 16
	s_cmpk_gt_u32 s4, 8
	s_cselect_b32 s7, s47, 0x100
	s_cselect_b32 s40, s28, s27
	s_mov_b32 s41, 0
	s_cselect_b32 s42, s20, s18
	s_cselect_b32 s43, s21, s19
	s_cselect_b32 s5, 9, 0
	s_cselect_b32 s6, 0x2400, 0
	s_sub_u32 s4, s4, s5
	s_cmpk_gt_u32 s4, 8
	s_cselect_b32 s5, 9, 0
	s_sub_u32 s4, s4, s5
	s_lshl_b32 s5, s4, 10
	s_add_u32 s26, s5, s6
	s_lshl_b32 s4, s4, 6
	v_add_u32_e32 v197, s4, v254
	v_mul_lo_u32 v198, v197, s48
	v_lshrrev_b32_e32 v198, 18, v198
	v_mul_u32_u24_e32 v190, 9, v198
	v_sub_u32_e32 v197, v197, v190
	v_cmp_ne_u32_e32 vcc, 8, v197
	s_nop 1
	v_cndmask_b32_e32 v197, 0, v197, vcc
	v_mul_lo_u32 v198, v198, s7
	v_lshl_add_u32 v190, v197, 4, v198
	v_mov_b32_e32 v191, 0
	v_lshl_add_u64 v[190:191], s[42:43], 0, v[190:191]
	global_load_dwordx4 v[2:5], v199, s[16:17] offset:0
	global_load_dwordx4 v[6:9], v199, s[16:17] offset:32
	global_load_dwordx4 v[10:13], v199, s[16:17] offset:64
	global_load_dwordx4 v[14:17], v199, s[16:17] offset:96
	s_mov_b32 s28, 0x0
	s_add_u32 m0, s28, s24
	s_nop 0
	global_load_lds_dwordx4 v[186:187], off
	s_mul_i32 s4, s36, s12
	s_mov_b32 s5, 0
	v_lshl_add_u64 v[186:187], v[186:187], 0, s[4:5]
	s_add_u32 m0, s28, s25
	s_nop 0
	global_load_lds_dwordx4 v[188:189], off
	s_mul_i32 s4, s38, s12
	s_mov_b32 s5, 0
	v_lshl_add_u64 v[188:189], v[188:189], 0, s[4:5]
	s_add_u32 m0, s28, s26
	s_nop 0
	global_load_lds_dwordx4 v[190:191], off
	s_mul_i32 s4, s40, s12
	s_mov_b32 s5, 0
	v_lshl_add_u64 v[190:191], v[190:191], 0, s[4:5]
	s_mov_b32 s28, 0x4800
	s_add_u32 m0, s28, s24
	s_nop 0
	global_load_lds_dwordx4 v[186:187], off
	v_lshl_add_u64 v[186:187], v[186:187], 0, s[36:37]
	s_add_u32 m0, s28, s25
	s_nop 0
	global_load_lds_dwordx4 v[188:189], off
	v_lshl_add_u64 v[188:189], v[188:189], 0, s[38:39]
	s_add_u32 m0, s28, s26
	s_nop 0
	global_load_lds_dwordx4 v[190:191], off
	v_lshl_add_u64 v[190:191], v[190:191], 0, s[40:41]
	s_mov_b32 s28, 0xf000
	s_add_u32 m0, s28, s24
	s_nop 0
	global_load_lds_dwordx4 v[186:187], off
	v_lshl_add_u64 v[186:187], v[186:187], 0, s[36:37]
	s_add_u32 m0, s28, s25
	s_nop 0
	global_load_lds_dwordx4 v[188:189], off
	v_lshl_add_u64 v[188:189], v[188:189], 0, s[38:39]
	s_add_u32 m0, s28, s26
	s_nop 0
	global_load_lds_dwordx4 v[190:191], off
	v_lshl_add_u64 v[190:191], v[190:191], 0, s[40:41]
	s_mov_b32 s28, 0x13800
	s_add_u32 m0, s28, s24
	s_nop 0
	global_load_lds_dwordx4 v[186:187], off
	v_lshl_add_u64 v[186:187], v[186:187], 0, s[36:37]
	s_add_u32 m0, s28, s25
	s_nop 0
	global_load_lds_dwordx4 v[188:189], off
	v_lshl_add_u64 v[188:189], v[188:189], 0, s[38:39]
	s_add_u32 m0, s28, s26
	s_nop 0
	global_load_lds_dwordx4 v[190:191], off
	v_lshl_add_u64 v[190:191], v[190:191], 0, s[40:41]
	v_mov_b64_e32 v[26:27], 0
	v_mov_b64_e32 v[28:29], 0
	v_mov_b64_e32 v[30:31], 0
	v_mov_b64_e32 v[32:33], 0
	v_mov_b64_e32 v[34:35], 0
	v_mov_b64_e32 v[36:37], 0
	v_mov_b64_e32 v[38:39], 0
	v_mov_b64_e32 v[40:41], 0
	v_mov_b64_e32 v[42:43], 0
	v_mov_b64_e32 v[44:45], 0
	v_mov_b64_e32 v[46:47], 0
	v_mov_b64_e32 v[48:49], 0
	v_mov_b64_e32 v[50:51], 0
	v_mov_b64_e32 v[52:53], 0
	v_mov_b64_e32 v[54:55], 0
	v_mov_b64_e32 v[56:57], 0
	v_mov_b64_e32 v[192:193], 0
	s_waitcnt vmcnt(16)
; #define LAS __attribute__((address_space(3)))
; #define ATT_GLOAD(k0_, k1_, v_, tile) do { const size_t rb = (size_t)base + (size_t)(tile) * 64; \
;         k0_ = *(const u32x4*)(K + (rb + kkey0) * ldk + koff + kpart0 * 8); \
;         if (kc1 < NKC) k1_ = *(const u32x4*)(K + (rb + kkey1) * ldk + koff + kpart1 * 8); \
;         v_ = *(const u32x4*)(Vt + (size_t)vd * MPAD + rb + vpart * 8); } while (0)
; #define ATT_LWRITE(k0_, k1_, v_, b) do { LAS unsigned char* kb = lds + (b) * ATT_BUF; \
;         *(LAS u32x4*)(kb + kkey0 * KP + kpart0 * 16) = k0_; \
;         if (kc1 < NKC) *(LAS u32x4*)(kb + kkey1 * KP + kpart1 * 16) = k1_; \
;         *(LAS u32x4*)(kb + KSZ + vd * 144 + vpart * 16) = v_; } while (0)
; DI void attn_lut(LAS float* LUT, int tid, const float* relb, int qhead) {
;     if (tid < 259) { const int rel = tid - 129, n = rel < 0 ? -rel : rel; int b;
;         if (n < 8) b = n; else { int m = (31 - __builtin_clz((unsigned)(n * n))) - 6; b = 8 + m; if (b > 15) b = 15; }
;         if (rel > 0) b += 16;
;         LUT[tid] = relb[b * 8 + qhead] * LOG2E; }
; }
; template <int DQK, bool SWA>
; DI void attn_block(int wv, LAS unsigned char* lds, const bf16_t* Q, int ldq, int qoff, const bf16_t* K, int ldk, int koff, const bf16_t* Vt,
;                    int base, int T, int q0, bf16_t* O, int ldo, int ooff, const float* relb, int qhead, float sink_add) {
;     ...
;     ATT_GLOAD(kA0, kA1, vA, ATT_TILE(0)); ATT_LWRITE(kA0, kA1, vA, 0);
;     if (ntl > 1) ATT_GLOAD(kB0, kB1, vB, ATT_TILE(1));
;     if (ntl > 2) ATT_GLOAD(kA0, kA1, vA, ATT_TILE(2));
;     __syncthreads();
	v_mul_f32_e32 v24, 0x3fb8aa3b, v24
	v_mov_b32_e32 v23, 0xf149f2ca
	v_add_u32_e32 v25, 0xffffff40, v21
	v_sub_u32_e32 v18, 0, v25
	v_max_i32_e32 v18, v25, v18
	v_cmp_lt_u32_e32 vcc, 0x80, v18
	s_nop 1
	v_cndmask_b32_e32 v24, v24, v23, vcc
	v_lshlrev_b32_e32 v25, 2, v21
	v_cmp_gt_u32_e32 vcc, 0x181, v21
	s_and_saveexec_b64 s[4:5], vcc
	ds_write_b32 v25, v24 offset:49152
	s_mov_b64 exec, s[4:5]
	s_mov_b32 s14, 0
	s_mov_b32 s30, 0x0
	s_mov_b32 s31, 0x18000
	s_waitcnt vmcnt(9) lgkmcnt(0)
	s_barrier
	s_cmpk_lt_u32 s15, 4
	s_cbranch_scc1 .Lswab_noskew
	s_barrier

; #define LAS __attribute__((address_space(3)))
; template <int DQK, bool SWA>
; DI void attn_tail(int wv, LAS unsigned char* lds, const bf16_t* Q, int ldq, int qoff, const bf16_t* K, int ldk, int koff, const bf16_t* Vt,
;                   int base, int T, int q0, bf16_t* O, int ldo, int ooff, const float* relb, int qhead, float sink_add) {
;     constexpr int NKS = DQK / 16;
;     const int tid = tid_(wv), lane = tid & 63, w = tid >> 6, r = lane & 31, h = lane >> 5;
;     LAS float* LUT = (LAS float*)(lds + ATT_LUT); LAS float* RED = (LAS float*)(lds + ATT_RED);
;     __syncthreads();
;     if (SWA) attn_lut(LUT, tid, relb, qhead);
;     for (int e = tid; e < 64 * 33; e += 512) RED[e] = 0.f;
;     const int qpos = q0 + r; const bool qvalid = qpos < T; const size_t qrow = (size_t)base + (qvalid ? qpos : T - 1);
;     bf16x8 qf[NKS];
; #pragma unroll
;     for (int ks = 0; ks < NKS; ++ks) qf[ks] = *(const bf16x8*)(Q + qrow * ldq + qoff + 16 * ks + 8 * h);
;     f32x16 o0, o1;
; #pragma unroll
;     for (int i = 0; i < 16; ++i) { o0[i] = 0.f; o1[i] = 0.f; }
;     float lsum = 0.f;
;     const int nt = (T + 63) >> 6;
;     int lo = 0, ntl = nt;
;     if (SWA) { lo = (q0 - 128) >> 6; if (lo < 1) lo = 1; int hi = nt - 1; ntl = 1 + (hi >= lo ? hi - lo + 1 : 0); }
;     __syncthreads();
.LBB0_2812:
	s_or_b64 exec, exec, s[4:5]
	s_waitcnt vmcnt(0)
	v_mul_f32_e32 v0, 0x3fb8aa3b, v0
	s_add_i32 s8, s90, 0x3800
	v_exp_f32_e32 v109, v0
	v_and_b32_e32 v0, 31, v107
	s_and_b64 s[4:5], s[60:61], exec
	v_or_b32_e32 v108, s89, v0
	s_cselect_b32 s63, 0, 0
	s_cselect_b32 s62, 0, s8
	s_add_i32 s4, s88, -1
	v_min_u32_e32 v2, s4, v108
	v_add_u32_e32 v2, s62, v2
	v_mov_b32_e32 v3, v1
	v_lshlrev_b64 v[2:3], 10, v[2:3]
	v_bfe_u32 v34, v107, 5, 1
	v_lshl_add_u64 v[2:3], s[16:17], 0, v[2:3]
	s_lshl_b32 s4, s52, 7
	s_mov_b32 s5, s53
	v_lshl_add_u64 v[2:3], v[2:3], 0, s[4:5]
	v_lshlrev_b32_e32 v4, 4, v34
	v_mov_b32_e32 v5, v1
	v_lshl_add_u64 v[2:3], v[2:3], 0, v[4:5]
	global_load_dwordx4 v[50:53], v[2:3], off
	global_load_dwordx4 v[54:57], v[2:3], off offset:32
	global_load_dwordx4 v[58:61], v[2:3], off offset:64
	global_load_dwordx4 v[62:65], v[2:3], off offset:96
	s_add_i32 s4, s88, 63
	s_lshr_b32 s5, s4, 6
	s_add_i32 s4, s88, 0xffffff70
	s_lshr_b32 s4, s4, 6
	v_mov_b32_e32 v2, s4
	v_ashrrev_i32_e32 v110, 6, v106
	v_sub_u32_e64 v111, s5, v2 clamp
	v_mov_b32_e32 v17, 0
	v_lshlrev_b32_e32 v94, 3, v34
	v_cmp_le_i32_e32 vcc, v110, v111
	v_mov_b64_e32 v[16:17], 0
	v_mov_b64_e32 v[14:15], 0
	v_mov_b64_e32 v[12:13], 0
	v_mov_b64_e32 v[10:11], 0
	v_mov_b64_e32 v[8:9], 0
	v_mov_b64_e32 v[6:7], 0
	v_mov_b64_e32 v[4:5], 0
	v_mov_b64_e32 v[2:3], 0
	v_mov_b64_e32 v[32:33], 0
	v_mov_b64_e32 v[30:31], 0
	v_mov_b64_e32 v[28:29], 0
	v_mov_b64_e32 v[26:27], 0
	v_mov_b64_e32 v[24:25], 0
	v_mov_b64_e32 v[22:23], 0
	v_mov_b64_e32 v[20:21], 0
	v_mov_b64_e32 v[18:19], 0
	v_mov_b32_e32 v113, 0
	s_waitcnt lgkmcnt(0)
	s_barrier
	s_and_saveexec_b64 s[64:65], vcc
	s_cbranch_execz .LBB0_2853
	s_lshr_b32 s5, s52, 2
	s_mul_i32 s8, s5, 0xa18000
	s_mul_hi_u32 s9, s5, 0xa18000
	s_add_u32 s8, s71, s8
	s_addc_u32 s9, s72, s9
	s_lshl_b32 s5, s5, 7
	s_add_u32 s66, s28, s5
	s_addc_u32 s67, s29, 0
	v_lshlrev_b32_e32 v2, 1, v94
	v_mov_b32_e32 v3, v1
	v_lshl_add_u64 v[96:97], s[66:67], 0, v[2:3]
	v_mov_b64_e32 v[2:3], s[8:9]
	v_mul_u32_u24_e32 v4, 0x28600, v0
	v_mov_b32_e32 v5, v1
	v_mov_b32_e32 v95, v1
	v_mad_u64_u32 v[2:3], s[66:67], v0, s76, v[2:3]
	v_lshl_add_u64 v[4:5], s[8:9], 0, v[4:5]
	v_lshl_add_u64 v[98:99], v[2:3], 0, v[94:95]
	v_lshl_add_u64 v[2:3], v[4:5], 0, v[94:95]
	v_lshl_add_u64 v[100:101], v[2:3], 0, s[56:57]
	v_add_u32_e32 v2, s4, v110
	v_mov_b32_e32 v113, 0
	v_lshlrev_b32_e32 v112, 2, v34
	v_lshl_add_u32 v95, v2, 6, v204
	s_mov_b64 s[66:67], 0
	v_mov_b32_e32 v2, 0
	v_mov_b32_e32 v3, v113
	v_mov_b32_e32 v4, v113
	v_mov_b32_e32 v5, v113
	v_mov_b32_e32 v6, v113
	v_mov_b32_e32 v7, v113
	v_mov_b32_e32 v8, v113
	v_mov_b32_e32 v9, v113
	v_mov_b32_e32 v10, v113
	v_mov_b32_e32 v11, v113
	v_mov_b32_e32 v12, v113
	v_mov_b32_e32 v13, v113
	v_mov_b32_e32 v14, v113
	v_mov_b32_e32 v15, v113
	v_mov_b32_e32 v16, v113
	v_mov_b32_e32 v17, v113
	v_mov_b32_e32 v18, 0
	v_mov_b32_e32 v19, v113
	v_mov_b32_e32 v20, v113
	v_mov_b32_e32 v21, v113
	v_mov_b32_e32 v22, v113
	v_mov_b32_e32 v23, v113
	v_mov_b32_e32 v24, v113
	v_mov_b32_e32 v25, v113
	v_mov_b32_e32 v26, v113
	v_mov_b32_e32 v27, v113
	v_mov_b32_e32 v28, v113
	v_mov_b32_e32 v29, v113
	v_mov_b32_e32 v30, v113
	v_mov_b32_e32 v31, v113
	v_mov_b32_e32 v32, v113
	v_mov_b32_e32 v33, v113
	s_branch .LBB0_2815

; #define LAS __attribute__((address_space(3)))
; template <int DQK, bool SWA>
; DI void attn_tail(int wv, LAS unsigned char* lds, const bf16_t* Q, int ldq, int qoff, const bf16_t* K, int ldk, int koff, const bf16_t* Vt,
;                   int base, int T, int q0, bf16_t* O, int ldo, int ooff, const float* relb, int qhead, float sink_add) {
;     constexpr int NKS = DQK / 16;
;     const int tid = tid_(wv), lane = tid & 63, w = tid >> 6, r = lane & 31, h = lane >> 5;
;     LAS float* LUT = (LAS float*)(lds + ATT_LUT); LAS float* RED = (LAS float*)(lds + ATT_RED);
;     __syncthreads();
;     if (SWA) attn_lut(LUT, tid, relb, qhead);
;     for (int e = tid; e < 64 * 33; e += 512) RED[e] = 0.f;
;     const int qpos = q0 + r; const bool qvalid = qpos < T; const size_t qrow = (size_t)base + (qvalid ? qpos : T - 1);
;     bf16x8 qf[NKS];
; #pragma unroll
;     for (int ks = 0; ks < NKS; ++ks) qf[ks] = *(const bf16x8*)(Q + qrow * ldq + qoff + 16 * ks + 8 * h);
;     f32x16 o0, o1;
; #pragma unroll
;     for (int i = 0; i < 16; ++i) { o0[i] = 0.f; o1[i] = 0.f; }
;     float lsum = 0.f;
;     const int nt = (T + 63) >> 6;
;     int lo = 0, ntl = nt;
;     if (SWA) { lo = (q0 - 128) >> 6; if (lo < 1) lo = 1; int hi = nt - 1; ntl = 1 + (hi >= lo ? hi - lo + 1 : 0); }
;     __syncthreads();
.LBB0_2862:
	s_or_b64 exec, exec, s[4:5]
	s_addk_i32 s90, 0x3800
	v_and_b32_e32 v0, 31, v88
	s_and_b64 s[4:5], s[60:61], exec
	v_or_b32_e32 v87, s89, v0
	s_cselect_b32 s5, 0, 0
	s_cselect_b32 s4, 0, s90
	s_add_i32 s8, s88, -1
	s_waitcnt vmcnt(0)
	v_min_u32_e32 v2, s8, v87
	s_mul_i32 s52, s58, 0x60
	v_add_u32_e32 v4, s4, v2
	v_mov_b64_e32 v[2:3], s[24:25]
	v_bfe_u32 v34, v88, 5, 1
	v_mad_u64_u32 v[2:3], s[8:9], v4, s82, v[2:3]
	s_lshl_b32 s52, s52, 1
	v_lshl_add_u64 v[2:3], v[2:3], 0, s[52:53]
	v_lshlrev_b32_e32 v4, 4, v34
	v_mov_b32_e32 v5, v1
	v_lshl_add_u64 v[2:3], v[2:3], 0, v[4:5]
	global_load_dwordx4 v[50:53], v[2:3], off
	global_load_dwordx4 v[54:57], v[2:3], off offset:32
	global_load_dwordx4 v[58:61], v[2:3], off offset:64
	global_load_dwordx4 v[62:65], v[2:3], off offset:96
	global_load_dwordx4 v[66:69], v[2:3], off offset:128
	global_load_dwordx4 v[70:73], v[2:3], off offset:160
	s_add_i32 s8, s88, 63
	v_ashrrev_i32_e32 v89, 6, v86
	s_lshr_b32 s59, s8, 6
	v_mov_b32_e32 v17, 0
	v_lshlrev_b32_e32 v74, 3, v34
	v_cmp_gt_i32_e32 vcc, s59, v89
	v_mov_b64_e32 v[16:17], 0
	v_mov_b64_e32 v[14:15], 0
	v_mov_b64_e32 v[12:13], 0
	v_mov_b64_e32 v[10:11], 0
	v_mov_b64_e32 v[8:9], 0
	v_mov_b64_e32 v[6:7], 0
	v_mov_b64_e32 v[4:5], 0
	v_mov_b64_e32 v[2:3], 0
	v_mov_b64_e32 v[32:33], 0
	v_mov_b64_e32 v[30:31], 0
	v_mov_b64_e32 v[28:29], 0
	v_mov_b64_e32 v[26:27], 0
	v_mov_b64_e32 v[24:25], 0
	v_mov_b64_e32 v[22:23], 0
	v_mov_b64_e32 v[20:21], 0
	v_mov_b64_e32 v[18:19], 0
	v_mov_b32_e32 v75, 0
	s_waitcnt lgkmcnt(0)
	s_barrier
	s_and_saveexec_b64 s[8:9], vcc
	s_cbranch_execz .LBB0_2866
	s_mul_i32 s60, s58, 0x50c000
	s_mov_b32 s61, s53
	s_lshl_b64 s[60:61], s[60:61], 1
	s_add_u32 s60, s41, s60
	s_addc_u32 s61, s70, s61
	s_add_u32 s62, s26, s52
	s_addc_u32 s63, s27, 0
	v_lshlrev_b32_e32 v2, 1, v74
	v_mov_b32_e32 v3, v1
	v_lshl_add_u64 v[76:77], s[62:63], 0, v[2:3]
	v_mov_b64_e32 v[2:3], s[60:61]
	v_mul_u32_u24_e32 v4, 0x28600, v0
	v_mov_b32_e32 v5, v1
	v_mov_b32_e32 v75, v1
	v_mad_u64_u32 v[2:3], s[62:63], v0, s76, v[2:3]
	v_lshl_add_u64 v[4:5], s[60:61], 0, v[4:5]
	v_lshl_add_u64 v[78:79], v[2:3], 0, v[74:75]
	v_lshl_add_u64 v[2:3], v[4:5], 0, v[74:75]
	v_mov_b32_e32 v75, 0
	v_lshlrev_b32_e32 v90, 2, v34
	v_lshl_add_u64 v[80:81], v[2:3], 0, s[56:57]
	v_lshlrev_b32_e32 v82, 6, v89
	s_mov_b64 s[60:61], 0
	v_mov_b32_e32 v2, 0
	v_mov_b32_e32 v3, v75
	v_mov_b32_e32 v4, v75
	v_mov_b32_e32 v5, v75
	v_mov_b32_e32 v6, v75
	v_mov_b32_e32 v7, v75
	v_mov_b32_e32 v8, v75
	v_mov_b32_e32 v9, v75
	v_mov_b32_e32 v10, v75
	v_mov_b32_e32 v11, v75
	v_mov_b32_e32 v12, v75
	v_mov_b32_e32 v13, v75
	v_mov_b32_e32 v14, v75
	v_mov_b32_e32 v15, v75
	v_mov_b32_e32 v16, v75
	v_mov_b32_e32 v17, v75
	v_mov_b32_e32 v18, 0
	v_mov_b32_e32 v19, v75
	v_mov_b32_e32 v20, v75
	v_mov_b32_e32 v21, v75
	v_mov_b32_e32 v22, v75
	v_mov_b32_e32 v23, v75
	v_mov_b32_e32 v24, v75
	v_mov_b32_e32 v25, v75
	v_mov_b32_e32 v26, v75
	v_mov_b32_e32 v27, v75
	v_mov_b32_e32 v28, v75
	v_mov_b32_e32 v29, v75
	v_mov_b32_e32 v30, v75
	v_mov_b32_e32 v31, v75
	v_mov_b32_e32 v32, v75
	v_mov_b32_e32 v33, v75

; template <class Epi>
; DI void gemm_phase(int wv, LAS unsigned char* lds, const Gemm g, const StaticOrder& S, const Epi& E) {
;     ...
;         const bool has_next = S.next(ui + 1, nxt);
;         const char* nA = has_next ? (const char*)g.A + (size_t)nxt.pm * tstep : cA; const char* nB = has_next ? (const char*)g.Bt + (size_t)nxt.pn * tstep : cB;
;         for (int t = 0; t < nt; t += 2) {
;             const bool last = (t == nt - 2);
;             const char* a1 = cA + (size_t)(t + 1) * kstep;
;             const char* a2 = last ? nA : cA + (size_t)(t + 2) * kstep; const char* b2 = last ? nB : cB + (size_t)(t + 2) * kstep;
;             const char* a3 = a2 + kstep; const char* b3 = b2 + kstep;
;     ...
; #pragma unroll
;         for (int a = 0; a < 2; ++a)
; #pragma unroll
;             for (int b = 0; b < 2; ++b)
; #pragma unroll
;                 for (int m = 0; m < 4; ++m)
; #pragma unroll
;                     for (int n = 0; n < 2; ++n) acc[a][b][m][n] = (f32x4){0.f, 0.f, 0.f, 0.f};
;         cur = nxt; cA = nA; cB = nB; ++ui;
.LBB0_3007:
	s_ashr_i32 s19, s18, 31
	v_cmp_lt_i64_e32 vcc, s[24:25], v[140:141]
	s_lshl_b64 s[24:25], s[18:19], 19
	s_add_u32 s24, s50, s24
	s_addc_u32 s25, s51, s25
	s_and_b64 s[26:27], vcc, exec
	s_cselect_b32 s19, s25, s31
	s_cselect_b32 s29, s24, s30
	s_ashr_i32 s17, s16, 31
	s_lshl_b64 s[26:27], s[16:17], 19
	s_add_u32 s26, s52, s26
	s_addc_u32 s27, s53, s27
	s_and_b64 s[46:47], vcc, exec
	s_cselect_b32 s17, s27, s37
	s_cselect_b32 s72, s26, s36
	s_add_u32 s73, s36, 0x100
	v_mov_b32_e32 v0, 0
	s_addc_u32 s74, s37, 0
	s_mov_b32 s75, -2
	v_mov_b64_e32 v[0:1], 0
	v_mov_b64_e32 v[2:3], 0
	v_mov_b64_e32 v[4:5], 0
	v_mov_b64_e32 v[6:7], 0
	v_mov_b64_e32 v[8:9], 0
	v_mov_b64_e32 v[10:11], 0
	v_mov_b64_e32 v[16:17], 0
	v_mov_b64_e32 v[18:19], 0
	v_mov_b64_e32 v[24:25], 0
	v_mov_b64_e32 v[26:27], 0
	v_mov_b64_e32 v[32:33], 0
	v_mov_b64_e32 v[34:35], 0
	v_mov_b64_e32 v[40:41], 0
	v_mov_b64_e32 v[42:43], 0
	v_mov_b64_e32 v[48:49], 0
	v_mov_b64_e32 v[50:51], 0
	v_mov_b64_e32 v[12:13], 0
	v_mov_b64_e32 v[14:15], 0
	v_mov_b64_e32 v[20:21], 0
	v_mov_b64_e32 v[22:23], 0
	v_mov_b64_e32 v[28:29], 0
	v_mov_b64_e32 v[30:31], 0
	v_mov_b64_e32 v[36:37], 0
	v_mov_b64_e32 v[38:39], 0
	v_mov_b64_e32 v[44:45], 0
	v_mov_b64_e32 v[46:47], 0
	v_mov_b64_e32 v[52:53], 0
	v_mov_b64_e32 v[54:55], 0
	v_mov_b64_e32 v[56:57], 0
	v_mov_b64_e32 v[58:59], 0
	v_mov_b64_e32 v[60:61], 0
	v_mov_b64_e32 v[62:63], 0
	v_mov_b64_e32 v[64:65], 0
	v_mov_b64_e32 v[66:67], 0
	v_mov_b64_e32 v[68:69], 0
	v_mov_b64_e32 v[70:71], 0
	v_mov_b64_e32 v[72:73], 0
	v_mov_b64_e32 v[74:75], 0
	v_mov_b64_e32 v[76:77], 0
	v_mov_b64_e32 v[78:79], 0
	v_mov_b64_e32 v[84:85], 0
	v_mov_b64_e32 v[86:87], 0
	v_mov_b64_e32 v[92:93], 0
	v_mov_b64_e32 v[94:95], 0
	v_mov_b64_e32 v[100:101], 0
	v_mov_b64_e32 v[102:103], 0
	v_mov_b64_e32 v[108:109], 0
	v_mov_b64_e32 v[110:111], 0
	v_mov_b64_e32 v[80:81], 0
	v_mov_b64_e32 v[82:83], 0
	v_mov_b64_e32 v[88:89], 0
	v_mov_b64_e32 v[90:91], 0
	v_mov_b64_e32 v[96:97], 0
	v_mov_b64_e32 v[98:99], 0
	v_mov_b64_e32 v[104:105], 0
	v_mov_b64_e32 v[106:107], 0
	v_mov_b64_e32 v[112:113], 0
	v_mov_b64_e32 v[114:115], 0
	v_mov_b64_e32 v[116:117], 0
	v_mov_b64_e32 v[118:119], 0
	v_mov_b64_e32 v[120:121], 0
	v_mov_b64_e32 v[122:123], 0
	v_mov_b64_e32 v[124:125], 0
	v_mov_b64_e32 v[126:127], 0

; template <class Epi>
; DI void gemm_phase(int wv, LAS unsigned char* lds, const Gemm g, const StaticOrder& S, const Epi& E) {
;     ...
;         const bool has_next = S.next(ui + 1, nxt);
;         const char* nA = has_next ? (const char*)g.A + (size_t)nxt.pm * tstep : cA; const char* nB = has_next ? (const char*)g.Bt + (size_t)nxt.pn * tstep : cB;
;         for (int t = 0; t < nt; t += 2) {
;             const bool last = (t == nt - 2);
;             const char* a1 = cA + (size_t)(t + 1) * kstep;
;             const char* a2 = last ? nA : cA + (size_t)(t + 2) * kstep; const char* b2 = last ? nB : cB + (size_t)(t + 2) * kstep;
;             const char* a3 = a2 + kstep; const char* b3 = b2 + kstep;
;             PG8_LDB(B0, 0, 0); PG8_SCHED; PG8_LDA(At, 0, 0); PG8_STAGE(PG8_SA(1, 1), a1 + hstep, voffA);
;             PG8_WAIT_L(8); PG8_BAR; PG8_WAIT_L(0); PG8_MMA(0, 0, At, B0); PG8_BAR; PG8_SCHED;
;             PG8_LDB(B1, 0, 1); PG8_STAGE(PG8_SB(0, 0), b2, voffB);
;             PG8_BAR; PG8_WAIT_L(0); PG8_MMA(0, 1, At, B1); PG8_BAR;
;             PG8_LDA(At, 0, 1); PG8_STAGE(PG8_SA(0, 0), a2, voffA);
;             PG8_BAR; PG8_WAIT_L(0); PG8_MMA(1, 0, At, B0); PG8_BAR; PG8_SCHED;
;             PG8_STAGE(PG8_SB(0, 1), b2 + hstep, voffB);
;             PG8_WAIT_V(6); PG8_BAR; PG8_MMA(1, 1, At, B1); PG8_BAR;
;             PG8_LDB(B0, 1, 0); PG8_SCHED; PG8_LDA(At, 1, 0); PG8_STAGE(PG8_SA(0, 1), a2 + hstep, voffA);
;             PG8_WAIT_L(8); PG8_BAR; PG8_WAIT_L(0); PG8_MMA(0, 0, At, B0); PG8_BAR; PG8_SCHED;
;             PG8_LDB(B1, 1, 1); PG8_STAGE(PG8_SB(1, 0), b3, voffB);
;             PG8_BAR; PG8_WAIT_L(0); PG8_MMA(0, 1, At, B1); PG8_BAR;
;             PG8_LDA(At, 1, 1); PG8_STAGE(PG8_SA(1, 0), a3, voffA);
;             PG8_BAR; PG8_WAIT_L(0); PG8_MMA(1, 0, At, B0); PG8_BAR; PG8_SCHED;
;             PG8_STAGE(PG8_SB(1, 1), b3 + hstep, voffB);
;             PG8_WAIT_V(6); PG8_BAR; PG8_MMA(1, 1, At, B1); PG8_BAR;
;         }
;         E(acc, cur, wr, wc, fr, fq);
;         if (!has_next) break;
; #pragma unroll
;         for (int a = 0; a < 2; ++a)
; #pragma unroll
;             for (int b = 0; b < 2; ++b)
; #pragma unroll
;                 for (int m = 0; m < 4; ++m)
; #pragma unroll
;                     for (int n = 0; n < 2; ++n) acc[a][b][m][n] = (f32x4){0.f, 0.f, 0.f, 0.f};
;         cur = nxt; cA = nA; cB = nB; ++ui;
.LBB0_3136:
	s_ashr_i32 s15, s14, 31
	v_cmp_lt_i64_e32 vcc, s[16:17], v[144:145]
	s_lshl_b64 s[16:17], s[14:15], 19
	s_add_u32 s16, s20, s16
	s_addc_u32 s17, s21, s17
	s_and_b64 s[18:19], vcc, exec
	s_cselect_b32 s15, s17, s27
	s_cselect_b32 s25, s16, s26
	s_ashr_i32 s13, s12, 31
	s_lshl_b64 s[18:19], s[12:13], 19
	s_add_u32 s18, s37, s18
	s_addc_u32 s19, s41, s19
	s_and_b64 s[30:31], vcc, exec
	s_cselect_b32 s13, s19, s29
	s_cselect_b32 s64, s18, s28
	s_add_u32 s26, s26, 0x40080
	s_addc_u32 s27, s27, 0
	s_add_u32 s65, s28, 0x100
	v_mov_b32_e32 v0, 0
	s_addc_u32 s66, s29, 0
	s_mov_b32 s67, -2
	v_mov_b64_e32 v[0:1], 0
	v_mov_b64_e32 v[2:3], 0
	v_mov_b64_e32 v[4:5], 0
	v_mov_b64_e32 v[6:7], 0
	v_mov_b64_e32 v[16:17], 0
	v_mov_b64_e32 v[18:19], 0
	v_mov_b64_e32 v[20:21], 0
	v_mov_b64_e32 v[22:23], 0
	v_mov_b64_e32 v[32:33], 0
	v_mov_b64_e32 v[34:35], 0
	v_mov_b64_e32 v[36:37], 0
	v_mov_b64_e32 v[38:39], 0
	v_mov_b64_e32 v[48:49], 0
	v_mov_b64_e32 v[50:51], 0
	v_mov_b64_e32 v[52:53], 0
	v_mov_b64_e32 v[54:55], 0
	v_mov_b64_e32 v[8:9], 0
	v_mov_b64_e32 v[10:11], 0
	v_mov_b64_e32 v[12:13], 0
	v_mov_b64_e32 v[14:15], 0
	v_mov_b64_e32 v[24:25], 0
	v_mov_b64_e32 v[26:27], 0
	v_mov_b64_e32 v[28:29], 0
	v_mov_b64_e32 v[30:31], 0
	v_mov_b64_e32 v[40:41], 0
	v_mov_b64_e32 v[42:43], 0
	v_mov_b64_e32 v[44:45], 0
	v_mov_b64_e32 v[46:47], 0
	v_mov_b64_e32 v[56:57], 0
	v_mov_b64_e32 v[58:59], 0
	v_mov_b64_e32 v[60:61], 0
	v_mov_b64_e32 v[62:63], 0
	v_mov_b64_e32 v[64:65], 0
	v_mov_b64_e32 v[66:67], 0
	v_mov_b64_e32 v[68:69], 0
	v_mov_b64_e32 v[70:71], 0
	v_mov_b64_e32 v[80:81], 0
	v_mov_b64_e32 v[82:83], 0
	v_mov_b64_e32 v[84:85], 0
	v_mov_b64_e32 v[86:87], 0
	v_mov_b64_e32 v[96:97], 0
	v_mov_b64_e32 v[98:99], 0
	v_mov_b64_e32 v[100:101], 0
	v_mov_b64_e32 v[102:103], 0
	v_mov_b64_e32 v[112:113], 0
	v_mov_b64_e32 v[114:115], 0
	v_mov_b64_e32 v[116:117], 0
	v_mov_b64_e32 v[118:119], 0
	v_mov_b64_e32 v[72:73], 0
	v_mov_b64_e32 v[74:75], 0
	v_mov_b64_e32 v[76:77], 0
	v_mov_b64_e32 v[78:79], 0
	v_mov_b64_e32 v[88:89], 0
	v_mov_b64_e32 v[90:91], 0
	v_mov_b64_e32 v[92:93], 0
	v_mov_b64_e32 v[94:95], 0
	v_mov_b64_e32 v[104:105], 0
	v_mov_b64_e32 v[106:107], 0
	v_mov_b64_e32 v[108:109], 0
	v_mov_b64_e32 v[110:111], 0
	v_mov_b64_e32 v[120:121], 0
	v_mov_b64_e32 v[122:123], 0
	v_mov_b64_e32 v[124:125], 0
	v_mov_b64_e32 v[126:127], 0

; template <class Epi>
; DI void gemm_phase(int wv, LAS unsigned char* lds, const Gemm g, const StaticOrder& S, const Epi& E) {
;     ...
;         const bool has_next = S.next(ui + 1, nxt);
;         const char* nA = has_next ? (const char*)g.A + (size_t)nxt.pm * tstep : cA; const char* nB = has_next ? (const char*)g.Bt + (size_t)nxt.pn * tstep : cB;
;         for (int t = 0; t < nt; t += 2) {
;             const bool last = (t == nt - 2);
;             const char* a1 = cA + (size_t)(t + 1) * kstep;
;             const char* a2 = last ? nA : cA + (size_t)(t + 2) * kstep; const char* b2 = last ? nB : cB + (size_t)(t + 2) * kstep;
;             const char* a3 = a2 + kstep; const char* b3 = b2 + kstep;
;             PG8_LDB(B0, 0, 0); PG8_SCHED; PG8_LDA(At, 0, 0); PG8_STAGE(PG8_SA(1, 1), a1 + hstep, voffA);
;             PG8_WAIT_L(8); PG8_BAR; PG8_WAIT_L(0); PG8_MMA(0, 0, At, B0); PG8_BAR; PG8_SCHED;
;             PG8_LDB(B1, 0, 1); PG8_STAGE(PG8_SB(0, 0), b2, voffB);
;             PG8_BAR; PG8_WAIT_L(0); PG8_MMA(0, 1, At, B1); PG8_BAR;
;             PG8_LDA(At, 0, 1); PG8_STAGE(PG8_SA(0, 0), a2, voffA);
;             PG8_BAR; PG8_WAIT_L(0); PG8_MMA(1, 0, At, B0); PG8_BAR; PG8_SCHED;
;             PG8_STAGE(PG8_SB(0, 1), b2 + hstep, voffB);
;             PG8_WAIT_V(6); PG8_BAR; PG8_MMA(1, 1, At, B1); PG8_BAR;
;             PG8_LDB(B0, 1, 0); PG8_SCHED; PG8_LDA(At, 1, 0); PG8_STAGE(PG8_SA(0, 1), a2 + hstep, voffA);
;             PG8_WAIT_L(8); PG8_BAR; PG8_WAIT_L(0); PG8_MMA(0, 0, At, B0); PG8_BAR; PG8_SCHED;
;             PG8_LDB(B1, 1, 1); PG8_STAGE(PG8_SB(1, 0), b3, voffB);
;             PG8_BAR; PG8_WAIT_L(0); PG8_MMA(0, 1, At, B1); PG8_BAR;
;             PG8_LDA(At, 1, 1); PG8_STAGE(PG8_SA(1, 0), a3, voffA);
;             PG8_BAR; PG8_WAIT_L(0); PG8_MMA(1, 0, At, B0); PG8_BAR; PG8_SCHED;
;             PG8_STAGE(PG8_SB(1, 1), b3 + hstep, voffB);
;             PG8_WAIT_V(6); PG8_BAR; PG8_MMA(1, 1, At, B1); PG8_BAR;
;         }
;         E(acc, cur, wr, wc, fr, fq);
;         if (!has_next) break;
; #pragma unroll
;         for (int a = 0; a < 2; ++a)
; #pragma unroll
;             for (int b = 0; b < 2; ++b)
; #pragma unroll
;                 for (int m = 0; m < 4; ++m)
; #pragma unroll
;                     for (int n = 0; n < 2; ++n) acc[a][b][m][n] = (f32x4){0.f, 0.f, 0.f, 0.f};
;         cur = nxt; cA = nA; cB = nB; ++ui;
.LBB0_3212:
	s_add_u32 s17, s20, 0x100
	v_mov_b32_e32 v0, 0
	s_addc_u32 s60, s21, 0
	s_mov_b32 s61, -2
	v_mov_b64_e32 v[0:1], 0
	v_mov_b64_e32 v[2:3], 0
	v_mov_b64_e32 v[4:5], 0
	v_mov_b64_e32 v[6:7], 0
	v_mov_b64_e32 v[8:9], 0
	v_mov_b64_e32 v[10:11], 0
	v_mov_b64_e32 v[16:17], 0
	v_mov_b64_e32 v[18:19], 0
	v_mov_b64_e32 v[24:25], 0
	v_mov_b64_e32 v[26:27], 0
	v_mov_b64_e32 v[32:33], 0
	v_mov_b64_e32 v[34:35], 0
	v_mov_b64_e32 v[40:41], 0
	v_mov_b64_e32 v[42:43], 0
	v_mov_b64_e32 v[48:49], 0
	v_mov_b64_e32 v[50:51], 0
	v_mov_b64_e32 v[12:13], 0
	v_mov_b64_e32 v[14:15], 0
	v_mov_b64_e32 v[20:21], 0
	v_mov_b64_e32 v[22:23], 0
	v_mov_b64_e32 v[28:29], 0
	v_mov_b64_e32 v[30:31], 0
	v_mov_b64_e32 v[36:37], 0
	v_mov_b64_e32 v[38:39], 0
	v_mov_b64_e32 v[44:45], 0
	v_mov_b64_e32 v[46:47], 0
	v_mov_b64_e32 v[52:53], 0
	v_mov_b64_e32 v[54:55], 0
	v_mov_b64_e32 v[56:57], 0
	v_mov_b64_e32 v[58:59], 0
	v_mov_b64_e32 v[60:61], 0
	v_mov_b64_e32 v[62:63], 0
	v_mov_b64_e32 v[64:65], 0
	v_mov_b64_e32 v[66:67], 0
	v_mov_b64_e32 v[68:69], 0
	v_mov_b64_e32 v[70:71], 0
	v_mov_b64_e32 v[72:73], 0
	v_mov_b64_e32 v[74:75], 0
	v_mov_b64_e32 v[76:77], 0
	v_mov_b64_e32 v[78:79], 0
	v_mov_b64_e32 v[84:85], 0
	v_mov_b64_e32 v[86:87], 0
	v_mov_b64_e32 v[92:93], 0
	v_mov_b64_e32 v[94:95], 0
	v_mov_b64_e32 v[100:101], 0
	v_mov_b64_e32 v[102:103], 0
	v_mov_b64_e32 v[108:109], 0
	v_mov_b64_e32 v[110:111], 0
	v_mov_b64_e32 v[80:81], 0
	v_mov_b64_e32 v[82:83], 0
	v_mov_b64_e32 v[88:89], 0
	v_mov_b64_e32 v[90:91], 0
	v_mov_b64_e32 v[96:97], 0
	v_mov_b64_e32 v[98:99], 0
	v_mov_b64_e32 v[104:105], 0
	v_mov_b64_e32 v[106:107], 0
	v_mov_b64_e32 v[112:113], 0
	v_mov_b64_e32 v[114:115], 0
	v_mov_b64_e32 v[116:117], 0
	v_mov_b64_e32 v[118:119], 0
	v_mov_b64_e32 v[120:121], 0
	v_mov_b64_e32 v[122:123], 0
	v_mov_b64_e32 v[124:125], 0
	v_mov_b64_e32 v[126:127], 0
